# W_in forget-gate tile epilogue: the 8 row groups of the 16 active lanes spread over all 64 lanes by ds_bpermute so the exact log-sigmoid code runs for 2 groups instead of 8 (was the phase's straggler)
# speedup vs baseline: 1.0151x; 1.0151x over previous
; __device__ __forceinline__ void epi_all_run(const void* Pk_, int l, int s, const f32x4 (&acc)[2][2][4][2], const pg8::Unit& u, int wr, int wc, int fr, int fq) {
;     ...
;             } else if (wc == 0 && fq == 0) {
;                 float* logf = (float*)(ws + WS_LOGF);
;                 const f32x4 fbv = *(const f32x4*)(A.fox_fb + l * 4);
; #pragma unroll
;                 for (int ai = 0; ai < 2; ++ai)
; #pragma unroll
;                     for (int m = 0; m < 4; ++m) {
;                         const int row = row0 + ai * 128 + m * 16;
;                         const f32x4 z = acc[ai][0][m][0] + fbv;
;                         f32x4 ls;
; #pragma unroll
;                         for (int j = 0; j < 4; ++j) ls[j] = fminf(z[j], 0.f) - log1pf(expf(-fabsf(z[j])));
.LBB0_72:
	s_andn2_b64 vcc, exec, s[50:51]
	s_lshl_b32 s50, s30, 8
	s_cbranch_vccnz .LBB0_80
	s_cmp_gt_i32 s30, 9
	s_mov_b64 s[46:47], -1
	s_cbranch_scc0 .LBB0_77
	s_cmp_eq_u32 s64, 0
	s_cselect_b64 vcc, -1, 0
	s_and_saveexec_b64 s[46:47], vcc
	s_cbranch_execz .LBB0_76
	v_and_b32_e32 v198, 15, v222
	v_lshlrev_b32_e32 v198, 2, v198
	v_bfe_u32 v199, v222, 4, 2
	ds_bpermute_b32 v190, v198, v94
	ds_bpermute_b32 v194, v198, v78
	ds_bpermute_b32 v191, v198, v95
	ds_bpermute_b32 v195, v198, v79
	ds_bpermute_b32 v192, v198, v96
	ds_bpermute_b32 v196, v198, v80
	ds_bpermute_b32 v193, v198, v97
	ds_bpermute_b32 v197, v198, v81
	v_cmp_eq_u32_e32 vcc, 1, v199
	s_waitcnt lgkmcnt(0)
	s_nop 0
	v_cndmask_b32_e32 v126, v126, v190, vcc
	v_cndmask_b32_e32 v110, v110, v194, vcc
	v_cndmask_b32_e32 v127, v127, v191, vcc
	v_cndmask_b32_e32 v111, v111, v195, vcc
	v_cndmask_b32_e32 v128, v128, v192, vcc
	v_cndmask_b32_e32 v112, v112, v196, vcc
	v_cndmask_b32_e32 v129, v129, v193, vcc
	v_cndmask_b32_e32 v113, v113, v197, vcc
	ds_bpermute_b32 v190, v198, v62
	ds_bpermute_b32 v194, v198, v46
	ds_bpermute_b32 v191, v198, v63
	ds_bpermute_b32 v195, v198, v47
	ds_bpermute_b32 v192, v198, v64
	ds_bpermute_b32 v196, v198, v48
	ds_bpermute_b32 v193, v198, v65
	ds_bpermute_b32 v197, v198, v49
	v_cmp_eq_u32_e32 vcc, 2, v199
	s_waitcnt lgkmcnt(0)
	s_nop 0
	v_cndmask_b32_e32 v126, v126, v190, vcc
	v_cndmask_b32_e32 v110, v110, v194, vcc
	v_cndmask_b32_e32 v127, v127, v191, vcc
	v_cndmask_b32_e32 v111, v111, v195, vcc
	v_cndmask_b32_e32 v128, v128, v192, vcc
	v_cndmask_b32_e32 v112, v112, v196, vcc
	v_cndmask_b32_e32 v129, v129, v193, vcc
	v_cndmask_b32_e32 v113, v113, v197, vcc
	ds_bpermute_b32 v190, v198, v30
	ds_bpermute_b32 v194, v198, v14
	ds_bpermute_b32 v191, v198, v31
	ds_bpermute_b32 v195, v198, v15
	ds_bpermute_b32 v192, v198, v32
	ds_bpermute_b32 v196, v198, v16
	ds_bpermute_b32 v193, v198, v33
	ds_bpermute_b32 v197, v198, v17
	v_cmp_eq_u32_e32 vcc, 3, v199
	s_waitcnt lgkmcnt(0)
	s_nop 0
	v_cndmask_b32_e32 v126, v126, v190, vcc
	v_cndmask_b32_e32 v110, v110, v194, vcc
	v_cndmask_b32_e32 v127, v127, v191, vcc
	v_cndmask_b32_e32 v111, v111, v195, vcc
	v_cndmask_b32_e32 v128, v128, v192, vcc
	v_cndmask_b32_e32 v112, v112, v196, vcc
	v_cndmask_b32_e32 v129, v129, v193, vcc
	v_cndmask_b32_e32 v113, v113, v197, vcc
	v_lshrrev_b32_e32 v190, 1, v199
	v_lshlrev_b32_e32 v190, 7, v190
	v_and_b32_e32 v191, 1, v199
	v_lshl_add_u32 v190, v191, 5, v190
	v_add_u32_e32 v184, v184, v190
	s_load_dwordx2 s[54:55], s[4:5], 0xb8
	s_add_u32 s52, s34, 0x200000
	s_addc_u32 s53, s35, 0
	s_lshl_b32 s78, s75, 2
	s_ashr_i32 s79, s78, 31
	s_lshl_b64 s[78:79], s[78:79], 2
	s_waitcnt lgkmcnt(0)
	s_add_u32 s54, s54, s78
	s_addc_u32 s55, s55, s79
	global_load_dwordx4 v[130:133], v0, s[54:55]
	s_mov_b32 s20, 0x3ecc95a3
	v_mov_b64_e32 v[134:135], s[20:21]
	s_mov_b32 s20, 0xbfb8aa3b
	s_mov_b32 s51, 0xb2a5705f
	s_mov_b32 s54, 0x42ce8ed0
	s_mov_b32 s55, 0xc2b17218
	s_mov_b32 s78, 0x3f2aaaab
	s_mov_b32 s84, 0x3f317218
	s_mov_b32 s86, 0xb102e308
	s_mov_b32 s80, 0x3e9b6dac
	s_mov_b32 s82, 0x3f2aaada
	s_mov_b32 s77, 0x7f800000
	s_mov_b32 s79, 0x33800000
	v_ashrrev_i32_e32 v185, 31, v184
	s_waitcnt vmcnt(0)
	v_add_f32_e32 v138, v126, v130
	v_add_f32_e32 v139, v127, v131
	v_mul_f32_e64 v136, |v138|, s20
	v_mul_f32_e64 v137, |v139|, s20
	v_fma_f32 v140, |v138|, s20, -v136
	v_rndne_f32_e32 v141, v136
	v_fma_f32 v142, |v139|, s20, -v137
	v_rndne_f32_e32 v143, v137
	v_fma_f32 v140, |v138|, s51, v140
	v_sub_f32_e32 v136, v136, v141
	v_fma_f32 v142, |v139|, s51, v142
	v_sub_f32_e32 v137, v137, v143
	v_add_f32_e32 v136, v136, v140
	v_cvt_i32_f32_e32 v141, v141
	v_add_f32_e32 v137, v137, v142
	v_exp_f32_e32 v140, v136
	v_cvt_i32_f32_e32 v143, v143
	v_exp_f32_e32 v142, v137
	v_cmp_ngt_f32_e64 vcc, |v138|, s54
	v_ldexp_f32 v140, v140, v141
	v_min_f32_e32 v136, 0, v138
	v_ldexp_f32 v141, v142, v143
	v_cndmask_b32_e32 v140, 0, v140, vcc
	v_cmp_ngt_f32_e64 vcc, |v139|, s54
	v_min_f32_e32 v137, 0, v139
	s_nop 0
	v_cndmask_b32_e32 v141, 0, v141, vcc
	v_cmp_nlt_f32_e64 vcc, |v138|, s55
	s_nop 1
	v_cndmask_b32_e32 v168, v221, v140, vcc
	v_cmp_nlt_f32_e64 vcc, |v139|, s55
	v_add_f32_e32 v142, 1.0, v168
	v_add_f32_e32 v144, -1.0, v142
	v_cndmask_b32_e32 v169, v221, v141, vcc
	v_add_f32_e32 v143, 1.0, v169
	v_frexp_mant_f32_e32 v147, v143
	v_cvt_f64_f32_e32 v[140:141], v143
	v_frexp_exp_i32_f64_e32 v140, v[140:141]
	v_cmp_gt_f32_e32 vcc, s78, v147
	v_frexp_mant_f32_e32 v145, v142
	v_cvt_f64_f32_e32 v[138:139], v142
	v_add_f32_e32 v146, -1.0, v143
	v_subbrev_co_u32_e32 v140, vcc, 0, v140, vcc
	v_sub_f32_e32 v148, v144, v142
	v_frexp_exp_i32_f64_e32 v138, v[138:139]
	v_sub_f32_e32 v139, v146, v143
	v_cmp_gt_f32_e32 vcc, s78, v145
	v_sub_f32_e32 v144, v168, v144
	v_sub_f32_e32 v146, v169, v146
	v_add_f32_e32 v141, 1.0, v148
	v_add_f32_e32 v139, 1.0, v139
	v_subbrev_co_u32_e32 v138, vcc, 0, v138, vcc
	v_add_f32_e32 v141, v144, v141
	v_add_f32_e32 v144, v146, v139
	v_sub_u32_e32 v145, 0, v138
	v_sub_u32_e32 v146, 0, v140
	v_cvt_f32_i32_e32 v139, v140
	v_cvt_f32_i32_e32 v138, v138
	v_ldexp_f32 v140, v142, v145
	v_ldexp_f32 v142, v141, v145
	v_ldexp_f32 v141, v143, v146
	v_ldexp_f32 v143, v144, v146
	v_pk_add_f32 v[144:145], v[140:141], 1.0 op_sel_hi:[1,0]
	v_pk_add_f32 v[146:147], v[140:141], -1.0 op_sel_hi:[1,0]
	v_pk_add_f32 v[148:149], v[144:145], -1.0 op_sel_hi:[1,0]
	v_pk_add_f32 v[150:151], v[146:147], 1.0 op_sel_hi:[1,0]
	v_pk_add_f32 v[148:149], v[140:141], v[148:149] neg_lo:[0,1] neg_hi:[0,1]
	v_pk_add_f32 v[140:141], v[140:141], v[150:151] neg_lo:[0,1] neg_hi:[0,1]
	v_pk_mul_f32 v[150:151], v[138:139], s[84:85] op_sel_hi:[1,0]
; __device__ __forceinline__ void epi_all_run(const void* Pk_, int l, int s, const f32x4 (&acc)[2][2][4][2], const pg8::Unit& u, int wr, int wc, int fr, int fq) {
;     ...
;                         const f32x4 z = acc[ai][0][m][0] + fbv;
;                         f32x4 ls;
; #pragma unroll
;                         for (int j = 0; j < 4; ++j) ls[j] = fminf(z[j], 0.f) - log1pf(expf(-fabsf(z[j])));
	v_pk_add_f32 v[148:149], v[142:143], v[148:149]
	v_pk_add_f32 v[140:141], v[142:143], v[140:141]
	v_pk_fma_f32 v[142:143], v[138:139], s[84:85], v[150:151] op_sel_hi:[1,0,1] neg_lo:[0,0,1] neg_hi:[0,0,1]
	v_pk_add_f32 v[154:155], v[144:145], v[148:149]
	v_pk_fma_f32 v[138:139], v[138:139], s[86:87], v[142:143] op_sel_hi:[1,0,1]
	v_rcp_f32_e32 v142, v154
	v_rcp_f32_e32 v143, v155
	v_pk_add_f32 v[156:157], v[146:147], v[140:141]
	v_pk_add_f32 v[144:145], v[144:145], v[154:155] neg_lo:[0,1] neg_hi:[0,1]
	v_pk_add_f32 v[146:147], v[146:147], v[156:157] neg_lo:[0,1] neg_hi:[0,1]
	v_pk_add_f32 v[144:145], v[148:149], v[144:145]
	v_pk_add_f32 v[140:141], v[140:141], v[146:147]
	v_pk_mul_f32 v[146:147], v[156:157], v[142:143]
	v_mov_b32_e32 v152, v150
	v_pk_mul_f32 v[148:149], v[154:155], v[146:147]
	v_mov_b32_e32 v160, v138
	v_pk_fma_f32 v[162:163], v[146:147], v[154:155], v[148:149] neg_lo:[0,0,1] neg_hi:[0,0,1]
	v_pk_add_f32 v[158:159], v[150:151], v[138:139]
	v_pk_fma_f32 v[162:163], v[146:147], v[144:145], v[162:163]
	v_cmp_neq_f32_e32 vcc, s77, v168
	v_pk_add_f32 v[164:165], v[148:149], v[162:163]
	s_nop 0
	v_pk_add_f32 v[166:167], v[156:157], v[164:165] neg_lo:[0,1] neg_hi:[0,1]
	v_pk_add_f32 v[148:149], v[164:165], v[148:149] neg_lo:[0,1] neg_hi:[0,1]
	v_pk_add_f32 v[156:157], v[156:157], v[166:167] neg_lo:[0,1] neg_hi:[0,1]
	v_pk_add_f32 v[148:149], v[148:149], v[162:163] neg_lo:[0,1] neg_hi:[0,1]
	v_pk_add_f32 v[156:157], v[156:157], v[164:165] neg_lo:[0,1] neg_hi:[0,1]
	s_nop 0
	v_pk_add_f32 v[140:141], v[140:141], v[156:157]
	s_nop 0
	v_pk_add_f32 v[140:141], v[148:149], v[140:141]
	s_nop 0
	v_pk_add_f32 v[148:149], v[166:167], v[140:141]
	s_nop 0
	v_pk_mul_f32 v[156:157], v[142:143], v[148:149]
	v_pk_add_f32 v[162:163], v[166:167], v[148:149] neg_lo:[0,1] neg_hi:[0,1]
	v_pk_mul_f32 v[164:165], v[154:155], v[156:157]
	v_pk_add_f32 v[140:141], v[140:141], v[162:163]
	v_pk_fma_f32 v[154:155], v[156:157], v[154:155], v[164:165] neg_lo:[0,0,1] neg_hi:[0,0,1]
	v_pk_add_f32 v[162:163], v[146:147], v[156:157]
	v_pk_fma_f32 v[144:145], v[156:157], v[144:145], v[154:155]
	v_pk_add_f32 v[146:147], v[162:163], v[146:147] neg_lo:[0,1] neg_hi:[0,1]
	v_pk_add_f32 v[154:155], v[164:165], v[144:145]
	v_pk_add_f32 v[146:147], v[156:157], v[146:147] neg_lo:[0,1] neg_hi:[0,1]
	v_pk_add_f32 v[156:157], v[154:155], v[164:165] neg_lo:[0,1] neg_hi:[0,1]
	v_pk_add_f32 v[164:165], v[148:149], v[154:155] neg_lo:[0,1] neg_hi:[0,1]
	v_pk_add_f32 v[144:145], v[156:157], v[144:145] neg_lo:[0,1] neg_hi:[0,1]
	v_pk_add_f32 v[148:149], v[148:149], v[164:165] neg_lo:[0,1] neg_hi:[0,1]
	v_mov_b32_e32 v157, v139
	v_pk_add_f32 v[148:149], v[148:149], v[154:155] neg_lo:[0,1] neg_hi:[0,1]
	v_mov_b32_e32 v154, v158
	v_pk_add_f32 v[140:141], v[140:141], v[148:149]
	v_mov_b32_e32 v155, v151
	v_pk_add_f32 v[140:141], v[144:145], v[140:141]
	s_nop 0
	v_pk_add_f32 v[140:141], v[164:165], v[140:141]
	v_mov_b32_e32 v165, v159
	v_pk_mul_f32 v[140:141], v[142:143], v[140:141]
	s_nop 0
	v_pk_add_f32 v[140:141], v[146:147], v[140:141]
	s_nop 0
	v_pk_add_f32 v[142:143], v[162:163], v[140:141]
	s_nop 0
	v_pk_add_f32 v[144:145], v[142:143], v[162:163] neg_lo:[0,1] neg_hi:[0,1]
	v_pk_mul_f32 v[148:149], v[142:143], v[142:143]
	v_pk_add_f32 v[140:141], v[140:141], v[144:145] neg_lo:[0,1] neg_hi:[0,1]
	v_pk_fma_f32 v[144:145], v[148:149], s[80:81], v[134:135] op_sel_hi:[1,0,0]
	v_ldexp_f32 v146, v142, 1
	v_ldexp_f32 v147, v143, 1
	v_pk_mul_f32 v[142:143], v[142:143], v[148:149]
	v_pk_fma_f32 v[144:145], v[148:149], v[144:145], s[82:83] op_sel_hi:[1,1,0]
	v_mov_b32_e32 v161, v147
	v_pk_mul_f32 v[142:143], v[142:143], v[144:145]
	v_ldexp_f32 v140, v140, 1
	v_pk_add_f32 v[144:145], v[146:147], v[142:143]
	v_ldexp_f32 v141, v141, 1
	v_pk_add_f32 v[146:147], v[144:145], v[146:147] neg_lo:[0,1] neg_hi:[0,1]
	v_mov_b32_e32 v153, v143
	v_pk_add_f32 v[142:143], v[142:143], v[146:147] neg_lo:[0,1] neg_hi:[0,1]
	v_pk_add_f32 v[148:149], v[152:153], v[160:161]
	v_pk_add_f32 v[146:147], v[140:141], v[142:143]
	v_mov_b32_e32 v142, v150
	v_mov_b32_e32 v140, v138
	v_pk_add_f32 v[152:153], v[142:143], v[140:141]
	v_mov_b32_e32 v140, v144
	v_mov_b32_e32 v142, v146
	v_pk_add_f32 v[140:141], v[140:141], v[142:143]
	v_pk_add_f32 v[142:143], v[144:145], v[146:147]
	v_pk_add_f32 v[140:141], v[148:149], v[140:141]
	v_mov_b32_e32 v156, v142
	v_pk_add_f32 v[148:149], v[158:159], v[142:143]
	v_pk_add_f32 v[160:161], v[154:155], v[156:157]
	v_mov_b32_e32 v162, v142
	v_mov_b32_e32 v163, v149
	v_mov_b32_e32 v164, v144
	v_pk_add_f32 v[154:155], v[160:161], v[154:155] neg_lo:[0,1] neg_hi:[0,1]
	v_pk_add_f32 v[162:163], v[162:163], v[164:165] neg_lo:[0,1] neg_hi:[0,1]
	v_pk_add_f32 v[160:161], v[158:159], v[150:151] neg_lo:[0,1] neg_hi:[0,1]
	v_pk_add_f32 v[156:157], v[156:157], v[154:155] neg_lo:[0,1] neg_hi:[0,1]
	v_mov_b32_e32 v164, v158
	v_mov_b32_e32 v165, v149
	v_mov_b32_e32 v151, v163
	v_mov_b32_e32 v155, v145
	v_pk_add_f32 v[144:145], v[142:143], v[144:145] neg_lo:[0,1] neg_hi:[0,1]
	v_pk_add_f32 v[150:151], v[164:165], v[150:151] neg_lo:[0,1] neg_hi:[0,1]
	v_pk_add_f32 v[160:161], v[138:139], v[160:161] neg_lo:[0,1] neg_hi:[0,1]
	v_pk_add_f32 v[140:141], v[140:141], v[154:155] neg_lo:[0,1] neg_hi:[0,1]
	v_pk_add_f32 v[144:145], v[146:147], v[144:145] neg_lo:[0,1] neg_hi:[0,1]
	v_mov_b32_e32 v139, v159
	v_mov_b32_e32 v147, v143
	v_pk_add_f32 v[140:141], v[152:153], v[140:141] neg_lo:[0,1] neg_hi:[0,1]
	v_pk_add_f32 v[138:139], v[138:139], v[150:151] neg_lo:[0,1] neg_hi:[0,1]
	v_pk_add_f32 v[142:143], v[146:147], v[162:163] neg_lo:[0,1] neg_hi:[0,1]
	v_pk_add_f32 v[150:151], v[156:157], v[140:141]
; __device__ __forceinline__ void epi_all_run(const void* Pk_, int l, int s, const f32x4 (&acc)[2][2][4][2], const pg8::Unit& u, int wr, int wc, int fr, int fq) {
;     ...
;                         const f32x4 z = acc[ai][0][m][0] + fbv;
;                         f32x4 ls;
; #pragma unroll
;                         for (int j = 0; j < 4; ++j) ls[j] = fminf(z[j], 0.f) - log1pf(expf(-fabsf(z[j])));
	v_pk_add_f32 v[146:147], v[142:143], v[138:139]
	v_mov_b32_e32 v143, v141
	v_pk_add_f32 v[140:141], v[160:161], v[142:143]
	v_mov_b32_e32 v139, v157
	v_pk_add_f32 v[140:141], v[140:141], v[138:139] neg_lo:[0,1] neg_hi:[0,1]
	v_mov_b32_e32 v142, v146
	v_mov_b32_e32 v143, v151
	v_pk_add_f32 v[142:143], v[142:143], v[140:141] neg_lo:[0,1] neg_hi:[0,1]
	v_pk_add_f32 v[140:141], v[144:145], v[140:141] neg_lo:[0,1] neg_hi:[0,1]
	v_pk_add_f32 v[138:139], v[138:139], v[142:143] neg_lo:[0,1] neg_hi:[0,1]
	s_nop 0
	v_pk_add_f32 v[138:139], v[140:141], v[138:139]
	v_pk_add_f32 v[140:141], v[150:151], v[146:147]
	s_nop 0
	v_pk_add_f32 v[142:143], v[148:149], v[140:141]
	s_nop 0
	v_pk_add_f32 v[144:145], v[142:143], v[148:149] neg_lo:[0,1] neg_hi:[0,1]
	s_nop 0
	v_pk_add_f32 v[140:141], v[140:141], v[144:145] neg_lo:[0,1] neg_hi:[0,1]
	v_add_f32_e32 v145, v129, v133
	v_pk_add_f32 v[138:139], v[138:139], v[140:141]
	v_add_f32_e32 v140, v128, v132
	v_mul_f32_e64 v141, |v140|, s20
	v_pk_add_f32 v[138:139], v[142:143], v[138:139]
	v_fma_f32 v142, |v140|, s20, -v141
	v_rndne_f32_e32 v143, v141
	v_fma_f32 v142, |v140|, s51, v142
	v_sub_f32_e32 v141, v141, v143
	v_add_f32_e32 v141, v141, v142
	v_cndmask_b32_e32 v138, v221, v138, vcc
	v_cmp_neq_f32_e32 vcc, s77, v169
	v_exp_f32_e32 v141, v141
	v_cvt_i32_f32_e32 v142, v143
	v_cndmask_b32_e32 v139, v221, v139, vcc
	v_cmp_lt_f32_e64 vcc, |v169|, s79
	s_nop 1
	v_cndmask_b32_e32 v139, v139, v169, vcc
	v_cmp_lt_f32_e64 vcc, |v168|, s79
	s_nop 1
	v_cndmask_b32_e32 v138, v138, v168, vcc
	v_pk_add_f32 v[138:139], v[136:137], v[138:139] neg_lo:[0,1] neg_hi:[0,1]
	v_ldexp_f32 v137, v141, v142
	v_cmp_ngt_f32_e64 vcc, |v140|, s54
	v_min_f32_e32 v136, 0, v140
	s_nop 0
	v_cndmask_b32_e32 v137, 0, v137, vcc
	v_cmp_nlt_f32_e64 vcc, |v140|, s55
	s_nop 1
	v_cndmask_b32_e32 v168, v221, v137, vcc
	v_add_f32_e32 v142, 1.0, v168
	v_add_f32_e32 v137, -1.0, v142
	v_sub_f32_e32 v140, v137, v142
	v_add_f32_e32 v140, 1.0, v140
	v_sub_f32_e32 v137, v168, v137
	v_add_f32_e32 v143, v137, v140
	v_mul_f32_e64 v137, |v145|, s20
	v_fma_f32 v140, |v145|, s20, -v137
	v_rndne_f32_e32 v141, v137
	v_fma_f32 v140, |v145|, s51, v140
	v_sub_f32_e32 v137, v137, v141
	v_add_f32_e32 v137, v137, v140
	v_exp_f32_e32 v146, v137
	v_cvt_i32_f32_e32 v147, v141
	v_cvt_f64_f32_e32 v[140:141], v142
	v_frexp_exp_i32_f64_e32 v148, v[140:141]
	v_cmp_ngt_f32_e64 vcc, |v145|, s54
	v_ldexp_f32 v140, v146, v147
	v_min_f32_e32 v137, 0, v145
	v_cndmask_b32_e32 v140, 0, v140, vcc
	v_cmp_nlt_f32_e64 vcc, |v145|, s55
	v_frexp_mant_f32_e32 v144, v142
	s_nop 0
	v_cndmask_b32_e32 v169, v221, v140, vcc
	v_add_f32_e32 v145, 1.0, v169
	v_add_f32_e32 v140, -1.0, v145
	v_sub_f32_e32 v141, v140, v145
	v_add_f32_e32 v141, 1.0, v141
	v_sub_f32_e32 v140, v169, v140
	v_add_f32_e32 v146, v140, v141
	v_frexp_mant_f32_e32 v147, v145
	v_cvt_f64_f32_e32 v[140:141], v145
	v_frexp_exp_i32_f64_e32 v140, v[140:141]
	v_cmp_gt_f32_e32 vcc, s78, v147
	s_nop 1
	v_subbrev_co_u32_e32 v160, vcc, 0, v140, vcc
	v_cmp_gt_f32_e32 vcc, s78, v144
	s_nop 1
	v_subbrev_co_u32_e32 v161, vcc, 0, v148, vcc
	v_sub_u32_e32 v141, 0, v161
	v_ldexp_f32 v140, v142, v141
	v_ldexp_f32 v142, v143, v141
	v_sub_u32_e32 v143, 0, v160
	v_ldexp_f32 v141, v145, v143
	v_pk_add_f32 v[144:145], v[140:141], 1.0 op_sel_hi:[1,0]
	v_ldexp_f32 v143, v146, v143
	v_pk_add_f32 v[146:147], v[144:145], -1.0 op_sel_hi:[1,0]
	v_pk_add_f32 v[152:153], v[140:141], -1.0 op_sel_hi:[1,0]
	v_pk_add_f32 v[146:147], v[140:141], v[146:147] neg_lo:[0,1] neg_hi:[0,1]
	v_pk_add_f32 v[154:155], v[152:153], 1.0 op_sel_hi:[1,0]
	v_pk_add_f32 v[146:147], v[142:143], v[146:147]
	v_pk_add_f32 v[140:141], v[140:141], v[154:155] neg_lo:[0,1] neg_hi:[0,1]
	v_pk_add_f32 v[148:149], v[144:145], v[146:147]
	v_pk_add_f32 v[140:141], v[142:143], v[140:141]
	v_rcp_f32_e32 v150, v148
	v_rcp_f32_e32 v151, v149
	v_pk_add_f32 v[142:143], v[152:153], v[140:141]
	v_pk_add_f32 v[144:145], v[144:145], v[148:149] neg_lo:[0,1] neg_hi:[0,1]
	v_pk_add_f32 v[152:153], v[152:153], v[142:143] neg_lo:[0,1] neg_hi:[0,1]
	v_pk_add_f32 v[144:145], v[146:147], v[144:145]
	v_pk_mul_f32 v[146:147], v[142:143], v[150:151]
	v_pk_add_f32 v[140:141], v[140:141], v[152:153]
	v_pk_mul_f32 v[152:153], v[148:149], v[146:147]
	v_cmp_neq_f32_e32 vcc, s77, v168
	v_pk_fma_f32 v[154:155], v[146:147], v[148:149], v[152:153] neg_lo:[0,0,1] neg_hi:[0,0,1]
	s_nop 0
	v_pk_fma_f32 v[154:155], v[146:147], v[144:145], v[154:155]
	s_nop 0
	v_pk_add_f32 v[156:157], v[152:153], v[154:155]
	s_nop 0
	v_pk_add_f32 v[158:159], v[142:143], v[156:157] neg_lo:[0,1] neg_hi:[0,1]
	v_pk_add_f32 v[152:153], v[156:157], v[152:153] neg_lo:[0,1] neg_hi:[0,1]
	v_pk_add_f32 v[142:143], v[142:143], v[158:159] neg_lo:[0,1] neg_hi:[0,1]
	s_nop 0
	v_pk_add_f32 v[142:143], v[142:143], v[156:157] neg_lo:[0,1] neg_hi:[0,1]
	s_nop 0
	v_pk_add_f32 v[140:141], v[140:141], v[142:143]
	v_pk_add_f32 v[142:143], v[152:153], v[154:155] neg_lo:[0,1] neg_hi:[0,1]
	s_nop 0
	v_pk_add_f32 v[140:141], v[142:143], v[140:141]
	s_nop 0
	v_pk_add_f32 v[142:143], v[158:159], v[140:141]
	s_nop 0
	v_pk_mul_f32 v[152:153], v[150:151], v[142:143]
	s_nop 0
	v_pk_mul_f32 v[154:155], v[148:149], v[152:153]
	s_nop 0
	v_pk_fma_f32 v[148:149], v[152:153], v[148:149], v[154:155] neg_lo:[0,0,1] neg_hi:[0,0,1]
	s_nop 0
	v_pk_fma_f32 v[144:145], v[152:153], v[144:145], v[148:149]
	v_pk_add_f32 v[148:149], v[158:159], v[142:143] neg_lo:[0,1] neg_hi:[0,1]
	s_nop 0
	v_pk_add_f32 v[140:141], v[140:141], v[148:149]
	v_pk_add_f32 v[148:149], v[154:155], v[144:145]
	s_nop 0
	v_pk_add_f32 v[156:157], v[142:143], v[148:149] neg_lo:[0,1] neg_hi:[0,1]
; __device__ __forceinline__ void epi_all_run(const void* Pk_, int l, int s, const f32x4 (&acc)[2][2][4][2], const pg8::Unit& u, int wr, int wc, int fr, int fq) {
;     ...
;                         const f32x4 z = acc[ai][0][m][0] + fbv;
;                         f32x4 ls;
; #pragma unroll
;                         for (int j = 0; j < 4; ++j) ls[j] = fminf(z[j], 0.f) - log1pf(expf(-fabsf(z[j])));
;                         *(f32x4*)(logf + (size_t)row * 4) = ls;
	v_pk_add_f32 v[154:155], v[148:149], v[154:155] neg_lo:[0,1] neg_hi:[0,1]
	v_pk_add_f32 v[142:143], v[142:143], v[156:157] neg_lo:[0,1] neg_hi:[0,1]
	s_nop 0
	v_pk_add_f32 v[142:143], v[142:143], v[148:149] neg_lo:[0,1] neg_hi:[0,1]
	s_nop 0
	v_pk_add_f32 v[140:141], v[140:141], v[142:143]
	v_pk_add_f32 v[142:143], v[154:155], v[144:145] neg_lo:[0,1] neg_hi:[0,1]
	s_nop 0
	v_pk_add_f32 v[140:141], v[142:143], v[140:141]
	v_pk_add_f32 v[142:143], v[146:147], v[152:153]
	v_pk_add_f32 v[140:141], v[156:157], v[140:141]
	v_pk_add_f32 v[144:145], v[142:143], v[146:147] neg_lo:[0,1] neg_hi:[0,1]
	v_pk_mul_f32 v[140:141], v[150:151], v[140:141]
	v_pk_add_f32 v[144:145], v[152:153], v[144:145] neg_lo:[0,1] neg_hi:[0,1]
	v_cvt_f32_i32_e32 v147, v160
	v_pk_add_f32 v[140:141], v[144:145], v[140:141]
	v_cvt_f32_i32_e32 v146, v161
	v_pk_add_f32 v[144:145], v[142:143], v[140:141]
	v_pk_mul_f32 v[152:153], v[146:147], s[84:85] op_sel_hi:[1,0]
	v_pk_mul_f32 v[148:149], v[144:145], v[144:145]
	v_pk_add_f32 v[142:143], v[144:145], v[142:143] neg_lo:[0,1] neg_hi:[0,1]
	v_pk_fma_f32 v[150:151], v[148:149], s[80:81], v[134:135] op_sel_hi:[1,0,0]
	v_pk_add_f32 v[140:141], v[140:141], v[142:143] neg_lo:[0,1] neg_hi:[0,1]
	v_ldexp_f32 v142, v144, 1
	v_pk_fma_f32 v[150:151], v[148:149], v[150:151], s[82:83] op_sel_hi:[1,1,0]
	v_ldexp_f32 v143, v145, 1
	v_pk_mul_f32 v[144:145], v[144:145], v[148:149]
	v_pk_fma_f32 v[154:155], v[146:147], s[84:85], v[152:153] op_sel_hi:[1,0,1] neg_lo:[0,0,1] neg_hi:[0,0,1]
	v_pk_mul_f32 v[144:145], v[144:145], v[150:151]
	v_mov_b32_e32 v157, v143
	v_pk_add_f32 v[148:149], v[142:143], v[144:145]
	v_ldexp_f32 v140, v140, 1
	v_pk_add_f32 v[142:143], v[148:149], v[142:143] neg_lo:[0,1] neg_hi:[0,1]
	v_pk_fma_f32 v[146:147], v[146:147], s[86:87], v[154:155] op_sel_hi:[1,0,1]
	v_ldexp_f32 v141, v141, 1
	v_pk_add_f32 v[142:143], v[144:145], v[142:143] neg_lo:[0,1] neg_hi:[0,1]
	v_mov_b32_e32 v150, v152
	v_mov_b32_e32 v151, v145
	v_mov_b32_e32 v156, v146
	v_pk_add_f32 v[144:145], v[140:141], v[142:143]
	v_mov_b32_e32 v142, v152
	v_mov_b32_e32 v140, v146
	v_pk_add_f32 v[150:151], v[150:151], v[156:157]
	v_pk_add_f32 v[156:157], v[142:143], v[140:141]
	v_mov_b32_e32 v140, v148
	v_mov_b32_e32 v142, v144
	v_pk_add_f32 v[154:155], v[152:153], v[146:147]
	v_pk_add_f32 v[140:141], v[140:141], v[142:143]
	v_pk_add_f32 v[142:143], v[148:149], v[144:145]
	v_mov_b32_e32 v158, v154
	v_mov_b32_e32 v159, v153
	v_mov_b32_e32 v160, v142
	v_mov_b32_e32 v161, v147
	v_pk_add_f32 v[140:141], v[150:151], v[140:141]
	v_pk_add_f32 v[150:151], v[154:155], v[142:143]
	v_pk_add_f32 v[162:163], v[158:159], v[160:161]
	v_mov_b32_e32 v164, v142
	v_mov_b32_e32 v165, v151
	v_mov_b32_e32 v166, v148
	v_mov_b32_e32 v167, v155
	v_pk_add_f32 v[158:159], v[162:163], v[158:159] neg_lo:[0,1] neg_hi:[0,1]
	v_pk_add_f32 v[164:165], v[164:165], v[166:167] neg_lo:[0,1] neg_hi:[0,1]
	v_pk_add_f32 v[162:163], v[154:155], v[152:153] neg_lo:[0,1] neg_hi:[0,1]
	v_pk_add_f32 v[160:161], v[160:161], v[158:159] neg_lo:[0,1] neg_hi:[0,1]
	v_mov_b32_e32 v166, v154
	v_mov_b32_e32 v167, v151
	v_mov_b32_e32 v153, v165
	v_mov_b32_e32 v159, v149
	v_pk_add_f32 v[148:149], v[142:143], v[148:149] neg_lo:[0,1] neg_hi:[0,1]
	v_pk_add_f32 v[152:153], v[166:167], v[152:153] neg_lo:[0,1] neg_hi:[0,1]
	v_pk_add_f32 v[162:163], v[146:147], v[162:163] neg_lo:[0,1] neg_hi:[0,1]
	v_pk_add_f32 v[140:141], v[140:141], v[158:159] neg_lo:[0,1] neg_hi:[0,1]
	v_pk_add_f32 v[148:149], v[144:145], v[148:149] neg_lo:[0,1] neg_hi:[0,1]
	v_mov_b32_e32 v147, v155
	v_mov_b32_e32 v145, v143
	v_pk_add_f32 v[140:141], v[156:157], v[140:141] neg_lo:[0,1] neg_hi:[0,1]
	v_pk_add_f32 v[146:147], v[146:147], v[152:153] neg_lo:[0,1] neg_hi:[0,1]
	v_pk_add_f32 v[142:143], v[144:145], v[164:165] neg_lo:[0,1] neg_hi:[0,1]
	v_pk_add_f32 v[152:153], v[160:161], v[140:141]
	v_pk_add_f32 v[144:145], v[142:143], v[146:147]
	v_mov_b32_e32 v143, v141
	v_pk_add_f32 v[140:141], v[162:163], v[142:143]
	v_mov_b32_e32 v147, v161
	v_pk_add_f32 v[140:141], v[140:141], v[146:147] neg_lo:[0,1] neg_hi:[0,1]
	v_mov_b32_e32 v142, v144
	v_mov_b32_e32 v143, v153
	v_pk_add_f32 v[142:143], v[142:143], v[140:141] neg_lo:[0,1] neg_hi:[0,1]
	v_pk_add_f32 v[140:141], v[148:149], v[140:141] neg_lo:[0,1] neg_hi:[0,1]
	v_pk_add_f32 v[142:143], v[146:147], v[142:143] neg_lo:[0,1] neg_hi:[0,1]
	s_nop 0
	v_pk_add_f32 v[140:141], v[140:141], v[142:143]
	v_pk_add_f32 v[142:143], v[152:153], v[144:145]
	s_nop 0
	v_pk_add_f32 v[144:145], v[150:151], v[142:143]
	s_nop 0
	v_pk_add_f32 v[146:147], v[144:145], v[150:151] neg_lo:[0,1] neg_hi:[0,1]
	s_nop 0
	v_pk_add_f32 v[142:143], v[142:143], v[146:147] neg_lo:[0,1] neg_hi:[0,1]
	s_nop 0
	v_pk_add_f32 v[140:141], v[140:141], v[142:143]
	v_add_f32_e32 v142, v110, v130
	v_pk_add_f32 v[140:141], v[144:145], v[140:141]
	v_add_f32_e32 v145, v111, v131
	v_cndmask_b32_e32 v140, v221, v140, vcc
	v_cmp_neq_f32_e32 vcc, s77, v169
	s_nop 1
	v_cndmask_b32_e32 v141, v221, v141, vcc
	v_cmp_lt_f32_e64 vcc, |v169|, s79
	s_nop 1
	v_cndmask_b32_e32 v141, v141, v169, vcc
	v_cmp_lt_f32_e64 vcc, |v168|, s79
	s_nop 1
	v_cndmask_b32_e32 v140, v140, v168, vcc
	v_pk_add_f32 v[140:141], v[136:137], v[140:141] neg_lo:[0,1] neg_hi:[0,1]
	v_mul_f32_e64 v136, |v142|, s20
	v_fma_f32 v137, |v142|, s20, -v136
	v_rndne_f32_e32 v143, v136
	v_fma_f32 v137, |v142|, s51, v137
	v_sub_f32_e32 v136, v136, v143
	v_add_f32_e32 v136, v136, v137
	v_exp_f32_e32 v144, v136
	v_cvt_i32_f32_e32 v143, v143
	v_lshl_add_u64 v[136:137], v[184:185], 4, s[52:53]
	global_store_dwordx4 v[136:137], v[138:141], off
	v_cmp_ngt_f32_e64 vcc, |v142|, s54
	s_nop 0
	v_ldexp_f32 v139, v144, v143
; __device__ __forceinline__ void epi_all_run(const void* Pk_, int l, int s, const f32x4 (&acc)[2][2][4][2], const pg8::Unit& u, int wr, int wc, int fr, int fq) {
;     ...
;                         const f32x4 z = acc[ai][0][m][0] + fbv;
;                         f32x4 ls;
; #pragma unroll
;                         for (int j = 0; j < 4; ++j) ls[j] = fminf(z[j], 0.f) - log1pf(expf(-fabsf(z[j])));
	v_cndmask_b32_e32 v139, 0, v139, vcc
	v_cmp_nlt_f32_e64 vcc, |v142|, s55
	v_min_f32_e32 v138, 0, v142
	s_nop 0
	v_cndmask_b32_e32 v168, v221, v139, vcc
	v_add_f32_e32 v142, 1.0, v168
	v_add_f32_e32 v139, -1.0, v142
	v_sub_f32_e32 v140, v139, v142
	v_add_f32_e32 v140, 1.0, v140
	v_sub_f32_e32 v139, v168, v139
	v_add_f32_e32 v143, v139, v140
	v_mul_f32_e64 v139, |v145|, s20
	v_fma_f32 v140, |v145|, s20, -v139
	v_rndne_f32_e32 v141, v139
	v_fma_f32 v140, |v145|, s51, v140
	v_sub_f32_e32 v139, v139, v141
	v_add_f32_e32 v139, v139, v140
	v_exp_f32_e32 v146, v139
	v_cvt_i32_f32_e32 v147, v141
	v_cvt_f64_f32_e32 v[140:141], v142
	v_frexp_exp_i32_f64_e32 v148, v[140:141]
	v_cmp_ngt_f32_e64 vcc, |v145|, s54
	v_ldexp_f32 v140, v146, v147
	v_min_f32_e32 v139, 0, v145
	v_cndmask_b32_e32 v140, 0, v140, vcc
	v_cmp_nlt_f32_e64 vcc, |v145|, s55
	v_frexp_mant_f32_e32 v144, v142
	s_nop 0
	v_cndmask_b32_e32 v169, v221, v140, vcc
	v_add_f32_e32 v145, 1.0, v169
	v_add_f32_e32 v140, -1.0, v145
	v_sub_f32_e32 v141, v140, v145
	v_add_f32_e32 v141, 1.0, v141
	v_sub_f32_e32 v140, v169, v140
	v_add_f32_e32 v146, v140, v141
	v_frexp_mant_f32_e32 v147, v145
	v_cvt_f64_f32_e32 v[140:141], v145
	v_frexp_exp_i32_f64_e32 v140, v[140:141]
	v_cmp_gt_f32_e32 vcc, s78, v147
	s_nop 1
	v_subbrev_co_u32_e32 v160, vcc, 0, v140, vcc
	v_cmp_gt_f32_e32 vcc, s78, v144
	s_nop 1
	v_subbrev_co_u32_e32 v161, vcc, 0, v148, vcc
	v_sub_u32_e32 v141, 0, v161
	v_ldexp_f32 v140, v142, v141
	v_ldexp_f32 v142, v143, v141
	v_sub_u32_e32 v143, 0, v160
	v_ldexp_f32 v141, v145, v143
	v_pk_add_f32 v[144:145], v[140:141], 1.0 op_sel_hi:[1,0]
	v_ldexp_f32 v143, v146, v143
	v_pk_add_f32 v[146:147], v[144:145], -1.0 op_sel_hi:[1,0]
	v_pk_add_f32 v[152:153], v[140:141], -1.0 op_sel_hi:[1,0]
	v_pk_add_f32 v[146:147], v[140:141], v[146:147] neg_lo:[0,1] neg_hi:[0,1]
	v_pk_add_f32 v[154:155], v[152:153], 1.0 op_sel_hi:[1,0]
	v_pk_add_f32 v[146:147], v[142:143], v[146:147]
	v_pk_add_f32 v[140:141], v[140:141], v[154:155] neg_lo:[0,1] neg_hi:[0,1]
	v_pk_add_f32 v[148:149], v[144:145], v[146:147]
	v_pk_add_f32 v[140:141], v[142:143], v[140:141]
	v_rcp_f32_e32 v150, v148
	v_rcp_f32_e32 v151, v149
	v_pk_add_f32 v[142:143], v[152:153], v[140:141]
	v_pk_add_f32 v[144:145], v[144:145], v[148:149] neg_lo:[0,1] neg_hi:[0,1]
	v_pk_add_f32 v[152:153], v[152:153], v[142:143] neg_lo:[0,1] neg_hi:[0,1]
	v_pk_add_f32 v[144:145], v[146:147], v[144:145]
	v_pk_mul_f32 v[146:147], v[142:143], v[150:151]
	v_pk_add_f32 v[140:141], v[140:141], v[152:153]
	v_pk_mul_f32 v[152:153], v[148:149], v[146:147]
	v_cmp_neq_f32_e32 vcc, s77, v168
	v_pk_fma_f32 v[154:155], v[146:147], v[148:149], v[152:153] neg_lo:[0,0,1] neg_hi:[0,0,1]
	s_nop 0
	v_pk_fma_f32 v[154:155], v[146:147], v[144:145], v[154:155]
	s_nop 0
	v_pk_add_f32 v[156:157], v[152:153], v[154:155]
	s_nop 0
	v_pk_add_f32 v[158:159], v[142:143], v[156:157] neg_lo:[0,1] neg_hi:[0,1]
	v_pk_add_f32 v[152:153], v[156:157], v[152:153] neg_lo:[0,1] neg_hi:[0,1]
	v_pk_add_f32 v[142:143], v[142:143], v[158:159] neg_lo:[0,1] neg_hi:[0,1]
	s_nop 0
	v_pk_add_f32 v[142:143], v[142:143], v[156:157] neg_lo:[0,1] neg_hi:[0,1]
	s_nop 0
	v_pk_add_f32 v[140:141], v[140:141], v[142:143]
	v_pk_add_f32 v[142:143], v[152:153], v[154:155] neg_lo:[0,1] neg_hi:[0,1]
	s_nop 0
	v_pk_add_f32 v[140:141], v[142:143], v[140:141]
	s_nop 0
	v_pk_add_f32 v[142:143], v[158:159], v[140:141]
	s_nop 0
	v_pk_mul_f32 v[152:153], v[150:151], v[142:143]
	s_nop 0
	v_pk_mul_f32 v[154:155], v[148:149], v[152:153]
	s_nop 0
	v_pk_fma_f32 v[148:149], v[152:153], v[148:149], v[154:155] neg_lo:[0,0,1] neg_hi:[0,0,1]
	s_nop 0
	v_pk_fma_f32 v[144:145], v[152:153], v[144:145], v[148:149]
	v_pk_add_f32 v[148:149], v[158:159], v[142:143] neg_lo:[0,1] neg_hi:[0,1]
	s_nop 0
	v_pk_add_f32 v[140:141], v[140:141], v[148:149]
	v_pk_add_f32 v[148:149], v[154:155], v[144:145]
	s_nop 0
	v_pk_add_f32 v[156:157], v[142:143], v[148:149] neg_lo:[0,1] neg_hi:[0,1]
	v_pk_add_f32 v[154:155], v[148:149], v[154:155] neg_lo:[0,1] neg_hi:[0,1]
	v_pk_add_f32 v[142:143], v[142:143], v[156:157] neg_lo:[0,1] neg_hi:[0,1]
	s_nop 0
	v_pk_add_f32 v[142:143], v[142:143], v[148:149] neg_lo:[0,1] neg_hi:[0,1]
	s_nop 0
	v_pk_add_f32 v[140:141], v[140:141], v[142:143]
	v_pk_add_f32 v[142:143], v[154:155], v[144:145] neg_lo:[0,1] neg_hi:[0,1]
	s_nop 0
	v_pk_add_f32 v[140:141], v[142:143], v[140:141]
	v_pk_add_f32 v[142:143], v[146:147], v[152:153]
	v_pk_add_f32 v[140:141], v[156:157], v[140:141]
	v_pk_add_f32 v[144:145], v[142:143], v[146:147] neg_lo:[0,1] neg_hi:[0,1]
	v_pk_mul_f32 v[140:141], v[150:151], v[140:141]
	v_pk_add_f32 v[144:145], v[152:153], v[144:145] neg_lo:[0,1] neg_hi:[0,1]
	v_cvt_f32_i32_e32 v147, v160
	v_pk_add_f32 v[140:141], v[144:145], v[140:141]
	v_cvt_f32_i32_e32 v146, v161
	v_pk_add_f32 v[144:145], v[142:143], v[140:141]
	v_pk_mul_f32 v[152:153], v[146:147], s[84:85] op_sel_hi:[1,0]
	v_pk_mul_f32 v[148:149], v[144:145], v[144:145]
	v_pk_add_f32 v[142:143], v[144:145], v[142:143] neg_lo:[0,1] neg_hi:[0,1]
	v_pk_fma_f32 v[150:151], v[148:149], s[80:81], v[134:135] op_sel_hi:[1,0,0]
	v_pk_add_f32 v[140:141], v[140:141], v[142:143] neg_lo:[0,1] neg_hi:[0,1]
	v_ldexp_f32 v142, v144, 1
	v_pk_fma_f32 v[150:151], v[148:149], v[150:151], s[82:83] op_sel_hi:[1,1,0]
	v_ldexp_f32 v143, v145, 1
	v_pk_mul_f32 v[144:145], v[144:145], v[148:149]
	v_pk_fma_f32 v[154:155], v[146:147], s[84:85], v[152:153] op_sel_hi:[1,0,1] neg_lo:[0,0,1] neg_hi:[0,0,1]
	v_pk_mul_f32 v[144:145], v[144:145], v[150:151]
	v_mov_b32_e32 v157, v143
	v_pk_add_f32 v[148:149], v[142:143], v[144:145]
	v_ldexp_f32 v140, v140, 1
	v_pk_add_f32 v[142:143], v[148:149], v[142:143] neg_lo:[0,1] neg_hi:[0,1]
; __device__ __forceinline__ void epi_all_run(const void* Pk_, int l, int s, const f32x4 (&acc)[2][2][4][2], const pg8::Unit& u, int wr, int wc, int fr, int fq) {
;     ...
;                         const f32x4 z = acc[ai][0][m][0] + fbv;
;                         f32x4 ls;
; #pragma unroll
;                         for (int j = 0; j < 4; ++j) ls[j] = fminf(z[j], 0.f) - log1pf(expf(-fabsf(z[j])));
	v_pk_fma_f32 v[146:147], v[146:147], s[86:87], v[154:155] op_sel_hi:[1,0,1]
	v_ldexp_f32 v141, v141, 1
	v_pk_add_f32 v[142:143], v[144:145], v[142:143] neg_lo:[0,1] neg_hi:[0,1]
	v_mov_b32_e32 v150, v152
	v_mov_b32_e32 v151, v145
	v_mov_b32_e32 v156, v146
	v_pk_add_f32 v[144:145], v[140:141], v[142:143]
	v_mov_b32_e32 v142, v152
	v_mov_b32_e32 v140, v146
	v_pk_add_f32 v[150:151], v[150:151], v[156:157]
	v_pk_add_f32 v[156:157], v[142:143], v[140:141]
	v_mov_b32_e32 v140, v148
	v_mov_b32_e32 v142, v144
	v_pk_add_f32 v[154:155], v[152:153], v[146:147]
	v_pk_add_f32 v[140:141], v[140:141], v[142:143]
	v_pk_add_f32 v[142:143], v[148:149], v[144:145]
	v_mov_b32_e32 v158, v154
	v_mov_b32_e32 v159, v153
	v_mov_b32_e32 v160, v142
	v_mov_b32_e32 v161, v147
	v_pk_add_f32 v[140:141], v[150:151], v[140:141]
	v_pk_add_f32 v[150:151], v[154:155], v[142:143]
	v_pk_add_f32 v[162:163], v[158:159], v[160:161]
	v_mov_b32_e32 v164, v142
	v_mov_b32_e32 v165, v151
	v_mov_b32_e32 v166, v148
	v_mov_b32_e32 v167, v155
	v_pk_add_f32 v[158:159], v[162:163], v[158:159] neg_lo:[0,1] neg_hi:[0,1]
	v_pk_add_f32 v[164:165], v[164:165], v[166:167] neg_lo:[0,1] neg_hi:[0,1]
	v_pk_add_f32 v[162:163], v[154:155], v[152:153] neg_lo:[0,1] neg_hi:[0,1]
	v_pk_add_f32 v[160:161], v[160:161], v[158:159] neg_lo:[0,1] neg_hi:[0,1]
	v_mov_b32_e32 v166, v154
	v_mov_b32_e32 v167, v151
	v_mov_b32_e32 v153, v165
	v_mov_b32_e32 v159, v149
	v_pk_add_f32 v[148:149], v[142:143], v[148:149] neg_lo:[0,1] neg_hi:[0,1]
	v_pk_add_f32 v[152:153], v[166:167], v[152:153] neg_lo:[0,1] neg_hi:[0,1]
	v_pk_add_f32 v[162:163], v[146:147], v[162:163] neg_lo:[0,1] neg_hi:[0,1]
	v_pk_add_f32 v[140:141], v[140:141], v[158:159] neg_lo:[0,1] neg_hi:[0,1]
	v_pk_add_f32 v[148:149], v[144:145], v[148:149] neg_lo:[0,1] neg_hi:[0,1]
	v_mov_b32_e32 v147, v155
	v_mov_b32_e32 v145, v143
	v_pk_add_f32 v[140:141], v[156:157], v[140:141] neg_lo:[0,1] neg_hi:[0,1]
	v_pk_add_f32 v[146:147], v[146:147], v[152:153] neg_lo:[0,1] neg_hi:[0,1]
	v_pk_add_f32 v[142:143], v[144:145], v[164:165] neg_lo:[0,1] neg_hi:[0,1]
	v_pk_add_f32 v[152:153], v[160:161], v[140:141]
	v_pk_add_f32 v[144:145], v[142:143], v[146:147]
	v_mov_b32_e32 v143, v141
	v_pk_add_f32 v[140:141], v[162:163], v[142:143]
	v_mov_b32_e32 v147, v161
	v_pk_add_f32 v[140:141], v[140:141], v[146:147] neg_lo:[0,1] neg_hi:[0,1]
	v_mov_b32_e32 v142, v144
	v_mov_b32_e32 v143, v153
	v_pk_add_f32 v[142:143], v[142:143], v[140:141] neg_lo:[0,1] neg_hi:[0,1]
	v_pk_add_f32 v[140:141], v[148:149], v[140:141] neg_lo:[0,1] neg_hi:[0,1]
	v_pk_add_f32 v[142:143], v[146:147], v[142:143] neg_lo:[0,1] neg_hi:[0,1]
	s_nop 0
	v_pk_add_f32 v[140:141], v[140:141], v[142:143]
	v_pk_add_f32 v[142:143], v[152:153], v[144:145]
	s_nop 0
	v_pk_add_f32 v[144:145], v[150:151], v[142:143]
	s_nop 0
	v_pk_add_f32 v[146:147], v[144:145], v[150:151] neg_lo:[0,1] neg_hi:[0,1]
	s_nop 0
	v_pk_add_f32 v[142:143], v[142:143], v[146:147] neg_lo:[0,1] neg_hi:[0,1]
	v_add_f32_e32 v147, v113, v133
	v_pk_add_f32 v[140:141], v[140:141], v[142:143]
	v_add_f32_e32 v142, v112, v132
	v_mul_f32_e64 v143, |v142|, s20
	v_pk_add_f32 v[140:141], v[144:145], v[140:141]
	v_fma_f32 v144, |v142|, s20, -v143
	v_rndne_f32_e32 v145, v143
	v_fma_f32 v144, |v142|, s51, v144
	v_sub_f32_e32 v143, v143, v145
	v_add_f32_e32 v143, v143, v144
	v_cndmask_b32_e32 v140, v221, v140, vcc
	v_cmp_neq_f32_e32 vcc, s77, v169
	v_exp_f32_e32 v143, v143
	v_cvt_i32_f32_e32 v144, v145
	v_cndmask_b32_e32 v141, v221, v141, vcc
	v_cmp_lt_f32_e64 vcc, |v169|, s79
	s_nop 1
	v_cndmask_b32_e32 v141, v141, v169, vcc
	v_cmp_lt_f32_e64 vcc, |v168|, s79
	s_nop 1
	v_cndmask_b32_e32 v140, v140, v168, vcc
	v_pk_add_f32 v[138:139], v[138:139], v[140:141] neg_lo:[0,1] neg_hi:[0,1]
	v_ldexp_f32 v141, v143, v144
	v_cmp_ngt_f32_e64 vcc, |v142|, s54
	v_min_f32_e32 v140, 0, v142
	s_nop 0
	v_cndmask_b32_e32 v141, 0, v141, vcc
	v_cmp_nlt_f32_e64 vcc, |v142|, s55
	s_nop 1
	v_cndmask_b32_e32 v185, v221, v141, vcc
	v_add_f32_e32 v144, 1.0, v185
	v_add_f32_e32 v141, -1.0, v144
	v_sub_f32_e32 v142, v141, v144
	v_add_f32_e32 v142, 1.0, v142
	v_sub_f32_e32 v141, v185, v141
	v_add_f32_e32 v145, v141, v142
	v_mul_f32_e64 v141, |v147|, s20
	v_fma_f32 v142, |v147|, s20, -v141
	v_rndne_f32_e32 v143, v141
	v_fma_f32 v142, |v147|, s51, v142
	v_sub_f32_e32 v141, v141, v143
	v_add_f32_e32 v141, v141, v142
	v_exp_f32_e32 v148, v141
	v_cvt_i32_f32_e32 v149, v143
	v_cvt_f64_f32_e32 v[142:143], v144
	v_frexp_exp_i32_f64_e32 v150, v[142:143]
	v_cmp_ngt_f32_e64 vcc, |v147|, s54
	v_ldexp_f32 v142, v148, v149
	v_min_f32_e32 v141, 0, v147
	v_cndmask_b32_e32 v142, 0, v142, vcc
	v_cmp_nlt_f32_e64 vcc, |v147|, s55
	v_frexp_mant_f32_e32 v146, v144
	s_nop 0
	v_cndmask_b32_e32 v186, v221, v142, vcc
	v_add_f32_e32 v147, 1.0, v186
	v_add_f32_e32 v142, -1.0, v147
	v_sub_f32_e32 v143, v142, v147
	v_add_f32_e32 v143, 1.0, v143
	v_sub_f32_e32 v142, v186, v142
	v_add_f32_e32 v148, v142, v143
	v_frexp_mant_f32_e32 v149, v147
	v_cvt_f64_f32_e32 v[142:143], v147
	v_frexp_exp_i32_f64_e32 v142, v[142:143]
	v_cmp_gt_f32_e32 vcc, s78, v149
	s_nop 1
	v_subbrev_co_u32_e32 v162, vcc, 0, v142, vcc
	v_cmp_gt_f32_e32 vcc, s78, v146
	s_nop 1
	v_subbrev_co_u32_e32 v163, vcc, 0, v150, vcc
	v_sub_u32_e32 v143, 0, v163
	v_ldexp_f32 v142, v144, v143
	v_ldexp_f32 v144, v145, v143
	v_sub_u32_e32 v145, 0, v162
	v_ldexp_f32 v143, v147, v145
	v_pk_add_f32 v[146:147], v[142:143], 1.0 op_sel_hi:[1,0]
	v_ldexp_f32 v145, v148, v145
	v_pk_add_f32 v[148:149], v[146:147], -1.0 op_sel_hi:[1,0]
	v_pk_add_f32 v[154:155], v[142:143], -1.0 op_sel_hi:[1,0]
	v_pk_add_f32 v[148:149], v[142:143], v[148:149] neg_lo:[0,1] neg_hi:[0,1]
; __device__ __forceinline__ void epi_all_run(const void* Pk_, int l, int s, const f32x4 (&acc)[2][2][4][2], const pg8::Unit& u, int wr, int wc, int fr, int fq) {
;     ...
;                         const f32x4 z = acc[ai][0][m][0] + fbv;
;                         f32x4 ls;
; #pragma unroll
;                         for (int j = 0; j < 4; ++j) ls[j] = fminf(z[j], 0.f) - log1pf(expf(-fabsf(z[j])));
	v_pk_add_f32 v[156:157], v[154:155], 1.0 op_sel_hi:[1,0]
	v_pk_add_f32 v[148:149], v[144:145], v[148:149]
	v_pk_add_f32 v[142:143], v[142:143], v[156:157] neg_lo:[0,1] neg_hi:[0,1]
	v_pk_add_f32 v[150:151], v[146:147], v[148:149]
	v_pk_add_f32 v[142:143], v[144:145], v[142:143]
	v_rcp_f32_e32 v152, v150
	v_rcp_f32_e32 v153, v151
	v_pk_add_f32 v[144:145], v[154:155], v[142:143]
	v_pk_add_f32 v[146:147], v[146:147], v[150:151] neg_lo:[0,1] neg_hi:[0,1]
	v_pk_add_f32 v[154:155], v[154:155], v[144:145] neg_lo:[0,1] neg_hi:[0,1]
	v_pk_add_f32 v[146:147], v[148:149], v[146:147]
	v_pk_mul_f32 v[148:149], v[144:145], v[152:153]
	v_pk_add_f32 v[142:143], v[142:143], v[154:155]
	v_pk_mul_f32 v[154:155], v[150:151], v[148:149]
	v_cmp_neq_f32_e32 vcc, s77, v185
	v_pk_fma_f32 v[156:157], v[148:149], v[150:151], v[154:155] neg_lo:[0,0,1] neg_hi:[0,0,1]
	s_nop 0
	v_pk_fma_f32 v[156:157], v[148:149], v[146:147], v[156:157]
	s_nop 0
	v_pk_add_f32 v[158:159], v[154:155], v[156:157]
	s_nop 0
	v_pk_add_f32 v[160:161], v[144:145], v[158:159] neg_lo:[0,1] neg_hi:[0,1]
	v_pk_add_f32 v[154:155], v[158:159], v[154:155] neg_lo:[0,1] neg_hi:[0,1]
	v_pk_add_f32 v[144:145], v[144:145], v[160:161] neg_lo:[0,1] neg_hi:[0,1]
	s_nop 0
	v_pk_add_f32 v[144:145], v[144:145], v[158:159] neg_lo:[0,1] neg_hi:[0,1]
	s_nop 0
	v_pk_add_f32 v[142:143], v[142:143], v[144:145]
	v_pk_add_f32 v[144:145], v[154:155], v[156:157] neg_lo:[0,1] neg_hi:[0,1]
	s_nop 0
	v_pk_add_f32 v[142:143], v[144:145], v[142:143]
	s_nop 0
	v_pk_add_f32 v[144:145], v[160:161], v[142:143]
	s_nop 0
	v_pk_mul_f32 v[154:155], v[152:153], v[144:145]
	s_nop 0
	v_pk_mul_f32 v[156:157], v[150:151], v[154:155]
	s_nop 0
	v_pk_fma_f32 v[150:151], v[154:155], v[150:151], v[156:157] neg_lo:[0,0,1] neg_hi:[0,0,1]
	s_nop 0
	v_pk_fma_f32 v[146:147], v[154:155], v[146:147], v[150:151]
	v_pk_add_f32 v[150:151], v[160:161], v[144:145] neg_lo:[0,1] neg_hi:[0,1]
	s_nop 0
	v_pk_add_f32 v[142:143], v[142:143], v[150:151]
	v_pk_add_f32 v[150:151], v[156:157], v[146:147]
	s_nop 0
	v_pk_add_f32 v[158:159], v[144:145], v[150:151] neg_lo:[0,1] neg_hi:[0,1]
	v_pk_add_f32 v[156:157], v[150:151], v[156:157] neg_lo:[0,1] neg_hi:[0,1]
	v_pk_add_f32 v[144:145], v[144:145], v[158:159] neg_lo:[0,1] neg_hi:[0,1]
	s_nop 0
	v_pk_add_f32 v[144:145], v[144:145], v[150:151] neg_lo:[0,1] neg_hi:[0,1]
	s_nop 0
	v_pk_add_f32 v[142:143], v[142:143], v[144:145]
	v_pk_add_f32 v[144:145], v[156:157], v[146:147] neg_lo:[0,1] neg_hi:[0,1]
	s_nop 0
	v_pk_add_f32 v[142:143], v[144:145], v[142:143]
	v_pk_add_f32 v[144:145], v[148:149], v[154:155]
	v_pk_add_f32 v[142:143], v[158:159], v[142:143]
	v_pk_add_f32 v[146:147], v[144:145], v[148:149] neg_lo:[0,1] neg_hi:[0,1]
	v_pk_mul_f32 v[142:143], v[152:153], v[142:143]
	v_pk_add_f32 v[146:147], v[154:155], v[146:147] neg_lo:[0,1] neg_hi:[0,1]
	v_cvt_f32_i32_e32 v149, v162
	v_pk_add_f32 v[142:143], v[146:147], v[142:143]
	v_cvt_f32_i32_e32 v148, v163
	v_pk_add_f32 v[146:147], v[144:145], v[142:143]
	v_pk_mul_f32 v[154:155], v[148:149], s[84:85] op_sel_hi:[1,0]
	v_pk_mul_f32 v[150:151], v[146:147], v[146:147]
	v_pk_add_f32 v[144:145], v[146:147], v[144:145] neg_lo:[0,1] neg_hi:[0,1]
	v_pk_fma_f32 v[152:153], v[150:151], s[80:81], v[134:135] op_sel_hi:[1,0,0]
	v_pk_add_f32 v[142:143], v[142:143], v[144:145] neg_lo:[0,1] neg_hi:[0,1]
	v_ldexp_f32 v144, v146, 1
	v_pk_fma_f32 v[152:153], v[150:151], v[152:153], s[82:83] op_sel_hi:[1,1,0]
	v_ldexp_f32 v145, v147, 1
	v_pk_mul_f32 v[146:147], v[146:147], v[150:151]
	v_pk_fma_f32 v[156:157], v[148:149], s[84:85], v[154:155] op_sel_hi:[1,0,1] neg_lo:[0,0,1] neg_hi:[0,0,1]
	v_pk_mul_f32 v[146:147], v[146:147], v[152:153]
	v_mov_b32_e32 v159, v145
	v_pk_add_f32 v[150:151], v[144:145], v[146:147]
	v_ldexp_f32 v142, v142, 1
	v_pk_add_f32 v[144:145], v[150:151], v[144:145] neg_lo:[0,1] neg_hi:[0,1]
	v_pk_fma_f32 v[148:149], v[148:149], s[86:87], v[156:157] op_sel_hi:[1,0,1]
	v_ldexp_f32 v143, v143, 1
	v_pk_add_f32 v[144:145], v[146:147], v[144:145] neg_lo:[0,1] neg_hi:[0,1]
	v_mov_b32_e32 v152, v154
	v_mov_b32_e32 v153, v147
	v_mov_b32_e32 v158, v148
	v_pk_add_f32 v[146:147], v[142:143], v[144:145]
	v_mov_b32_e32 v144, v154
	v_mov_b32_e32 v142, v148
	v_pk_add_f32 v[152:153], v[152:153], v[158:159]
	v_pk_add_f32 v[158:159], v[144:145], v[142:143]
	v_mov_b32_e32 v142, v150
	v_mov_b32_e32 v144, v146
	v_pk_add_f32 v[156:157], v[154:155], v[148:149]
	v_pk_add_f32 v[142:143], v[142:143], v[144:145]
	v_pk_add_f32 v[144:145], v[150:151], v[146:147]
	v_mov_b32_e32 v160, v156
	v_mov_b32_e32 v161, v155
	v_mov_b32_e32 v162, v144
	v_mov_b32_e32 v163, v149
	v_pk_add_f32 v[142:143], v[152:153], v[142:143]
	v_pk_add_f32 v[152:153], v[156:157], v[144:145]
	v_pk_add_f32 v[164:165], v[160:161], v[162:163]
	v_mov_b32_e32 v166, v144
	v_mov_b32_e32 v167, v153
	v_mov_b32_e32 v168, v150
	v_mov_b32_e32 v169, v157
	v_pk_add_f32 v[160:161], v[164:165], v[160:161] neg_lo:[0,1] neg_hi:[0,1]
	v_pk_add_f32 v[166:167], v[166:167], v[168:169] neg_lo:[0,1] neg_hi:[0,1]
	v_pk_add_f32 v[164:165], v[156:157], v[154:155] neg_lo:[0,1] neg_hi:[0,1]
	v_pk_add_f32 v[162:163], v[162:163], v[160:161] neg_lo:[0,1] neg_hi:[0,1]
	v_mov_b32_e32 v168, v156
	v_mov_b32_e32 v169, v153
	v_mov_b32_e32 v155, v167
	v_mov_b32_e32 v161, v151
	v_pk_add_f32 v[150:151], v[144:145], v[150:151] neg_lo:[0,1] neg_hi:[0,1]
	v_pk_add_f32 v[154:155], v[168:169], v[154:155] neg_lo:[0,1] neg_hi:[0,1]
	v_pk_add_f32 v[164:165], v[148:149], v[164:165] neg_lo:[0,1] neg_hi:[0,1]
	v_pk_add_f32 v[142:143], v[142:143], v[160:161] neg_lo:[0,1] neg_hi:[0,1]
	v_pk_add_f32 v[150:151], v[146:147], v[150:151] neg_lo:[0,1] neg_hi:[0,1]
	v_mov_b32_e32 v149, v157
; __device__ __forceinline__ void epi_all_run(const void* Pk_, int l, int s, const f32x4 (&acc)[2][2][4][2], const pg8::Unit& u, int wr, int wc, int fr, int fq) {
;     ...
;                     for (int m = 0; m < 4; ++m) {
;                         const int row = row0 + ai * 128 + m * 16;
;                         const f32x4 z = acc[ai][0][m][0] + fbv;
;                         f32x4 ls;
; #pragma unroll
;                         for (int j = 0; j < 4; ++j) ls[j] = fminf(z[j], 0.f) - log1pf(expf(-fabsf(z[j])));
;                         *(f32x4*)(logf + (size_t)row * 4) = ls;
	v_mov_b32_e32 v147, v145
	v_pk_add_f32 v[142:143], v[158:159], v[142:143] neg_lo:[0,1] neg_hi:[0,1]
	v_pk_add_f32 v[148:149], v[148:149], v[154:155] neg_lo:[0,1] neg_hi:[0,1]
	v_pk_add_f32 v[144:145], v[146:147], v[166:167] neg_lo:[0,1] neg_hi:[0,1]
	v_pk_add_f32 v[154:155], v[162:163], v[142:143]
	v_pk_add_f32 v[146:147], v[144:145], v[148:149]
	v_mov_b32_e32 v145, v143
	v_pk_add_f32 v[142:143], v[164:165], v[144:145]
	v_mov_b32_e32 v149, v163
	v_pk_add_f32 v[142:143], v[142:143], v[148:149] neg_lo:[0,1] neg_hi:[0,1]
	v_mov_b32_e32 v144, v146
	v_mov_b32_e32 v145, v155
	v_pk_add_f32 v[144:145], v[144:145], v[142:143] neg_lo:[0,1] neg_hi:[0,1]
	v_pk_add_f32 v[142:143], v[150:151], v[142:143] neg_lo:[0,1] neg_hi:[0,1]
	v_pk_add_f32 v[144:145], v[148:149], v[144:145] neg_lo:[0,1] neg_hi:[0,1]
	s_nop 0
	v_pk_add_f32 v[142:143], v[142:143], v[144:145]
	v_pk_add_f32 v[144:145], v[154:155], v[146:147]
	s_nop 0
	v_pk_add_f32 v[146:147], v[152:153], v[144:145]
	s_nop 0
	v_pk_add_f32 v[148:149], v[146:147], v[152:153] neg_lo:[0,1] neg_hi:[0,1]
	s_nop 0
	v_pk_add_f32 v[144:145], v[144:145], v[148:149] neg_lo:[0,1] neg_hi:[0,1]
	s_nop 0
	v_pk_add_f32 v[142:143], v[142:143], v[144:145]
	v_add_f32_e32 v144, v94, v130
	v_pk_add_f32 v[142:143], v[146:147], v[142:143]
	v_mul_f32_e64 v145, |v144|, s20
	v_cndmask_b32_e32 v142, v221, v142, vcc
	v_cmp_neq_f32_e32 vcc, s77, v186
	v_fma_f32 v146, |v144|, s20, -v145
	v_rndne_f32_e32 v147, v145
	v_cndmask_b32_e32 v143, v221, v143, vcc
	v_cmp_lt_f32_e64 vcc, |v186|, s79
	v_fma_f32 v146, |v144|, s51, v146
	v_sub_f32_e32 v145, v145, v147
	v_cndmask_b32_e32 v143, v143, v186, vcc
	v_cmp_lt_f32_e64 vcc, |v185|, s79
	v_add_f32_e32 v145, v145, v146
	v_exp_f32_e32 v145, v145
	v_cndmask_b32_e32 v142, v142, v185, vcc
	v_cvt_i32_f32_e32 v146, v147
	v_pk_add_f32 v[140:141], v[140:141], v[142:143] neg_lo:[0,1] neg_hi:[0,1]
	v_or_b32_e32 v142, 16, v184
	v_ashrrev_i32_e32 v143, 31, v142
	v_lshl_add_u64 v[142:143], v[142:143], 4, s[52:53]
	global_store_dwordx4 v[142:143], v[138:141], off
	s_branch .LBB0_76
	v_cmp_ngt_f32_e64 vcc, |v144|, s54
	s_nop 0
	v_ldexp_f32 v139, v145, v146
	v_cndmask_b32_e32 v139, 0, v139, vcc
	v_cmp_nlt_f32_e64 vcc, |v144|, s55
	v_add_f32_e32 v145, v95, v131
	v_min_f32_e32 v138, 0, v144
	v_cndmask_b32_e32 v168, v221, v139, vcc
	v_add_f32_e32 v142, 1.0, v168
	v_add_f32_e32 v139, -1.0, v142
	v_sub_f32_e32 v140, v139, v142
	v_add_f32_e32 v140, 1.0, v140
	v_sub_f32_e32 v139, v168, v139
	v_add_f32_e32 v143, v139, v140
	v_mul_f32_e64 v139, |v145|, s20
	v_fma_f32 v140, |v145|, s20, -v139
	v_rndne_f32_e32 v141, v139
	v_fma_f32 v140, |v145|, s51, v140
	v_sub_f32_e32 v139, v139, v141
	v_add_f32_e32 v139, v139, v140
	v_exp_f32_e32 v146, v139
	v_cvt_i32_f32_e32 v147, v141
	v_cvt_f64_f32_e32 v[140:141], v142
	v_frexp_exp_i32_f64_e32 v148, v[140:141]
	v_cmp_ngt_f32_e64 vcc, |v145|, s54
	v_ldexp_f32 v140, v146, v147
	v_min_f32_e32 v139, 0, v145
	v_cndmask_b32_e32 v140, 0, v140, vcc
	v_cmp_nlt_f32_e64 vcc, |v145|, s55
	v_frexp_mant_f32_e32 v144, v142
	s_nop 0
	v_cndmask_b32_e32 v169, v221, v140, vcc
	v_add_f32_e32 v145, 1.0, v169
	v_add_f32_e32 v140, -1.0, v145
	v_sub_f32_e32 v141, v140, v145
	v_add_f32_e32 v141, 1.0, v141
	v_sub_f32_e32 v140, v169, v140
	v_add_f32_e32 v146, v140, v141
	v_frexp_mant_f32_e32 v147, v145
	v_cvt_f64_f32_e32 v[140:141], v145
	v_frexp_exp_i32_f64_e32 v140, v[140:141]
	v_cmp_gt_f32_e32 vcc, s78, v147
	s_nop 1
	v_subbrev_co_u32_e32 v160, vcc, 0, v140, vcc
	v_cmp_gt_f32_e32 vcc, s78, v144
	s_nop 1
	v_subbrev_co_u32_e32 v161, vcc, 0, v148, vcc
	v_sub_u32_e32 v141, 0, v161
	v_ldexp_f32 v140, v142, v141
	v_ldexp_f32 v142, v143, v141
	v_sub_u32_e32 v143, 0, v160
	v_ldexp_f32 v141, v145, v143
	v_pk_add_f32 v[144:145], v[140:141], 1.0 op_sel_hi:[1,0]
	v_ldexp_f32 v143, v146, v143
	v_pk_add_f32 v[146:147], v[144:145], -1.0 op_sel_hi:[1,0]
	v_pk_add_f32 v[152:153], v[140:141], -1.0 op_sel_hi:[1,0]
	v_pk_add_f32 v[146:147], v[140:141], v[146:147] neg_lo:[0,1] neg_hi:[0,1]
	v_pk_add_f32 v[154:155], v[152:153], 1.0 op_sel_hi:[1,0]
	v_pk_add_f32 v[146:147], v[142:143], v[146:147]
	v_pk_add_f32 v[140:141], v[140:141], v[154:155] neg_lo:[0,1] neg_hi:[0,1]
	v_pk_add_f32 v[148:149], v[144:145], v[146:147]
	v_pk_add_f32 v[140:141], v[142:143], v[140:141]
	v_rcp_f32_e32 v150, v148
	v_rcp_f32_e32 v151, v149
	v_pk_add_f32 v[142:143], v[152:153], v[140:141]
	v_pk_add_f32 v[144:145], v[144:145], v[148:149] neg_lo:[0,1] neg_hi:[0,1]
	v_pk_add_f32 v[152:153], v[152:153], v[142:143] neg_lo:[0,1] neg_hi:[0,1]
	v_pk_add_f32 v[144:145], v[146:147], v[144:145]
	v_pk_mul_f32 v[146:147], v[142:143], v[150:151]
	v_pk_add_f32 v[140:141], v[140:141], v[152:153]
	v_pk_mul_f32 v[152:153], v[148:149], v[146:147]
	v_cmp_neq_f32_e32 vcc, s77, v168
	v_pk_fma_f32 v[154:155], v[146:147], v[148:149], v[152:153] neg_lo:[0,0,1] neg_hi:[0,0,1]
	s_nop 0
	v_pk_fma_f32 v[154:155], v[146:147], v[144:145], v[154:155]
	s_nop 0
	v_pk_add_f32 v[156:157], v[152:153], v[154:155]
	s_nop 0
	v_pk_add_f32 v[158:159], v[142:143], v[156:157] neg_lo:[0,1] neg_hi:[0,1]
	v_pk_add_f32 v[152:153], v[156:157], v[152:153] neg_lo:[0,1] neg_hi:[0,1]
	v_pk_add_f32 v[142:143], v[142:143], v[158:159] neg_lo:[0,1] neg_hi:[0,1]
	s_nop 0
	v_pk_add_f32 v[142:143], v[142:143], v[156:157] neg_lo:[0,1] neg_hi:[0,1]
	s_nop 0
	v_pk_add_f32 v[140:141], v[140:141], v[142:143]
	v_pk_add_f32 v[142:143], v[152:153], v[154:155] neg_lo:[0,1] neg_hi:[0,1]
	s_nop 0
	v_pk_add_f32 v[140:141], v[142:143], v[140:141]
	s_nop 0
	v_pk_add_f32 v[142:143], v[158:159], v[140:141]
	s_nop 0
	v_pk_mul_f32 v[152:153], v[150:151], v[142:143]
	s_nop 0
	v_pk_mul_f32 v[154:155], v[148:149], v[152:153]
; __device__ __forceinline__ void epi_all_run(const void* Pk_, int l, int s, const f32x4 (&acc)[2][2][4][2], const pg8::Unit& u, int wr, int wc, int fr, int fq) {
;     ...
;                 for (int ai = 0; ai < 2; ++ai)
; #pragma unroll
;                     for (int m = 0; m < 4; ++m) {
;                         const int row = row0 + ai * 128 + m * 16;
;                         const f32x4 z = acc[ai][0][m][0] + fbv;
;                         f32x4 ls;
; #pragma unroll
;                         for (int j = 0; j < 4; ++j) ls[j] = fminf(z[j], 0.f) - log1pf(expf(-fabsf(z[j])));
	s_nop 0
	v_pk_fma_f32 v[148:149], v[152:153], v[148:149], v[154:155] neg_lo:[0,0,1] neg_hi:[0,0,1]
	s_nop 0
	v_pk_fma_f32 v[144:145], v[152:153], v[144:145], v[148:149]
	v_pk_add_f32 v[148:149], v[158:159], v[142:143] neg_lo:[0,1] neg_hi:[0,1]
	s_nop 0
	v_pk_add_f32 v[140:141], v[140:141], v[148:149]
	v_pk_add_f32 v[148:149], v[154:155], v[144:145]
	s_nop 0
	v_pk_add_f32 v[156:157], v[142:143], v[148:149] neg_lo:[0,1] neg_hi:[0,1]
	v_pk_add_f32 v[154:155], v[148:149], v[154:155] neg_lo:[0,1] neg_hi:[0,1]
	v_pk_add_f32 v[142:143], v[142:143], v[156:157] neg_lo:[0,1] neg_hi:[0,1]
	s_nop 0
	v_pk_add_f32 v[142:143], v[142:143], v[148:149] neg_lo:[0,1] neg_hi:[0,1]
	s_nop 0
	v_pk_add_f32 v[140:141], v[140:141], v[142:143]
	v_pk_add_f32 v[142:143], v[154:155], v[144:145] neg_lo:[0,1] neg_hi:[0,1]
	s_nop 0
	v_pk_add_f32 v[140:141], v[142:143], v[140:141]
	v_pk_add_f32 v[142:143], v[146:147], v[152:153]
	v_pk_add_f32 v[140:141], v[156:157], v[140:141]
	v_pk_add_f32 v[144:145], v[142:143], v[146:147] neg_lo:[0,1] neg_hi:[0,1]
	v_pk_mul_f32 v[140:141], v[150:151], v[140:141]
	v_pk_add_f32 v[144:145], v[152:153], v[144:145] neg_lo:[0,1] neg_hi:[0,1]
	v_cvt_f32_i32_e32 v147, v160
	v_pk_add_f32 v[140:141], v[144:145], v[140:141]
	v_cvt_f32_i32_e32 v146, v161
	v_pk_add_f32 v[144:145], v[142:143], v[140:141]
	v_pk_mul_f32 v[152:153], v[146:147], s[84:85] op_sel_hi:[1,0]
	v_pk_mul_f32 v[148:149], v[144:145], v[144:145]
	v_pk_add_f32 v[142:143], v[144:145], v[142:143] neg_lo:[0,1] neg_hi:[0,1]
	v_pk_fma_f32 v[150:151], v[148:149], s[80:81], v[134:135] op_sel_hi:[1,0,0]
	v_pk_add_f32 v[140:141], v[140:141], v[142:143] neg_lo:[0,1] neg_hi:[0,1]
	v_ldexp_f32 v142, v144, 1
	v_pk_fma_f32 v[150:151], v[148:149], v[150:151], s[82:83] op_sel_hi:[1,1,0]
	v_ldexp_f32 v143, v145, 1
	v_pk_mul_f32 v[144:145], v[144:145], v[148:149]
	v_pk_fma_f32 v[154:155], v[146:147], s[84:85], v[152:153] op_sel_hi:[1,0,1] neg_lo:[0,0,1] neg_hi:[0,0,1]
	v_pk_mul_f32 v[144:145], v[144:145], v[150:151]
	v_mov_b32_e32 v157, v143
	v_pk_add_f32 v[148:149], v[142:143], v[144:145]
	v_ldexp_f32 v140, v140, 1
	v_pk_add_f32 v[142:143], v[148:149], v[142:143] neg_lo:[0,1] neg_hi:[0,1]
	v_pk_fma_f32 v[146:147], v[146:147], s[86:87], v[154:155] op_sel_hi:[1,0,1]
	v_ldexp_f32 v141, v141, 1
	v_pk_add_f32 v[142:143], v[144:145], v[142:143] neg_lo:[0,1] neg_hi:[0,1]
	v_mov_b32_e32 v150, v152
	v_mov_b32_e32 v151, v145
	v_mov_b32_e32 v156, v146
	v_pk_add_f32 v[144:145], v[140:141], v[142:143]
	v_mov_b32_e32 v142, v152
	v_mov_b32_e32 v140, v146
	v_pk_add_f32 v[150:151], v[150:151], v[156:157]
	v_pk_add_f32 v[156:157], v[142:143], v[140:141]
	v_mov_b32_e32 v140, v148
	v_mov_b32_e32 v142, v144
	v_pk_add_f32 v[154:155], v[152:153], v[146:147]
	v_pk_add_f32 v[140:141], v[140:141], v[142:143]
	v_pk_add_f32 v[142:143], v[148:149], v[144:145]
	v_mov_b32_e32 v158, v154
	v_mov_b32_e32 v159, v153
	v_mov_b32_e32 v160, v142
	v_mov_b32_e32 v161, v147
	v_pk_add_f32 v[140:141], v[150:151], v[140:141]
	v_pk_add_f32 v[150:151], v[154:155], v[142:143]
	v_pk_add_f32 v[162:163], v[158:159], v[160:161]
	v_mov_b32_e32 v164, v142
	v_mov_b32_e32 v165, v151
	v_mov_b32_e32 v166, v148
	v_mov_b32_e32 v167, v155
	v_pk_add_f32 v[158:159], v[162:163], v[158:159] neg_lo:[0,1] neg_hi:[0,1]
	v_pk_add_f32 v[164:165], v[164:165], v[166:167] neg_lo:[0,1] neg_hi:[0,1]
	v_pk_add_f32 v[162:163], v[154:155], v[152:153] neg_lo:[0,1] neg_hi:[0,1]
	v_pk_add_f32 v[160:161], v[160:161], v[158:159] neg_lo:[0,1] neg_hi:[0,1]
	v_mov_b32_e32 v166, v154
	v_mov_b32_e32 v167, v151
	v_mov_b32_e32 v153, v165
	v_mov_b32_e32 v159, v149
	v_pk_add_f32 v[148:149], v[142:143], v[148:149] neg_lo:[0,1] neg_hi:[0,1]
	v_pk_add_f32 v[152:153], v[166:167], v[152:153] neg_lo:[0,1] neg_hi:[0,1]
	v_pk_add_f32 v[162:163], v[146:147], v[162:163] neg_lo:[0,1] neg_hi:[0,1]
	v_pk_add_f32 v[140:141], v[140:141], v[158:159] neg_lo:[0,1] neg_hi:[0,1]
	v_pk_add_f32 v[148:149], v[144:145], v[148:149] neg_lo:[0,1] neg_hi:[0,1]
	v_mov_b32_e32 v147, v155
	v_mov_b32_e32 v145, v143
	v_pk_add_f32 v[140:141], v[156:157], v[140:141] neg_lo:[0,1] neg_hi:[0,1]
	v_pk_add_f32 v[146:147], v[146:147], v[152:153] neg_lo:[0,1] neg_hi:[0,1]
	v_pk_add_f32 v[142:143], v[144:145], v[164:165] neg_lo:[0,1] neg_hi:[0,1]
	v_pk_add_f32 v[152:153], v[160:161], v[140:141]
	v_pk_add_f32 v[144:145], v[142:143], v[146:147]
	v_mov_b32_e32 v143, v141
	v_pk_add_f32 v[140:141], v[162:163], v[142:143]
	v_mov_b32_e32 v147, v161
	v_pk_add_f32 v[140:141], v[140:141], v[146:147] neg_lo:[0,1] neg_hi:[0,1]
	v_mov_b32_e32 v142, v144
	v_mov_b32_e32 v143, v153
	v_pk_add_f32 v[142:143], v[142:143], v[140:141] neg_lo:[0,1] neg_hi:[0,1]
	v_pk_add_f32 v[140:141], v[148:149], v[140:141] neg_lo:[0,1] neg_hi:[0,1]
	v_pk_add_f32 v[142:143], v[146:147], v[142:143] neg_lo:[0,1] neg_hi:[0,1]
	s_nop 0
	v_pk_add_f32 v[140:141], v[140:141], v[142:143]
	v_pk_add_f32 v[142:143], v[152:153], v[144:145]
	s_nop 0
	v_pk_add_f32 v[144:145], v[150:151], v[142:143]
	s_nop 0
	v_pk_add_f32 v[146:147], v[144:145], v[150:151] neg_lo:[0,1] neg_hi:[0,1]
	s_nop 0
	v_pk_add_f32 v[142:143], v[142:143], v[146:147] neg_lo:[0,1] neg_hi:[0,1]
	v_add_f32_e32 v147, v97, v133
	v_pk_add_f32 v[140:141], v[140:141], v[142:143]
	v_add_f32_e32 v142, v96, v132
	v_mul_f32_e64 v143, |v142|, s20
	v_pk_add_f32 v[140:141], v[144:145], v[140:141]
	v_fma_f32 v144, |v142|, s20, -v143
	v_rndne_f32_e32 v145, v143
	v_fma_f32 v144, |v142|, s51, v144
	v_sub_f32_e32 v143, v143, v145
	v_add_f32_e32 v143, v143, v144
	v_cndmask_b32_e32 v140, v221, v140, vcc
	v_cmp_neq_f32_e32 vcc, s77, v169
	v_exp_f32_e32 v143, v143
	v_cvt_i32_f32_e32 v144, v145
	v_cndmask_b32_e32 v141, v221, v141, vcc
; __device__ __forceinline__ void epi_all_run(const void* Pk_, int l, int s, const f32x4 (&acc)[2][2][4][2], const pg8::Unit& u, int wr, int wc, int fr, int fq) {
;     ...
;                 for (int ai = 0; ai < 2; ++ai)
; #pragma unroll
;                     for (int m = 0; m < 4; ++m) {
;                         const int row = row0 + ai * 128 + m * 16;
;                         const f32x4 z = acc[ai][0][m][0] + fbv;
;                         f32x4 ls;
; #pragma unroll
;                         for (int j = 0; j < 4; ++j) ls[j] = fminf(z[j], 0.f) - log1pf(expf(-fabsf(z[j])));
	v_cmp_lt_f32_e64 vcc, |v169|, s79
	s_nop 1
	v_cndmask_b32_e32 v141, v141, v169, vcc
	v_cmp_lt_f32_e64 vcc, |v168|, s79
	s_nop 1
	v_cndmask_b32_e32 v140, v140, v168, vcc
	v_pk_add_f32 v[138:139], v[138:139], v[140:141] neg_lo:[0,1] neg_hi:[0,1]
	v_ldexp_f32 v141, v143, v144
	v_cmp_ngt_f32_e64 vcc, |v142|, s54
	v_min_f32_e32 v140, 0, v142
	s_nop 0
	v_cndmask_b32_e32 v141, 0, v141, vcc
	v_cmp_nlt_f32_e64 vcc, |v142|, s55
	s_nop 1
	v_cndmask_b32_e32 v185, v221, v141, vcc
	v_add_f32_e32 v144, 1.0, v185
	v_add_f32_e32 v141, -1.0, v144
	v_sub_f32_e32 v142, v141, v144
	v_add_f32_e32 v142, 1.0, v142
	v_sub_f32_e32 v141, v185, v141
	v_add_f32_e32 v145, v141, v142
	v_mul_f32_e64 v141, |v147|, s20
	v_fma_f32 v142, |v147|, s20, -v141
	v_rndne_f32_e32 v143, v141
	v_fma_f32 v142, |v147|, s51, v142
	v_sub_f32_e32 v141, v141, v143
	v_add_f32_e32 v141, v141, v142
	v_exp_f32_e32 v148, v141
	v_cvt_i32_f32_e32 v149, v143
	v_cvt_f64_f32_e32 v[142:143], v144
	v_frexp_exp_i32_f64_e32 v150, v[142:143]
	v_cmp_ngt_f32_e64 vcc, |v147|, s54
	v_ldexp_f32 v142, v148, v149
	v_min_f32_e32 v141, 0, v147
	v_cndmask_b32_e32 v142, 0, v142, vcc
	v_cmp_nlt_f32_e64 vcc, |v147|, s55
	v_frexp_mant_f32_e32 v146, v144
	s_nop 0
	v_cndmask_b32_e32 v186, v221, v142, vcc
	v_add_f32_e32 v147, 1.0, v186
	v_add_f32_e32 v142, -1.0, v147
	v_sub_f32_e32 v143, v142, v147
	v_add_f32_e32 v143, 1.0, v143
	v_sub_f32_e32 v142, v186, v142
	v_add_f32_e32 v148, v142, v143
	v_frexp_mant_f32_e32 v149, v147
	v_cvt_f64_f32_e32 v[142:143], v147
	v_frexp_exp_i32_f64_e32 v142, v[142:143]
	v_cmp_gt_f32_e32 vcc, s78, v149
	s_nop 1
	v_subbrev_co_u32_e32 v162, vcc, 0, v142, vcc
	v_cmp_gt_f32_e32 vcc, s78, v146
	s_nop 1
	v_subbrev_co_u32_e32 v163, vcc, 0, v150, vcc
	v_sub_u32_e32 v143, 0, v163
	v_ldexp_f32 v142, v144, v143
	v_ldexp_f32 v144, v145, v143
	v_sub_u32_e32 v145, 0, v162
	v_ldexp_f32 v143, v147, v145
	v_pk_add_f32 v[146:147], v[142:143], 1.0 op_sel_hi:[1,0]
	v_ldexp_f32 v145, v148, v145
	v_pk_add_f32 v[148:149], v[146:147], -1.0 op_sel_hi:[1,0]
	v_pk_add_f32 v[154:155], v[142:143], -1.0 op_sel_hi:[1,0]
	v_pk_add_f32 v[148:149], v[142:143], v[148:149] neg_lo:[0,1] neg_hi:[0,1]
	v_pk_add_f32 v[156:157], v[154:155], 1.0 op_sel_hi:[1,0]
	v_pk_add_f32 v[148:149], v[144:145], v[148:149]
	v_pk_add_f32 v[142:143], v[142:143], v[156:157] neg_lo:[0,1] neg_hi:[0,1]
	v_pk_add_f32 v[150:151], v[146:147], v[148:149]
	v_pk_add_f32 v[142:143], v[144:145], v[142:143]
	v_rcp_f32_e32 v152, v150
	v_rcp_f32_e32 v153, v151
	v_pk_add_f32 v[144:145], v[154:155], v[142:143]
	v_pk_add_f32 v[146:147], v[146:147], v[150:151] neg_lo:[0,1] neg_hi:[0,1]
	v_pk_add_f32 v[154:155], v[154:155], v[144:145] neg_lo:[0,1] neg_hi:[0,1]
	v_pk_add_f32 v[146:147], v[148:149], v[146:147]
	v_pk_mul_f32 v[148:149], v[144:145], v[152:153]
	v_pk_add_f32 v[142:143], v[142:143], v[154:155]
	v_pk_mul_f32 v[154:155], v[150:151], v[148:149]
	v_cmp_neq_f32_e32 vcc, s77, v185
	v_pk_fma_f32 v[156:157], v[148:149], v[150:151], v[154:155] neg_lo:[0,0,1] neg_hi:[0,0,1]
	s_nop 0
	v_pk_fma_f32 v[156:157], v[148:149], v[146:147], v[156:157]
	s_nop 0
	v_pk_add_f32 v[158:159], v[154:155], v[156:157]
	s_nop 0
	v_pk_add_f32 v[160:161], v[144:145], v[158:159] neg_lo:[0,1] neg_hi:[0,1]
	v_pk_add_f32 v[154:155], v[158:159], v[154:155] neg_lo:[0,1] neg_hi:[0,1]
	v_pk_add_f32 v[144:145], v[144:145], v[160:161] neg_lo:[0,1] neg_hi:[0,1]
	s_nop 0
	v_pk_add_f32 v[144:145], v[144:145], v[158:159] neg_lo:[0,1] neg_hi:[0,1]
	s_nop 0
	v_pk_add_f32 v[142:143], v[142:143], v[144:145]
	v_pk_add_f32 v[144:145], v[154:155], v[156:157] neg_lo:[0,1] neg_hi:[0,1]
	s_nop 0
	v_pk_add_f32 v[142:143], v[144:145], v[142:143]
	s_nop 0
	v_pk_add_f32 v[144:145], v[160:161], v[142:143]
	s_nop 0
	v_pk_mul_f32 v[154:155], v[152:153], v[144:145]
	s_nop 0
	v_pk_mul_f32 v[156:157], v[150:151], v[154:155]
	s_nop 0
	v_pk_fma_f32 v[150:151], v[154:155], v[150:151], v[156:157] neg_lo:[0,0,1] neg_hi:[0,0,1]
	s_nop 0
	v_pk_fma_f32 v[146:147], v[154:155], v[146:147], v[150:151]
	v_pk_add_f32 v[150:151], v[160:161], v[144:145] neg_lo:[0,1] neg_hi:[0,1]
	s_nop 0
	v_pk_add_f32 v[142:143], v[142:143], v[150:151]
	v_pk_add_f32 v[150:151], v[156:157], v[146:147]
	s_nop 0
	v_pk_add_f32 v[158:159], v[144:145], v[150:151] neg_lo:[0,1] neg_hi:[0,1]
	v_pk_add_f32 v[156:157], v[150:151], v[156:157] neg_lo:[0,1] neg_hi:[0,1]
	v_pk_add_f32 v[144:145], v[144:145], v[158:159] neg_lo:[0,1] neg_hi:[0,1]
	s_nop 0
	v_pk_add_f32 v[144:145], v[144:145], v[150:151] neg_lo:[0,1] neg_hi:[0,1]
	s_nop 0
	v_pk_add_f32 v[142:143], v[142:143], v[144:145]
	v_pk_add_f32 v[144:145], v[156:157], v[146:147] neg_lo:[0,1] neg_hi:[0,1]
	s_nop 0
	v_pk_add_f32 v[142:143], v[144:145], v[142:143]
	v_pk_add_f32 v[144:145], v[148:149], v[154:155]
	v_pk_add_f32 v[142:143], v[158:159], v[142:143]
	v_pk_add_f32 v[146:147], v[144:145], v[148:149] neg_lo:[0,1] neg_hi:[0,1]
	v_pk_mul_f32 v[142:143], v[152:153], v[142:143]
	v_pk_add_f32 v[146:147], v[154:155], v[146:147] neg_lo:[0,1] neg_hi:[0,1]
	v_cvt_f32_i32_e32 v149, v162
	v_pk_add_f32 v[142:143], v[146:147], v[142:143]
	v_cvt_f32_i32_e32 v148, v163
	v_pk_add_f32 v[146:147], v[144:145], v[142:143]
	v_pk_mul_f32 v[154:155], v[148:149], s[84:85] op_sel_hi:[1,0]
	v_pk_mul_f32 v[150:151], v[146:147], v[146:147]
	v_pk_add_f32 v[144:145], v[146:147], v[144:145] neg_lo:[0,1] neg_hi:[0,1]
	v_pk_fma_f32 v[152:153], v[150:151], s[80:81], v[134:135] op_sel_hi:[1,0,0]
	v_pk_add_f32 v[142:143], v[142:143], v[144:145] neg_lo:[0,1] neg_hi:[0,1]
	v_ldexp_f32 v144, v146, 1
	v_pk_fma_f32 v[152:153], v[150:151], v[152:153], s[82:83] op_sel_hi:[1,1,0]
	v_ldexp_f32 v145, v147, 1
	v_pk_mul_f32 v[146:147], v[146:147], v[150:151]
; __device__ __forceinline__ void epi_all_run(const void* Pk_, int l, int s, const f32x4 (&acc)[2][2][4][2], const pg8::Unit& u, int wr, int wc, int fr, int fq) {
;     ...
;                 for (int ai = 0; ai < 2; ++ai)
; #pragma unroll
;                     for (int m = 0; m < 4; ++m) {
;                         const int row = row0 + ai * 128 + m * 16;
;                         const f32x4 z = acc[ai][0][m][0] + fbv;
;                         f32x4 ls;
; #pragma unroll
;                         for (int j = 0; j < 4; ++j) ls[j] = fminf(z[j], 0.f) - log1pf(expf(-fabsf(z[j])));
	v_pk_fma_f32 v[156:157], v[148:149], s[84:85], v[154:155] op_sel_hi:[1,0,1] neg_lo:[0,0,1] neg_hi:[0,0,1]
	v_pk_mul_f32 v[146:147], v[146:147], v[152:153]
	v_mov_b32_e32 v159, v145
	v_pk_add_f32 v[150:151], v[144:145], v[146:147]
	v_ldexp_f32 v142, v142, 1
	v_pk_add_f32 v[144:145], v[150:151], v[144:145] neg_lo:[0,1] neg_hi:[0,1]
	v_pk_fma_f32 v[148:149], v[148:149], s[86:87], v[156:157] op_sel_hi:[1,0,1]
	v_ldexp_f32 v143, v143, 1
	v_pk_add_f32 v[144:145], v[146:147], v[144:145] neg_lo:[0,1] neg_hi:[0,1]
	v_mov_b32_e32 v152, v154
	v_mov_b32_e32 v153, v147
	v_mov_b32_e32 v158, v148
	v_pk_add_f32 v[146:147], v[142:143], v[144:145]
	v_mov_b32_e32 v144, v154
	v_mov_b32_e32 v142, v148
	v_pk_add_f32 v[152:153], v[152:153], v[158:159]
	v_pk_add_f32 v[158:159], v[144:145], v[142:143]
	v_mov_b32_e32 v142, v150
	v_mov_b32_e32 v144, v146
	v_pk_add_f32 v[156:157], v[154:155], v[148:149]
	v_pk_add_f32 v[142:143], v[142:143], v[144:145]
	v_pk_add_f32 v[144:145], v[150:151], v[146:147]
	v_mov_b32_e32 v160, v156
	v_mov_b32_e32 v161, v155
	v_mov_b32_e32 v162, v144
	v_mov_b32_e32 v163, v149
	v_pk_add_f32 v[142:143], v[152:153], v[142:143]
	v_pk_add_f32 v[152:153], v[156:157], v[144:145]
	v_pk_add_f32 v[164:165], v[160:161], v[162:163]
	v_mov_b32_e32 v166, v144
	v_mov_b32_e32 v167, v153
	v_mov_b32_e32 v168, v150
	v_mov_b32_e32 v169, v157
	v_pk_add_f32 v[160:161], v[164:165], v[160:161] neg_lo:[0,1] neg_hi:[0,1]
	v_pk_add_f32 v[166:167], v[166:167], v[168:169] neg_lo:[0,1] neg_hi:[0,1]
	v_pk_add_f32 v[164:165], v[156:157], v[154:155] neg_lo:[0,1] neg_hi:[0,1]
	v_pk_add_f32 v[162:163], v[162:163], v[160:161] neg_lo:[0,1] neg_hi:[0,1]
	v_mov_b32_e32 v168, v156
	v_mov_b32_e32 v169, v153
	v_mov_b32_e32 v155, v167
	v_mov_b32_e32 v161, v151
	v_pk_add_f32 v[150:151], v[144:145], v[150:151] neg_lo:[0,1] neg_hi:[0,1]
	v_pk_add_f32 v[154:155], v[168:169], v[154:155] neg_lo:[0,1] neg_hi:[0,1]
	v_pk_add_f32 v[164:165], v[148:149], v[164:165] neg_lo:[0,1] neg_hi:[0,1]
	v_pk_add_f32 v[142:143], v[142:143], v[160:161] neg_lo:[0,1] neg_hi:[0,1]
	v_pk_add_f32 v[150:151], v[146:147], v[150:151] neg_lo:[0,1] neg_hi:[0,1]
	v_mov_b32_e32 v149, v157
	v_mov_b32_e32 v147, v145
	v_pk_add_f32 v[142:143], v[158:159], v[142:143] neg_lo:[0,1] neg_hi:[0,1]
	v_pk_add_f32 v[148:149], v[148:149], v[154:155] neg_lo:[0,1] neg_hi:[0,1]
	v_pk_add_f32 v[144:145], v[146:147], v[166:167] neg_lo:[0,1] neg_hi:[0,1]
	v_pk_add_f32 v[154:155], v[162:163], v[142:143]
	v_pk_add_f32 v[146:147], v[144:145], v[148:149]
	v_mov_b32_e32 v145, v143
	v_pk_add_f32 v[142:143], v[164:165], v[144:145]
	v_mov_b32_e32 v149, v163
	v_pk_add_f32 v[142:143], v[142:143], v[148:149] neg_lo:[0,1] neg_hi:[0,1]
	v_mov_b32_e32 v144, v146
	v_mov_b32_e32 v145, v155
	v_pk_add_f32 v[144:145], v[144:145], v[142:143] neg_lo:[0,1] neg_hi:[0,1]
	v_pk_add_f32 v[142:143], v[150:151], v[142:143] neg_lo:[0,1] neg_hi:[0,1]
	v_pk_add_f32 v[144:145], v[148:149], v[144:145] neg_lo:[0,1] neg_hi:[0,1]
	s_nop 0
	v_pk_add_f32 v[142:143], v[142:143], v[144:145]
	v_pk_add_f32 v[144:145], v[154:155], v[146:147]
	s_nop 0
	v_pk_add_f32 v[146:147], v[152:153], v[144:145]
	s_nop 0
	v_pk_add_f32 v[148:149], v[146:147], v[152:153] neg_lo:[0,1] neg_hi:[0,1]
	s_nop 0
	v_pk_add_f32 v[144:145], v[144:145], v[148:149] neg_lo:[0,1] neg_hi:[0,1]
	s_nop 0
	v_pk_add_f32 v[142:143], v[142:143], v[144:145]
	v_add_f32_e32 v144, v78, v130
	v_pk_add_f32 v[142:143], v[146:147], v[142:143]
	v_mul_f32_e64 v145, |v144|, s20
	v_cndmask_b32_e32 v142, v221, v142, vcc
	v_cmp_neq_f32_e32 vcc, s77, v186
	v_fma_f32 v146, |v144|, s20, -v145
	v_rndne_f32_e32 v147, v145
	v_cndmask_b32_e32 v143, v221, v143, vcc
	v_cmp_lt_f32_e64 vcc, |v186|, s79
	v_fma_f32 v146, |v144|, s51, v146
	v_sub_f32_e32 v145, v145, v147
	v_cndmask_b32_e32 v143, v143, v186, vcc
	v_cmp_lt_f32_e64 vcc, |v185|, s79
	v_add_f32_e32 v145, v145, v146
	v_exp_f32_e32 v145, v145
	v_cndmask_b32_e32 v142, v142, v185, vcc
	v_cvt_i32_f32_e32 v146, v147
	v_pk_add_f32 v[140:141], v[140:141], v[142:143] neg_lo:[0,1] neg_hi:[0,1]
	v_or_b32_e32 v142, 32, v184
	v_ashrrev_i32_e32 v143, 31, v142
	v_lshl_add_u64 v[142:143], v[142:143], 4, s[52:53]
	global_store_dwordx4 v[142:143], v[138:141], off
	v_cmp_ngt_f32_e64 vcc, |v144|, s54
	s_nop 0
	v_ldexp_f32 v139, v145, v146
	v_cndmask_b32_e32 v139, 0, v139, vcc
	v_cmp_nlt_f32_e64 vcc, |v144|, s55
	v_add_f32_e32 v145, v79, v131
	v_min_f32_e32 v138, 0, v144
	v_cndmask_b32_e32 v168, v221, v139, vcc
	v_add_f32_e32 v142, 1.0, v168
	v_add_f32_e32 v139, -1.0, v142
	v_sub_f32_e32 v140, v139, v142
	v_add_f32_e32 v140, 1.0, v140
	v_sub_f32_e32 v139, v168, v139
	v_add_f32_e32 v143, v139, v140
	v_mul_f32_e64 v139, |v145|, s20
	v_fma_f32 v140, |v145|, s20, -v139
	v_rndne_f32_e32 v141, v139
	v_fma_f32 v140, |v145|, s51, v140
	v_sub_f32_e32 v139, v139, v141
	v_add_f32_e32 v139, v139, v140
	v_exp_f32_e32 v146, v139
	v_cvt_i32_f32_e32 v147, v141
	v_cvt_f64_f32_e32 v[140:141], v142
	v_frexp_exp_i32_f64_e32 v148, v[140:141]
	v_cmp_ngt_f32_e64 vcc, |v145|, s54
	v_ldexp_f32 v140, v146, v147
	v_min_f32_e32 v139, 0, v145
	v_cndmask_b32_e32 v140, 0, v140, vcc
	v_cmp_nlt_f32_e64 vcc, |v145|, s55
	v_frexp_mant_f32_e32 v144, v142
	s_nop 0
	v_cndmask_b32_e32 v169, v221, v140, vcc
	v_add_f32_e32 v145, 1.0, v169
	v_add_f32_e32 v140, -1.0, v145
	v_sub_f32_e32 v141, v140, v145
	v_add_f32_e32 v141, 1.0, v141
	v_sub_f32_e32 v140, v169, v140
	v_add_f32_e32 v146, v140, v141
	v_frexp_mant_f32_e32 v147, v145
	v_cvt_f64_f32_e32 v[140:141], v145
	v_frexp_exp_i32_f64_e32 v140, v[140:141]
	v_cmp_gt_f32_e32 vcc, s78, v147
	s_nop 1
	v_subbrev_co_u32_e32 v160, vcc, 0, v140, vcc
	v_cmp_gt_f32_e32 vcc, s78, v144
	s_nop 1
; __device__ __forceinline__ void epi_all_run(const void* Pk_, int l, int s, const f32x4 (&acc)[2][2][4][2], const pg8::Unit& u, int wr, int wc, int fr, int fq) {
;     ...
;                 for (int ai = 0; ai < 2; ++ai)
; #pragma unroll
;                     for (int m = 0; m < 4; ++m) {
;                         const int row = row0 + ai * 128 + m * 16;
;                         const f32x4 z = acc[ai][0][m][0] + fbv;
;                         f32x4 ls;
; #pragma unroll
;                         for (int j = 0; j < 4; ++j) ls[j] = fminf(z[j], 0.f) - log1pf(expf(-fabsf(z[j])));
	v_subbrev_co_u32_e32 v161, vcc, 0, v148, vcc
	v_sub_u32_e32 v141, 0, v161
	v_ldexp_f32 v140, v142, v141
	v_ldexp_f32 v142, v143, v141
	v_sub_u32_e32 v143, 0, v160
	v_ldexp_f32 v141, v145, v143
	v_pk_add_f32 v[144:145], v[140:141], 1.0 op_sel_hi:[1,0]
	v_ldexp_f32 v143, v146, v143
	v_pk_add_f32 v[146:147], v[144:145], -1.0 op_sel_hi:[1,0]
	v_pk_add_f32 v[152:153], v[140:141], -1.0 op_sel_hi:[1,0]
	v_pk_add_f32 v[146:147], v[140:141], v[146:147] neg_lo:[0,1] neg_hi:[0,1]
	v_pk_add_f32 v[154:155], v[152:153], 1.0 op_sel_hi:[1,0]
	v_pk_add_f32 v[146:147], v[142:143], v[146:147]
	v_pk_add_f32 v[140:141], v[140:141], v[154:155] neg_lo:[0,1] neg_hi:[0,1]
	v_pk_add_f32 v[148:149], v[144:145], v[146:147]
	v_pk_add_f32 v[140:141], v[142:143], v[140:141]
	v_rcp_f32_e32 v150, v148
	v_rcp_f32_e32 v151, v149
	v_pk_add_f32 v[142:143], v[152:153], v[140:141]
	v_pk_add_f32 v[144:145], v[144:145], v[148:149] neg_lo:[0,1] neg_hi:[0,1]
	v_pk_add_f32 v[152:153], v[152:153], v[142:143] neg_lo:[0,1] neg_hi:[0,1]
	v_pk_add_f32 v[144:145], v[146:147], v[144:145]
	v_pk_mul_f32 v[146:147], v[142:143], v[150:151]
	v_pk_add_f32 v[140:141], v[140:141], v[152:153]
	v_pk_mul_f32 v[152:153], v[148:149], v[146:147]
	v_cmp_neq_f32_e32 vcc, s77, v168
	v_pk_fma_f32 v[154:155], v[146:147], v[148:149], v[152:153] neg_lo:[0,0,1] neg_hi:[0,0,1]
	s_nop 0
	v_pk_fma_f32 v[154:155], v[146:147], v[144:145], v[154:155]
	s_nop 0
	v_pk_add_f32 v[156:157], v[152:153], v[154:155]
	s_nop 0
	v_pk_add_f32 v[158:159], v[142:143], v[156:157] neg_lo:[0,1] neg_hi:[0,1]
	v_pk_add_f32 v[152:153], v[156:157], v[152:153] neg_lo:[0,1] neg_hi:[0,1]
	v_pk_add_f32 v[142:143], v[142:143], v[158:159] neg_lo:[0,1] neg_hi:[0,1]
	s_nop 0
	v_pk_add_f32 v[142:143], v[142:143], v[156:157] neg_lo:[0,1] neg_hi:[0,1]
	s_nop 0
	v_pk_add_f32 v[140:141], v[140:141], v[142:143]
	v_pk_add_f32 v[142:143], v[152:153], v[154:155] neg_lo:[0,1] neg_hi:[0,1]
	s_nop 0
	v_pk_add_f32 v[140:141], v[142:143], v[140:141]
	s_nop 0
	v_pk_add_f32 v[142:143], v[158:159], v[140:141]
	s_nop 0
	v_pk_mul_f32 v[152:153], v[150:151], v[142:143]
	s_nop 0
	v_pk_mul_f32 v[154:155], v[148:149], v[152:153]
	s_nop 0
	v_pk_fma_f32 v[148:149], v[152:153], v[148:149], v[154:155] neg_lo:[0,0,1] neg_hi:[0,0,1]
	s_nop 0
	v_pk_fma_f32 v[144:145], v[152:153], v[144:145], v[148:149]
	v_pk_add_f32 v[148:149], v[158:159], v[142:143] neg_lo:[0,1] neg_hi:[0,1]
	s_nop 0
	v_pk_add_f32 v[140:141], v[140:141], v[148:149]
	v_pk_add_f32 v[148:149], v[154:155], v[144:145]
	s_nop 0
	v_pk_add_f32 v[156:157], v[142:143], v[148:149] neg_lo:[0,1] neg_hi:[0,1]
	v_pk_add_f32 v[154:155], v[148:149], v[154:155] neg_lo:[0,1] neg_hi:[0,1]
	v_pk_add_f32 v[142:143], v[142:143], v[156:157] neg_lo:[0,1] neg_hi:[0,1]
	s_nop 0
	v_pk_add_f32 v[142:143], v[142:143], v[148:149] neg_lo:[0,1] neg_hi:[0,1]
	s_nop 0
	v_pk_add_f32 v[140:141], v[140:141], v[142:143]
	v_pk_add_f32 v[142:143], v[154:155], v[144:145] neg_lo:[0,1] neg_hi:[0,1]
	s_nop 0
	v_pk_add_f32 v[140:141], v[142:143], v[140:141]
	v_pk_add_f32 v[142:143], v[146:147], v[152:153]
	v_pk_add_f32 v[140:141], v[156:157], v[140:141]
	v_pk_add_f32 v[144:145], v[142:143], v[146:147] neg_lo:[0,1] neg_hi:[0,1]
	v_pk_mul_f32 v[140:141], v[150:151], v[140:141]
	v_pk_add_f32 v[144:145], v[152:153], v[144:145] neg_lo:[0,1] neg_hi:[0,1]
	v_cvt_f32_i32_e32 v147, v160
	v_pk_add_f32 v[140:141], v[144:145], v[140:141]
	v_cvt_f32_i32_e32 v146, v161
	v_pk_add_f32 v[144:145], v[142:143], v[140:141]
	v_pk_mul_f32 v[152:153], v[146:147], s[84:85] op_sel_hi:[1,0]
	v_pk_mul_f32 v[148:149], v[144:145], v[144:145]
	v_pk_add_f32 v[142:143], v[144:145], v[142:143] neg_lo:[0,1] neg_hi:[0,1]
	v_pk_fma_f32 v[150:151], v[148:149], s[80:81], v[134:135] op_sel_hi:[1,0,0]
	v_pk_add_f32 v[140:141], v[140:141], v[142:143] neg_lo:[0,1] neg_hi:[0,1]
	v_ldexp_f32 v142, v144, 1
	v_pk_fma_f32 v[150:151], v[148:149], v[150:151], s[82:83] op_sel_hi:[1,1,0]
	v_ldexp_f32 v143, v145, 1
	v_pk_mul_f32 v[144:145], v[144:145], v[148:149]
	v_pk_fma_f32 v[154:155], v[146:147], s[84:85], v[152:153] op_sel_hi:[1,0,1] neg_lo:[0,0,1] neg_hi:[0,0,1]
	v_pk_mul_f32 v[144:145], v[144:145], v[150:151]
	v_mov_b32_e32 v157, v143
	v_pk_add_f32 v[148:149], v[142:143], v[144:145]
	v_ldexp_f32 v140, v140, 1
	v_pk_add_f32 v[142:143], v[148:149], v[142:143] neg_lo:[0,1] neg_hi:[0,1]
	v_pk_fma_f32 v[146:147], v[146:147], s[86:87], v[154:155] op_sel_hi:[1,0,1]
	v_ldexp_f32 v141, v141, 1
	v_pk_add_f32 v[142:143], v[144:145], v[142:143] neg_lo:[0,1] neg_hi:[0,1]
	v_mov_b32_e32 v150, v152
	v_mov_b32_e32 v151, v145
	v_mov_b32_e32 v156, v146
	v_pk_add_f32 v[144:145], v[140:141], v[142:143]
	v_mov_b32_e32 v142, v152
	v_mov_b32_e32 v140, v146
	v_pk_add_f32 v[150:151], v[150:151], v[156:157]
	v_pk_add_f32 v[156:157], v[142:143], v[140:141]
	v_mov_b32_e32 v140, v148
	v_mov_b32_e32 v142, v144
	v_pk_add_f32 v[154:155], v[152:153], v[146:147]
	v_pk_add_f32 v[140:141], v[140:141], v[142:143]
	v_pk_add_f32 v[142:143], v[148:149], v[144:145]
	v_mov_b32_e32 v158, v154
	v_mov_b32_e32 v159, v153
	v_mov_b32_e32 v160, v142
	v_mov_b32_e32 v161, v147
	v_pk_add_f32 v[140:141], v[150:151], v[140:141]
	v_pk_add_f32 v[150:151], v[154:155], v[142:143]
	v_pk_add_f32 v[162:163], v[158:159], v[160:161]
	v_mov_b32_e32 v164, v142
	v_mov_b32_e32 v165, v151
	v_mov_b32_e32 v166, v148
	v_mov_b32_e32 v167, v155
	v_pk_add_f32 v[158:159], v[162:163], v[158:159] neg_lo:[0,1] neg_hi:[0,1]
	v_pk_add_f32 v[164:165], v[164:165], v[166:167] neg_lo:[0,1] neg_hi:[0,1]
	v_pk_add_f32 v[162:163], v[154:155], v[152:153] neg_lo:[0,1] neg_hi:[0,1]
	v_pk_add_f32 v[160:161], v[160:161], v[158:159] neg_lo:[0,1] neg_hi:[0,1]
	v_mov_b32_e32 v166, v154
; __device__ __forceinline__ void epi_all_run(const void* Pk_, int l, int s, const f32x4 (&acc)[2][2][4][2], const pg8::Unit& u, int wr, int wc, int fr, int fq) {
;     ...
;             } else if (wc == 0 && fq == 0) {
;                 float* logf = (float*)(ws + WS_LOGF);
;                 const f32x4 fbv = *(const f32x4*)(A.fox_fb + l * 4);
; #pragma unroll
;                 for (int ai = 0; ai < 2; ++ai)
; #pragma unroll
;                     for (int m = 0; m < 4; ++m) {
;                         const int row = row0 + ai * 128 + m * 16;
;                         const f32x4 z = acc[ai][0][m][0] + fbv;
;                         f32x4 ls;
; #pragma unroll
;                         for (int j = 0; j < 4; ++j) ls[j] = fminf(z[j], 0.f) - log1pf(expf(-fabsf(z[j])));
;                         *(f32x4*)(logf + (size_t)row * 4) = ls;
;                     }
;             }
	v_mov_b32_e32 v167, v151
	v_mov_b32_e32 v153, v165
	v_mov_b32_e32 v159, v149
	v_pk_add_f32 v[148:149], v[142:143], v[148:149] neg_lo:[0,1] neg_hi:[0,1]
	v_pk_add_f32 v[152:153], v[166:167], v[152:153] neg_lo:[0,1] neg_hi:[0,1]
	v_pk_add_f32 v[162:163], v[146:147], v[162:163] neg_lo:[0,1] neg_hi:[0,1]
	v_pk_add_f32 v[140:141], v[140:141], v[158:159] neg_lo:[0,1] neg_hi:[0,1]
	v_pk_add_f32 v[148:149], v[144:145], v[148:149] neg_lo:[0,1] neg_hi:[0,1]
	v_mov_b32_e32 v147, v155
	v_mov_b32_e32 v145, v143
	v_pk_add_f32 v[140:141], v[156:157], v[140:141] neg_lo:[0,1] neg_hi:[0,1]
	v_pk_add_f32 v[146:147], v[146:147], v[152:153] neg_lo:[0,1] neg_hi:[0,1]
	v_pk_add_f32 v[142:143], v[144:145], v[164:165] neg_lo:[0,1] neg_hi:[0,1]
	v_pk_add_f32 v[152:153], v[160:161], v[140:141]
	v_pk_add_f32 v[144:145], v[142:143], v[146:147]
	v_mov_b32_e32 v143, v141
	v_pk_add_f32 v[140:141], v[162:163], v[142:143]
	v_mov_b32_e32 v147, v161
	v_pk_add_f32 v[140:141], v[140:141], v[146:147] neg_lo:[0,1] neg_hi:[0,1]
	v_mov_b32_e32 v142, v144
	v_mov_b32_e32 v143, v153
	v_pk_add_f32 v[142:143], v[142:143], v[140:141] neg_lo:[0,1] neg_hi:[0,1]
	v_pk_add_f32 v[140:141], v[148:149], v[140:141] neg_lo:[0,1] neg_hi:[0,1]
	v_pk_add_f32 v[142:143], v[146:147], v[142:143] neg_lo:[0,1] neg_hi:[0,1]
	s_nop 0
	v_pk_add_f32 v[140:141], v[140:141], v[142:143]
	v_pk_add_f32 v[142:143], v[152:153], v[144:145]
	s_nop 0
	v_pk_add_f32 v[144:145], v[150:151], v[142:143]
	s_nop 0
	v_pk_add_f32 v[146:147], v[144:145], v[150:151] neg_lo:[0,1] neg_hi:[0,1]
	s_nop 0
	v_pk_add_f32 v[142:143], v[142:143], v[146:147] neg_lo:[0,1] neg_hi:[0,1]
	v_add_f32_e32 v147, v81, v133
	v_pk_add_f32 v[140:141], v[140:141], v[142:143]
	v_add_f32_e32 v142, v80, v132
	v_mul_f32_e64 v143, |v142|, s20
	v_pk_add_f32 v[140:141], v[144:145], v[140:141]
	v_fma_f32 v144, |v142|, s20, -v143
	v_rndne_f32_e32 v145, v143
	v_fma_f32 v144, |v142|, s51, v144
	v_sub_f32_e32 v143, v143, v145
	v_add_f32_e32 v143, v143, v144
	v_cndmask_b32_e32 v140, v221, v140, vcc
	v_cmp_neq_f32_e32 vcc, s77, v169
	v_exp_f32_e32 v143, v143
	v_cvt_i32_f32_e32 v144, v145
	v_cndmask_b32_e32 v141, v221, v141, vcc
	v_cmp_lt_f32_e64 vcc, |v169|, s79
	s_nop 1
	v_cndmask_b32_e32 v141, v141, v169, vcc
	v_cmp_lt_f32_e64 vcc, |v168|, s79
	s_nop 1
	v_cndmask_b32_e32 v140, v140, v168, vcc
	v_pk_add_f32 v[138:139], v[138:139], v[140:141] neg_lo:[0,1] neg_hi:[0,1]
	v_ldexp_f32 v141, v143, v144
	v_cmp_ngt_f32_e64 vcc, |v142|, s54
	v_min_f32_e32 v140, 0, v142
	s_nop 0
	v_cndmask_b32_e32 v141, 0, v141, vcc
	v_cmp_nlt_f32_e64 vcc, |v142|, s55
	s_nop 1
	v_cndmask_b32_e32 v185, v221, v141, vcc
	v_add_f32_e32 v144, 1.0, v185
	v_add_f32_e32 v141, -1.0, v144
	v_sub_f32_e32 v142, v141, v144
	v_add_f32_e32 v142, 1.0, v142
	v_sub_f32_e32 v141, v185, v141
	v_add_f32_e32 v145, v141, v142
	v_mul_f32_e64 v141, |v147|, s20
	v_fma_f32 v142, |v147|, s20, -v141
	v_rndne_f32_e32 v143, v141
	v_fma_f32 v142, |v147|, s51, v142
	v_sub_f32_e32 v141, v141, v143
	v_add_f32_e32 v141, v141, v142
	v_exp_f32_e32 v148, v141
	v_cvt_i32_f32_e32 v149, v143
	v_cvt_f64_f32_e32 v[142:143], v144
	v_frexp_exp_i32_f64_e32 v150, v[142:143]
	v_cmp_ngt_f32_e64 vcc, |v147|, s54
	v_ldexp_f32 v142, v148, v149
	v_min_f32_e32 v141, 0, v147
	v_cndmask_b32_e32 v142, 0, v142, vcc
	v_cmp_nlt_f32_e64 vcc, |v147|, s55
	v_frexp_mant_f32_e32 v146, v144
	s_nop 0
	v_cndmask_b32_e32 v186, v221, v142, vcc
	v_add_f32_e32 v147, 1.0, v186
	v_add_f32_e32 v142, -1.0, v147
	v_sub_f32_e32 v143, v142, v147
	v_add_f32_e32 v143, 1.0, v143
	v_sub_f32_e32 v142, v186, v142
	v_add_f32_e32 v148, v142, v143
	v_frexp_mant_f32_e32 v149, v147
	v_cvt_f64_f32_e32 v[142:143], v147
	v_frexp_exp_i32_f64_e32 v142, v[142:143]
	v_cmp_gt_f32_e32 vcc, s78, v149
	s_nop 1
	v_subbrev_co_u32_e32 v162, vcc, 0, v142, vcc
	v_cmp_gt_f32_e32 vcc, s78, v146
	s_nop 1
	v_subbrev_co_u32_e32 v163, vcc, 0, v150, vcc
	v_sub_u32_e32 v143, 0, v163
	v_ldexp_f32 v142, v144, v143
	v_ldexp_f32 v144, v145, v143
	v_sub_u32_e32 v145, 0, v162
	v_ldexp_f32 v143, v147, v145
	v_pk_add_f32 v[146:147], v[142:143], 1.0 op_sel_hi:[1,0]
	v_ldexp_f32 v145, v148, v145
	v_pk_add_f32 v[148:149], v[146:147], -1.0 op_sel_hi:[1,0]
	v_pk_add_f32 v[154:155], v[142:143], -1.0 op_sel_hi:[1,0]
	v_pk_add_f32 v[148:149], v[142:143], v[148:149] neg_lo:[0,1] neg_hi:[0,1]
	v_pk_add_f32 v[156:157], v[154:155], 1.0 op_sel_hi:[1,0]
	v_pk_add_f32 v[148:149], v[144:145], v[148:149]
	v_pk_add_f32 v[142:143], v[142:143], v[156:157] neg_lo:[0,1] neg_hi:[0,1]
	v_pk_add_f32 v[150:151], v[146:147], v[148:149]
	v_pk_add_f32 v[142:143], v[144:145], v[142:143]
	v_rcp_f32_e32 v152, v150
	v_rcp_f32_e32 v153, v151
	v_pk_add_f32 v[144:145], v[154:155], v[142:143]
	v_pk_add_f32 v[146:147], v[146:147], v[150:151] neg_lo:[0,1] neg_hi:[0,1]
	v_pk_add_f32 v[154:155], v[154:155], v[144:145] neg_lo:[0,1] neg_hi:[0,1]
	v_pk_add_f32 v[146:147], v[148:149], v[146:147]
	v_pk_mul_f32 v[148:149], v[144:145], v[152:153]
	v_pk_add_f32 v[142:143], v[142:143], v[154:155]
	v_pk_mul_f32 v[154:155], v[150:151], v[148:149]
	v_cmp_neq_f32_e32 vcc, s77, v185
	v_pk_fma_f32 v[156:157], v[148:149], v[150:151], v[154:155] neg_lo:[0,0,1] neg_hi:[0,0,1]
	s_nop 0
	v_pk_fma_f32 v[156:157], v[148:149], v[146:147], v[156:157]
	s_nop 0
	v_pk_add_f32 v[158:159], v[154:155], v[156:157]
	s_nop 0
	v_pk_add_f32 v[160:161], v[144:145], v[158:159] neg_lo:[0,1] neg_hi:[0,1]
	v_pk_add_f32 v[154:155], v[158:159], v[154:155] neg_lo:[0,1] neg_hi:[0,1]
	v_pk_add_f32 v[144:145], v[144:145], v[160:161] neg_lo:[0,1] neg_hi:[0,1]
	s_nop 0
	v_pk_add_f32 v[144:145], v[144:145], v[158:159] neg_lo:[0,1] neg_hi:[0,1]
	s_nop 0
	v_pk_add_f32 v[142:143], v[142:143], v[144:145]
; __device__ __forceinline__ void epi_all_run(const void* Pk_, int l, int s, const f32x4 (&acc)[2][2][4][2], const pg8::Unit& u, int wr, int wc, int fr, int fq) {
;     ...
;                         for (int j = 0; j < 4; ++j) ls[j] = fminf(z[j], 0.f) - log1pf(expf(-fabsf(z[j])));
	v_pk_add_f32 v[144:145], v[154:155], v[156:157] neg_lo:[0,1] neg_hi:[0,1]
	s_nop 0
	v_pk_add_f32 v[142:143], v[144:145], v[142:143]
	s_nop 0
	v_pk_add_f32 v[144:145], v[160:161], v[142:143]
	s_nop 0
	v_pk_mul_f32 v[154:155], v[152:153], v[144:145]
	s_nop 0
	v_pk_mul_f32 v[156:157], v[150:151], v[154:155]
	s_nop 0
	v_pk_fma_f32 v[150:151], v[154:155], v[150:151], v[156:157] neg_lo:[0,0,1] neg_hi:[0,0,1]
	s_nop 0
	v_pk_fma_f32 v[146:147], v[154:155], v[146:147], v[150:151]
	v_pk_add_f32 v[150:151], v[160:161], v[144:145] neg_lo:[0,1] neg_hi:[0,1]
	s_nop 0
	v_pk_add_f32 v[142:143], v[142:143], v[150:151]
	v_pk_add_f32 v[150:151], v[156:157], v[146:147]
	s_nop 0
	v_pk_add_f32 v[158:159], v[144:145], v[150:151] neg_lo:[0,1] neg_hi:[0,1]
	v_pk_add_f32 v[156:157], v[150:151], v[156:157] neg_lo:[0,1] neg_hi:[0,1]
	v_pk_add_f32 v[144:145], v[144:145], v[158:159] neg_lo:[0,1] neg_hi:[0,1]
	s_nop 0
	v_pk_add_f32 v[144:145], v[144:145], v[150:151] neg_lo:[0,1] neg_hi:[0,1]
	s_nop 0
	v_pk_add_f32 v[142:143], v[142:143], v[144:145]
	v_pk_add_f32 v[144:145], v[156:157], v[146:147] neg_lo:[0,1] neg_hi:[0,1]
	s_nop 0
	v_pk_add_f32 v[142:143], v[144:145], v[142:143]
	v_pk_add_f32 v[144:145], v[148:149], v[154:155]
	v_pk_add_f32 v[142:143], v[158:159], v[142:143]
	v_pk_add_f32 v[146:147], v[144:145], v[148:149] neg_lo:[0,1] neg_hi:[0,1]
	v_pk_mul_f32 v[142:143], v[152:153], v[142:143]
	v_pk_add_f32 v[146:147], v[154:155], v[146:147] neg_lo:[0,1] neg_hi:[0,1]
	v_cvt_f32_i32_e32 v149, v162
	v_pk_add_f32 v[142:143], v[146:147], v[142:143]
	v_cvt_f32_i32_e32 v148, v163
	v_pk_add_f32 v[146:147], v[144:145], v[142:143]
	v_pk_mul_f32 v[154:155], v[148:149], s[84:85] op_sel_hi:[1,0]
	v_pk_mul_f32 v[150:151], v[146:147], v[146:147]
	v_pk_add_f32 v[144:145], v[146:147], v[144:145] neg_lo:[0,1] neg_hi:[0,1]
	v_pk_fma_f32 v[152:153], v[150:151], s[80:81], v[134:135] op_sel_hi:[1,0,0]
	v_pk_add_f32 v[142:143], v[142:143], v[144:145] neg_lo:[0,1] neg_hi:[0,1]
	v_ldexp_f32 v144, v146, 1
	v_pk_fma_f32 v[152:153], v[150:151], v[152:153], s[82:83] op_sel_hi:[1,1,0]
	v_ldexp_f32 v145, v147, 1
	v_pk_mul_f32 v[146:147], v[146:147], v[150:151]
	v_pk_fma_f32 v[156:157], v[148:149], s[84:85], v[154:155] op_sel_hi:[1,0,1] neg_lo:[0,0,1] neg_hi:[0,0,1]
	v_pk_mul_f32 v[146:147], v[146:147], v[152:153]
	v_mov_b32_e32 v159, v145
	v_pk_add_f32 v[150:151], v[144:145], v[146:147]
	v_ldexp_f32 v142, v142, 1
	v_pk_add_f32 v[144:145], v[150:151], v[144:145] neg_lo:[0,1] neg_hi:[0,1]
	v_pk_fma_f32 v[148:149], v[148:149], s[86:87], v[156:157] op_sel_hi:[1,0,1]
	v_ldexp_f32 v143, v143, 1
	v_pk_add_f32 v[144:145], v[146:147], v[144:145] neg_lo:[0,1] neg_hi:[0,1]
	v_mov_b32_e32 v152, v154
	v_mov_b32_e32 v153, v147
	v_mov_b32_e32 v158, v148
	v_pk_add_f32 v[146:147], v[142:143], v[144:145]
	v_mov_b32_e32 v144, v154
	v_mov_b32_e32 v142, v148
	v_pk_add_f32 v[152:153], v[152:153], v[158:159]
	v_pk_add_f32 v[158:159], v[144:145], v[142:143]
	v_mov_b32_e32 v142, v150
	v_mov_b32_e32 v144, v146
	v_pk_add_f32 v[156:157], v[154:155], v[148:149]
	v_pk_add_f32 v[142:143], v[142:143], v[144:145]
	v_pk_add_f32 v[144:145], v[150:151], v[146:147]
	v_mov_b32_e32 v160, v156
	v_mov_b32_e32 v161, v155
	v_mov_b32_e32 v162, v144
	v_mov_b32_e32 v163, v149
	v_pk_add_f32 v[142:143], v[152:153], v[142:143]
	v_pk_add_f32 v[152:153], v[156:157], v[144:145]
	v_pk_add_f32 v[164:165], v[160:161], v[162:163]
	v_mov_b32_e32 v166, v144
	v_mov_b32_e32 v167, v153
	v_mov_b32_e32 v168, v150
	v_mov_b32_e32 v169, v157
	v_pk_add_f32 v[160:161], v[164:165], v[160:161] neg_lo:[0,1] neg_hi:[0,1]
	v_pk_add_f32 v[166:167], v[166:167], v[168:169] neg_lo:[0,1] neg_hi:[0,1]
	v_pk_add_f32 v[164:165], v[156:157], v[154:155] neg_lo:[0,1] neg_hi:[0,1]
	v_pk_add_f32 v[162:163], v[162:163], v[160:161] neg_lo:[0,1] neg_hi:[0,1]
	v_mov_b32_e32 v168, v156
	v_mov_b32_e32 v169, v153
	v_mov_b32_e32 v155, v167
	v_mov_b32_e32 v161, v151
	v_pk_add_f32 v[150:151], v[144:145], v[150:151] neg_lo:[0,1] neg_hi:[0,1]
	v_pk_add_f32 v[154:155], v[168:169], v[154:155] neg_lo:[0,1] neg_hi:[0,1]
	v_pk_add_f32 v[164:165], v[148:149], v[164:165] neg_lo:[0,1] neg_hi:[0,1]
	v_pk_add_f32 v[142:143], v[142:143], v[160:161] neg_lo:[0,1] neg_hi:[0,1]
	v_pk_add_f32 v[150:151], v[146:147], v[150:151] neg_lo:[0,1] neg_hi:[0,1]
	v_mov_b32_e32 v149, v157
	v_mov_b32_e32 v147, v145
	v_pk_add_f32 v[142:143], v[158:159], v[142:143] neg_lo:[0,1] neg_hi:[0,1]
	v_pk_add_f32 v[148:149], v[148:149], v[154:155] neg_lo:[0,1] neg_hi:[0,1]
	v_pk_add_f32 v[144:145], v[146:147], v[166:167] neg_lo:[0,1] neg_hi:[0,1]
	v_pk_add_f32 v[154:155], v[162:163], v[142:143]
	v_pk_add_f32 v[146:147], v[144:145], v[148:149]
	v_mov_b32_e32 v145, v143
	v_pk_add_f32 v[142:143], v[164:165], v[144:145]
	v_mov_b32_e32 v149, v163
	v_pk_add_f32 v[142:143], v[142:143], v[148:149] neg_lo:[0,1] neg_hi:[0,1]
	v_mov_b32_e32 v144, v146
	v_mov_b32_e32 v145, v155
	v_pk_add_f32 v[144:145], v[144:145], v[142:143] neg_lo:[0,1] neg_hi:[0,1]
	v_pk_add_f32 v[142:143], v[150:151], v[142:143] neg_lo:[0,1] neg_hi:[0,1]
	v_pk_add_f32 v[144:145], v[148:149], v[144:145] neg_lo:[0,1] neg_hi:[0,1]
	s_nop 0
	v_pk_add_f32 v[142:143], v[142:143], v[144:145]
	v_pk_add_f32 v[144:145], v[154:155], v[146:147]
	s_nop 0
	v_pk_add_f32 v[146:147], v[152:153], v[144:145]
	s_nop 0
	v_pk_add_f32 v[148:149], v[146:147], v[152:153] neg_lo:[0,1] neg_hi:[0,1]
	s_nop 0
	v_pk_add_f32 v[144:145], v[144:145], v[148:149] neg_lo:[0,1] neg_hi:[0,1]
	s_nop 0
	v_pk_add_f32 v[142:143], v[142:143], v[144:145]
	v_add_f32_e32 v144, v62, v130
	v_pk_add_f32 v[142:143], v[146:147], v[142:143]
	v_mul_f32_e64 v145, |v144|, s20
	v_cndmask_b32_e32 v142, v221, v142, vcc
; __device__ __forceinline__ void epi_all_run(const void* Pk_, int l, int s, const f32x4 (&acc)[2][2][4][2], const pg8::Unit& u, int wr, int wc, int fr, int fq) {
;     ...
;                         const f32x4 z = acc[ai][0][m][0] + fbv;
;                         f32x4 ls;
; #pragma unroll
;                         for (int j = 0; j < 4; ++j) ls[j] = fminf(z[j], 0.f) - log1pf(expf(-fabsf(z[j])));
;                         *(f32x4*)(logf + (size_t)row * 4) = ls;
	v_cmp_neq_f32_e32 vcc, s77, v186
	v_fma_f32 v146, |v144|, s20, -v145
	v_rndne_f32_e32 v147, v145
	v_cndmask_b32_e32 v143, v221, v143, vcc
	v_cmp_lt_f32_e64 vcc, |v186|, s79
	v_fma_f32 v146, |v144|, s51, v146
	v_sub_f32_e32 v145, v145, v147
	v_cndmask_b32_e32 v143, v143, v186, vcc
	v_cmp_lt_f32_e64 vcc, |v185|, s79
	v_add_f32_e32 v145, v145, v146
	v_exp_f32_e32 v145, v145
	v_cndmask_b32_e32 v142, v142, v185, vcc
	v_cvt_i32_f32_e32 v146, v147
	v_pk_add_f32 v[140:141], v[140:141], v[142:143] neg_lo:[0,1] neg_hi:[0,1]
	v_or_b32_e32 v142, 48, v184
	v_ashrrev_i32_e32 v143, 31, v142
	v_lshl_add_u64 v[142:143], v[142:143], 4, s[52:53]
	global_store_dwordx4 v[142:143], v[138:141], off
	v_cmp_ngt_f32_e64 vcc, |v144|, s54
	s_nop 0
	v_ldexp_f32 v139, v145, v146
	v_cndmask_b32_e32 v139, 0, v139, vcc
	v_cmp_nlt_f32_e64 vcc, |v144|, s55
	v_add_f32_e32 v145, v63, v131
	v_min_f32_e32 v138, 0, v144
	v_cndmask_b32_e32 v168, v221, v139, vcc
	v_add_f32_e32 v142, 1.0, v168
	v_add_f32_e32 v139, -1.0, v142
	v_sub_f32_e32 v140, v139, v142
	v_add_f32_e32 v140, 1.0, v140
	v_sub_f32_e32 v139, v168, v139
	v_add_f32_e32 v143, v139, v140
	v_mul_f32_e64 v139, |v145|, s20
	v_fma_f32 v140, |v145|, s20, -v139
	v_rndne_f32_e32 v141, v139
	v_fma_f32 v140, |v145|, s51, v140
	v_sub_f32_e32 v139, v139, v141
	v_add_f32_e32 v139, v139, v140
	v_exp_f32_e32 v146, v139
	v_cvt_i32_f32_e32 v147, v141
	v_cvt_f64_f32_e32 v[140:141], v142
	v_frexp_exp_i32_f64_e32 v148, v[140:141]
	v_cmp_ngt_f32_e64 vcc, |v145|, s54
	v_ldexp_f32 v140, v146, v147
	v_min_f32_e32 v139, 0, v145
	v_cndmask_b32_e32 v140, 0, v140, vcc
	v_cmp_nlt_f32_e64 vcc, |v145|, s55
	v_frexp_mant_f32_e32 v144, v142
	s_nop 0
	v_cndmask_b32_e32 v169, v221, v140, vcc
	v_add_f32_e32 v145, 1.0, v169
	v_add_f32_e32 v140, -1.0, v145
	v_sub_f32_e32 v141, v140, v145
	v_add_f32_e32 v141, 1.0, v141
	v_sub_f32_e32 v140, v169, v140
	v_add_f32_e32 v146, v140, v141
	v_frexp_mant_f32_e32 v147, v145
	v_cvt_f64_f32_e32 v[140:141], v145
	v_frexp_exp_i32_f64_e32 v140, v[140:141]
	v_cmp_gt_f32_e32 vcc, s78, v147
	s_nop 1
	v_subbrev_co_u32_e32 v160, vcc, 0, v140, vcc
	v_cmp_gt_f32_e32 vcc, s78, v144
	s_nop 1
	v_subbrev_co_u32_e32 v161, vcc, 0, v148, vcc
	v_sub_u32_e32 v141, 0, v161
	v_ldexp_f32 v140, v142, v141
	v_ldexp_f32 v142, v143, v141
	v_sub_u32_e32 v143, 0, v160
	v_ldexp_f32 v141, v145, v143
	v_pk_add_f32 v[144:145], v[140:141], 1.0 op_sel_hi:[1,0]
	v_ldexp_f32 v143, v146, v143
	v_pk_add_f32 v[146:147], v[144:145], -1.0 op_sel_hi:[1,0]
	v_pk_add_f32 v[152:153], v[140:141], -1.0 op_sel_hi:[1,0]
	v_pk_add_f32 v[146:147], v[140:141], v[146:147] neg_lo:[0,1] neg_hi:[0,1]
	v_pk_add_f32 v[154:155], v[152:153], 1.0 op_sel_hi:[1,0]
	v_pk_add_f32 v[146:147], v[142:143], v[146:147]
	v_pk_add_f32 v[140:141], v[140:141], v[154:155] neg_lo:[0,1] neg_hi:[0,1]
	v_pk_add_f32 v[148:149], v[144:145], v[146:147]
	v_pk_add_f32 v[140:141], v[142:143], v[140:141]
	v_rcp_f32_e32 v150, v148
	v_rcp_f32_e32 v151, v149
	v_pk_add_f32 v[142:143], v[152:153], v[140:141]
	v_pk_add_f32 v[144:145], v[144:145], v[148:149] neg_lo:[0,1] neg_hi:[0,1]
	v_pk_add_f32 v[152:153], v[152:153], v[142:143] neg_lo:[0,1] neg_hi:[0,1]
	v_pk_add_f32 v[144:145], v[146:147], v[144:145]
	v_pk_mul_f32 v[146:147], v[142:143], v[150:151]
	v_pk_add_f32 v[140:141], v[140:141], v[152:153]
	v_pk_mul_f32 v[152:153], v[148:149], v[146:147]
	v_cmp_neq_f32_e32 vcc, s77, v168
	v_pk_fma_f32 v[154:155], v[146:147], v[148:149], v[152:153] neg_lo:[0,0,1] neg_hi:[0,0,1]
	s_nop 0
	v_pk_fma_f32 v[154:155], v[146:147], v[144:145], v[154:155]
	s_nop 0
	v_pk_add_f32 v[156:157], v[152:153], v[154:155]
	s_nop 0
	v_pk_add_f32 v[158:159], v[142:143], v[156:157] neg_lo:[0,1] neg_hi:[0,1]
	v_pk_add_f32 v[152:153], v[156:157], v[152:153] neg_lo:[0,1] neg_hi:[0,1]
	v_pk_add_f32 v[142:143], v[142:143], v[158:159] neg_lo:[0,1] neg_hi:[0,1]
	s_nop 0
	v_pk_add_f32 v[142:143], v[142:143], v[156:157] neg_lo:[0,1] neg_hi:[0,1]
	s_nop 0
	v_pk_add_f32 v[140:141], v[140:141], v[142:143]
	v_pk_add_f32 v[142:143], v[152:153], v[154:155] neg_lo:[0,1] neg_hi:[0,1]
	s_nop 0
	v_pk_add_f32 v[140:141], v[142:143], v[140:141]
	s_nop 0
	v_pk_add_f32 v[142:143], v[158:159], v[140:141]
	s_nop 0
	v_pk_mul_f32 v[152:153], v[150:151], v[142:143]
	s_nop 0
	v_pk_mul_f32 v[154:155], v[148:149], v[152:153]
	s_nop 0
	v_pk_fma_f32 v[148:149], v[152:153], v[148:149], v[154:155] neg_lo:[0,0,1] neg_hi:[0,0,1]
	s_nop 0
	v_pk_fma_f32 v[144:145], v[152:153], v[144:145], v[148:149]
	v_pk_add_f32 v[148:149], v[158:159], v[142:143] neg_lo:[0,1] neg_hi:[0,1]
	s_nop 0
	v_pk_add_f32 v[140:141], v[140:141], v[148:149]
	v_pk_add_f32 v[148:149], v[154:155], v[144:145]
	s_nop 0
	v_pk_add_f32 v[156:157], v[142:143], v[148:149] neg_lo:[0,1] neg_hi:[0,1]
	v_pk_add_f32 v[154:155], v[148:149], v[154:155] neg_lo:[0,1] neg_hi:[0,1]
	v_pk_add_f32 v[142:143], v[142:143], v[156:157] neg_lo:[0,1] neg_hi:[0,1]
	s_nop 0
	v_pk_add_f32 v[142:143], v[142:143], v[148:149] neg_lo:[0,1] neg_hi:[0,1]
	s_nop 0
	v_pk_add_f32 v[140:141], v[140:141], v[142:143]
	v_pk_add_f32 v[142:143], v[154:155], v[144:145] neg_lo:[0,1] neg_hi:[0,1]
	s_nop 0
	v_pk_add_f32 v[140:141], v[142:143], v[140:141]
	v_pk_add_f32 v[142:143], v[146:147], v[152:153]
	v_pk_add_f32 v[140:141], v[156:157], v[140:141]
	v_pk_add_f32 v[144:145], v[142:143], v[146:147] neg_lo:[0,1] neg_hi:[0,1]
	v_pk_mul_f32 v[140:141], v[150:151], v[140:141]
	v_pk_add_f32 v[144:145], v[152:153], v[144:145] neg_lo:[0,1] neg_hi:[0,1]
	v_cvt_f32_i32_e32 v147, v160
	v_pk_add_f32 v[140:141], v[144:145], v[140:141]
	v_cvt_f32_i32_e32 v146, v161
	v_pk_add_f32 v[144:145], v[142:143], v[140:141]
	v_pk_mul_f32 v[152:153], v[146:147], s[84:85] op_sel_hi:[1,0]
; __device__ __forceinline__ void epi_all_run(const void* Pk_, int l, int s, const f32x4 (&acc)[2][2][4][2], const pg8::Unit& u, int wr, int wc, int fr, int fq) {
;     ...
;                         for (int j = 0; j < 4; ++j) ls[j] = fminf(z[j], 0.f) - log1pf(expf(-fabsf(z[j])));
	v_pk_mul_f32 v[148:149], v[144:145], v[144:145]
	v_pk_add_f32 v[142:143], v[144:145], v[142:143] neg_lo:[0,1] neg_hi:[0,1]
	v_pk_fma_f32 v[150:151], v[148:149], s[80:81], v[134:135] op_sel_hi:[1,0,0]
	v_pk_add_f32 v[140:141], v[140:141], v[142:143] neg_lo:[0,1] neg_hi:[0,1]
	v_ldexp_f32 v142, v144, 1
	v_pk_fma_f32 v[150:151], v[148:149], v[150:151], s[82:83] op_sel_hi:[1,1,0]
	v_ldexp_f32 v143, v145, 1
	v_pk_mul_f32 v[144:145], v[144:145], v[148:149]
	v_pk_fma_f32 v[154:155], v[146:147], s[84:85], v[152:153] op_sel_hi:[1,0,1] neg_lo:[0,0,1] neg_hi:[0,0,1]
	v_pk_mul_f32 v[144:145], v[144:145], v[150:151]
	v_mov_b32_e32 v157, v143
	v_pk_add_f32 v[148:149], v[142:143], v[144:145]
	v_ldexp_f32 v140, v140, 1
	v_pk_add_f32 v[142:143], v[148:149], v[142:143] neg_lo:[0,1] neg_hi:[0,1]
	v_pk_fma_f32 v[146:147], v[146:147], s[86:87], v[154:155] op_sel_hi:[1,0,1]
	v_ldexp_f32 v141, v141, 1
	v_pk_add_f32 v[142:143], v[144:145], v[142:143] neg_lo:[0,1] neg_hi:[0,1]
	v_mov_b32_e32 v150, v152
	v_mov_b32_e32 v151, v145
	v_mov_b32_e32 v156, v146
	v_pk_add_f32 v[144:145], v[140:141], v[142:143]
	v_mov_b32_e32 v142, v152
	v_mov_b32_e32 v140, v146
	v_pk_add_f32 v[150:151], v[150:151], v[156:157]
	v_pk_add_f32 v[156:157], v[142:143], v[140:141]
	v_mov_b32_e32 v140, v148
	v_mov_b32_e32 v142, v144
	v_pk_add_f32 v[154:155], v[152:153], v[146:147]
	v_pk_add_f32 v[140:141], v[140:141], v[142:143]
	v_pk_add_f32 v[142:143], v[148:149], v[144:145]
	v_mov_b32_e32 v158, v154
	v_mov_b32_e32 v159, v153
	v_mov_b32_e32 v160, v142
	v_mov_b32_e32 v161, v147
	v_pk_add_f32 v[140:141], v[150:151], v[140:141]
	v_pk_add_f32 v[150:151], v[154:155], v[142:143]
	v_pk_add_f32 v[162:163], v[158:159], v[160:161]
	v_mov_b32_e32 v164, v142
	v_mov_b32_e32 v165, v151
	v_mov_b32_e32 v166, v148
	v_mov_b32_e32 v167, v155
	v_pk_add_f32 v[158:159], v[162:163], v[158:159] neg_lo:[0,1] neg_hi:[0,1]
	v_pk_add_f32 v[164:165], v[164:165], v[166:167] neg_lo:[0,1] neg_hi:[0,1]
	v_pk_add_f32 v[162:163], v[154:155], v[152:153] neg_lo:[0,1] neg_hi:[0,1]
	v_pk_add_f32 v[160:161], v[160:161], v[158:159] neg_lo:[0,1] neg_hi:[0,1]
	v_mov_b32_e32 v166, v154
	v_mov_b32_e32 v167, v151
	v_mov_b32_e32 v153, v165
	v_mov_b32_e32 v159, v149
	v_pk_add_f32 v[148:149], v[142:143], v[148:149] neg_lo:[0,1] neg_hi:[0,1]
	v_pk_add_f32 v[152:153], v[166:167], v[152:153] neg_lo:[0,1] neg_hi:[0,1]
	v_pk_add_f32 v[162:163], v[146:147], v[162:163] neg_lo:[0,1] neg_hi:[0,1]
	v_pk_add_f32 v[140:141], v[140:141], v[158:159] neg_lo:[0,1] neg_hi:[0,1]
	v_pk_add_f32 v[148:149], v[144:145], v[148:149] neg_lo:[0,1] neg_hi:[0,1]
	v_mov_b32_e32 v147, v155
	v_mov_b32_e32 v145, v143
	v_pk_add_f32 v[140:141], v[156:157], v[140:141] neg_lo:[0,1] neg_hi:[0,1]
	v_pk_add_f32 v[146:147], v[146:147], v[152:153] neg_lo:[0,1] neg_hi:[0,1]
	v_pk_add_f32 v[142:143], v[144:145], v[164:165] neg_lo:[0,1] neg_hi:[0,1]
	v_pk_add_f32 v[152:153], v[160:161], v[140:141]
	v_pk_add_f32 v[144:145], v[142:143], v[146:147]
	v_mov_b32_e32 v143, v141
	v_pk_add_f32 v[140:141], v[162:163], v[142:143]
	v_mov_b32_e32 v147, v161
	v_pk_add_f32 v[140:141], v[140:141], v[146:147] neg_lo:[0,1] neg_hi:[0,1]
	v_mov_b32_e32 v142, v144
	v_mov_b32_e32 v143, v153
	v_pk_add_f32 v[142:143], v[142:143], v[140:141] neg_lo:[0,1] neg_hi:[0,1]
	v_pk_add_f32 v[140:141], v[148:149], v[140:141] neg_lo:[0,1] neg_hi:[0,1]
	v_pk_add_f32 v[142:143], v[146:147], v[142:143] neg_lo:[0,1] neg_hi:[0,1]
	s_nop 0
	v_pk_add_f32 v[140:141], v[140:141], v[142:143]
	v_pk_add_f32 v[142:143], v[152:153], v[144:145]
	s_nop 0
	v_pk_add_f32 v[144:145], v[150:151], v[142:143]
	s_nop 0
	v_pk_add_f32 v[146:147], v[144:145], v[150:151] neg_lo:[0,1] neg_hi:[0,1]
	s_nop 0
	v_pk_add_f32 v[142:143], v[142:143], v[146:147] neg_lo:[0,1] neg_hi:[0,1]
	v_add_f32_e32 v147, v65, v133
	v_pk_add_f32 v[140:141], v[140:141], v[142:143]
	v_add_f32_e32 v142, v64, v132
	v_mul_f32_e64 v143, |v142|, s20
	v_pk_add_f32 v[140:141], v[144:145], v[140:141]
	v_fma_f32 v144, |v142|, s20, -v143
	v_rndne_f32_e32 v145, v143
	v_fma_f32 v144, |v142|, s51, v144
	v_sub_f32_e32 v143, v143, v145
	v_add_f32_e32 v143, v143, v144
	v_cndmask_b32_e32 v140, v221, v140, vcc
	v_cmp_neq_f32_e32 vcc, s77, v169
	v_exp_f32_e32 v143, v143
	v_cvt_i32_f32_e32 v144, v145
	v_cndmask_b32_e32 v141, v221, v141, vcc
	v_cmp_lt_f32_e64 vcc, |v169|, s79
	s_nop 1
	v_cndmask_b32_e32 v141, v141, v169, vcc
	v_cmp_lt_f32_e64 vcc, |v168|, s79
	s_nop 1
	v_cndmask_b32_e32 v140, v140, v168, vcc
	v_pk_add_f32 v[138:139], v[138:139], v[140:141] neg_lo:[0,1] neg_hi:[0,1]
	v_ldexp_f32 v141, v143, v144
	v_cmp_ngt_f32_e64 vcc, |v142|, s54
	v_min_f32_e32 v140, 0, v142
	s_nop 0
	v_cndmask_b32_e32 v141, 0, v141, vcc
	v_cmp_nlt_f32_e64 vcc, |v142|, s55
	s_nop 1
	v_cndmask_b32_e32 v185, v221, v141, vcc
	v_add_f32_e32 v144, 1.0, v185
	v_add_f32_e32 v141, -1.0, v144
	v_sub_f32_e32 v142, v141, v144
	v_add_f32_e32 v142, 1.0, v142
	v_sub_f32_e32 v141, v185, v141
	v_add_f32_e32 v145, v141, v142
	v_mul_f32_e64 v141, |v147|, s20
	v_fma_f32 v142, |v147|, s20, -v141
	v_rndne_f32_e32 v143, v141
	v_fma_f32 v142, |v147|, s51, v142
	v_sub_f32_e32 v141, v141, v143
	v_add_f32_e32 v141, v141, v142
	v_exp_f32_e32 v148, v141
	v_cvt_i32_f32_e32 v149, v143
	v_cvt_f64_f32_e32 v[142:143], v144
	v_frexp_exp_i32_f64_e32 v150, v[142:143]
	v_cmp_ngt_f32_e64 vcc, |v147|, s54
	v_ldexp_f32 v142, v148, v149
	v_min_f32_e32 v141, 0, v147
	v_cndmask_b32_e32 v142, 0, v142, vcc
	v_cmp_nlt_f32_e64 vcc, |v147|, s55
	v_frexp_mant_f32_e32 v146, v144
	s_nop 0
	v_cndmask_b32_e32 v186, v221, v142, vcc
	v_add_f32_e32 v147, 1.0, v186
	v_add_f32_e32 v142, -1.0, v147
	v_sub_f32_e32 v143, v142, v147
	v_add_f32_e32 v143, 1.0, v143
; __device__ __forceinline__ void epi_all_run(const void* Pk_, int l, int s, const f32x4 (&acc)[2][2][4][2], const pg8::Unit& u, int wr, int wc, int fr, int fq) {
;     ...
;                         for (int j = 0; j < 4; ++j) ls[j] = fminf(z[j], 0.f) - log1pf(expf(-fabsf(z[j])));
	v_sub_f32_e32 v142, v186, v142
	v_add_f32_e32 v148, v142, v143
	v_frexp_mant_f32_e32 v149, v147
	v_cvt_f64_f32_e32 v[142:143], v147
	v_frexp_exp_i32_f64_e32 v142, v[142:143]
	v_cmp_gt_f32_e32 vcc, s78, v149
	s_nop 1
	v_subbrev_co_u32_e32 v162, vcc, 0, v142, vcc
	v_cmp_gt_f32_e32 vcc, s78, v146
	s_nop 1
	v_subbrev_co_u32_e32 v163, vcc, 0, v150, vcc
	v_sub_u32_e32 v143, 0, v163
	v_ldexp_f32 v142, v144, v143
	v_ldexp_f32 v144, v145, v143
	v_sub_u32_e32 v145, 0, v162
	v_ldexp_f32 v143, v147, v145
	v_pk_add_f32 v[146:147], v[142:143], 1.0 op_sel_hi:[1,0]
	v_ldexp_f32 v145, v148, v145
	v_pk_add_f32 v[148:149], v[146:147], -1.0 op_sel_hi:[1,0]
	v_pk_add_f32 v[154:155], v[142:143], -1.0 op_sel_hi:[1,0]
	v_pk_add_f32 v[148:149], v[142:143], v[148:149] neg_lo:[0,1] neg_hi:[0,1]
	v_pk_add_f32 v[156:157], v[154:155], 1.0 op_sel_hi:[1,0]
	v_pk_add_f32 v[148:149], v[144:145], v[148:149]
	v_pk_add_f32 v[142:143], v[142:143], v[156:157] neg_lo:[0,1] neg_hi:[0,1]
	v_pk_add_f32 v[150:151], v[146:147], v[148:149]
	v_pk_add_f32 v[142:143], v[144:145], v[142:143]
	v_rcp_f32_e32 v152, v150
	v_rcp_f32_e32 v153, v151
	v_pk_add_f32 v[144:145], v[154:155], v[142:143]
	v_pk_add_f32 v[146:147], v[146:147], v[150:151] neg_lo:[0,1] neg_hi:[0,1]
	v_pk_add_f32 v[154:155], v[154:155], v[144:145] neg_lo:[0,1] neg_hi:[0,1]
	v_pk_add_f32 v[146:147], v[148:149], v[146:147]
	v_pk_mul_f32 v[148:149], v[144:145], v[152:153]
	v_pk_add_f32 v[142:143], v[142:143], v[154:155]
	v_pk_mul_f32 v[154:155], v[150:151], v[148:149]
	v_cmp_neq_f32_e32 vcc, s77, v185
	v_pk_fma_f32 v[156:157], v[148:149], v[150:151], v[154:155] neg_lo:[0,0,1] neg_hi:[0,0,1]
	s_nop 0
	v_pk_fma_f32 v[156:157], v[148:149], v[146:147], v[156:157]
	s_nop 0
	v_pk_add_f32 v[158:159], v[154:155], v[156:157]
	s_nop 0
	v_pk_add_f32 v[160:161], v[144:145], v[158:159] neg_lo:[0,1] neg_hi:[0,1]
	v_pk_add_f32 v[154:155], v[158:159], v[154:155] neg_lo:[0,1] neg_hi:[0,1]
	v_pk_add_f32 v[144:145], v[144:145], v[160:161] neg_lo:[0,1] neg_hi:[0,1]
	s_nop 0
	v_pk_add_f32 v[144:145], v[144:145], v[158:159] neg_lo:[0,1] neg_hi:[0,1]
	s_nop 0
	v_pk_add_f32 v[142:143], v[142:143], v[144:145]
	v_pk_add_f32 v[144:145], v[154:155], v[156:157] neg_lo:[0,1] neg_hi:[0,1]
	s_nop 0
	v_pk_add_f32 v[142:143], v[144:145], v[142:143]
	s_nop 0
	v_pk_add_f32 v[144:145], v[160:161], v[142:143]
	s_nop 0
	v_pk_mul_f32 v[154:155], v[152:153], v[144:145]
	s_nop 0
	v_pk_mul_f32 v[156:157], v[150:151], v[154:155]
	s_nop 0
	v_pk_fma_f32 v[150:151], v[154:155], v[150:151], v[156:157] neg_lo:[0,0,1] neg_hi:[0,0,1]
	s_nop 0
	v_pk_fma_f32 v[146:147], v[154:155], v[146:147], v[150:151]
	v_pk_add_f32 v[150:151], v[160:161], v[144:145] neg_lo:[0,1] neg_hi:[0,1]
	s_nop 0
	v_pk_add_f32 v[142:143], v[142:143], v[150:151]
	v_pk_add_f32 v[150:151], v[156:157], v[146:147]
	s_nop 0
	v_pk_add_f32 v[158:159], v[144:145], v[150:151] neg_lo:[0,1] neg_hi:[0,1]
	v_pk_add_f32 v[156:157], v[150:151], v[156:157] neg_lo:[0,1] neg_hi:[0,1]
	v_pk_add_f32 v[144:145], v[144:145], v[158:159] neg_lo:[0,1] neg_hi:[0,1]
	s_nop 0
	v_pk_add_f32 v[144:145], v[144:145], v[150:151] neg_lo:[0,1] neg_hi:[0,1]
	s_nop 0
	v_pk_add_f32 v[142:143], v[142:143], v[144:145]
	v_pk_add_f32 v[144:145], v[156:157], v[146:147] neg_lo:[0,1] neg_hi:[0,1]
	s_nop 0
	v_pk_add_f32 v[142:143], v[144:145], v[142:143]
	v_pk_add_f32 v[144:145], v[148:149], v[154:155]
	v_pk_add_f32 v[142:143], v[158:159], v[142:143]
	v_pk_add_f32 v[146:147], v[144:145], v[148:149] neg_lo:[0,1] neg_hi:[0,1]
	v_pk_mul_f32 v[142:143], v[152:153], v[142:143]
	v_pk_add_f32 v[146:147], v[154:155], v[146:147] neg_lo:[0,1] neg_hi:[0,1]
	v_cvt_f32_i32_e32 v149, v162
	v_pk_add_f32 v[142:143], v[146:147], v[142:143]
	v_cvt_f32_i32_e32 v148, v163
	v_pk_add_f32 v[146:147], v[144:145], v[142:143]
	v_pk_mul_f32 v[154:155], v[148:149], s[84:85] op_sel_hi:[1,0]
	v_pk_mul_f32 v[150:151], v[146:147], v[146:147]
	v_pk_add_f32 v[144:145], v[146:147], v[144:145] neg_lo:[0,1] neg_hi:[0,1]
	v_pk_fma_f32 v[152:153], v[150:151], s[80:81], v[134:135] op_sel_hi:[1,0,0]
	v_pk_add_f32 v[142:143], v[142:143], v[144:145] neg_lo:[0,1] neg_hi:[0,1]
	v_ldexp_f32 v144, v146, 1
	v_pk_fma_f32 v[152:153], v[150:151], v[152:153], s[82:83] op_sel_hi:[1,1,0]
	v_ldexp_f32 v145, v147, 1
	v_pk_mul_f32 v[146:147], v[146:147], v[150:151]
	v_pk_fma_f32 v[156:157], v[148:149], s[84:85], v[154:155] op_sel_hi:[1,0,1] neg_lo:[0,0,1] neg_hi:[0,0,1]
	v_pk_mul_f32 v[146:147], v[146:147], v[152:153]
	v_mov_b32_e32 v159, v145
	v_pk_add_f32 v[150:151], v[144:145], v[146:147]
	v_ldexp_f32 v142, v142, 1
	v_pk_add_f32 v[144:145], v[150:151], v[144:145] neg_lo:[0,1] neg_hi:[0,1]
	v_pk_fma_f32 v[148:149], v[148:149], s[86:87], v[156:157] op_sel_hi:[1,0,1]
	v_ldexp_f32 v143, v143, 1
	v_pk_add_f32 v[144:145], v[146:147], v[144:145] neg_lo:[0,1] neg_hi:[0,1]
	v_mov_b32_e32 v152, v154
	v_mov_b32_e32 v153, v147
	v_mov_b32_e32 v158, v148
	v_pk_add_f32 v[146:147], v[142:143], v[144:145]
	v_mov_b32_e32 v144, v154
	v_mov_b32_e32 v142, v148
	v_pk_add_f32 v[152:153], v[152:153], v[158:159]
	v_pk_add_f32 v[158:159], v[144:145], v[142:143]
	v_mov_b32_e32 v142, v150
	v_mov_b32_e32 v144, v146
	v_pk_add_f32 v[156:157], v[154:155], v[148:149]
	v_pk_add_f32 v[142:143], v[142:143], v[144:145]
	v_pk_add_f32 v[144:145], v[150:151], v[146:147]
	v_mov_b32_e32 v160, v156
	v_mov_b32_e32 v161, v155
	v_mov_b32_e32 v162, v144
	v_mov_b32_e32 v163, v149
	v_pk_add_f32 v[142:143], v[152:153], v[142:143]
	v_pk_add_f32 v[152:153], v[156:157], v[144:145]
	v_pk_add_f32 v[164:165], v[160:161], v[162:163]
	v_mov_b32_e32 v166, v144
	v_mov_b32_e32 v167, v153
	v_mov_b32_e32 v168, v150
	v_mov_b32_e32 v169, v157
; __device__ __forceinline__ void epi_all_run(const void* Pk_, int l, int s, const f32x4 (&acc)[2][2][4][2], const pg8::Unit& u, int wr, int wc, int fr, int fq) {
;     ...
;                         const f32x4 z = acc[ai][0][m][0] + fbv;
;                         f32x4 ls;
; #pragma unroll
;                         for (int j = 0; j < 4; ++j) ls[j] = fminf(z[j], 0.f) - log1pf(expf(-fabsf(z[j])));
;                         *(f32x4*)(logf + (size_t)row * 4) = ls;
	v_pk_add_f32 v[160:161], v[164:165], v[160:161] neg_lo:[0,1] neg_hi:[0,1]
	v_pk_add_f32 v[166:167], v[166:167], v[168:169] neg_lo:[0,1] neg_hi:[0,1]
	v_pk_add_f32 v[164:165], v[156:157], v[154:155] neg_lo:[0,1] neg_hi:[0,1]
	v_pk_add_f32 v[162:163], v[162:163], v[160:161] neg_lo:[0,1] neg_hi:[0,1]
	v_mov_b32_e32 v168, v156
	v_mov_b32_e32 v169, v153
	v_mov_b32_e32 v155, v167
	v_mov_b32_e32 v161, v151
	v_pk_add_f32 v[150:151], v[144:145], v[150:151] neg_lo:[0,1] neg_hi:[0,1]
	v_pk_add_f32 v[154:155], v[168:169], v[154:155] neg_lo:[0,1] neg_hi:[0,1]
	v_pk_add_f32 v[164:165], v[148:149], v[164:165] neg_lo:[0,1] neg_hi:[0,1]
	v_pk_add_f32 v[142:143], v[142:143], v[160:161] neg_lo:[0,1] neg_hi:[0,1]
	v_pk_add_f32 v[150:151], v[146:147], v[150:151] neg_lo:[0,1] neg_hi:[0,1]
	v_mov_b32_e32 v149, v157
	v_mov_b32_e32 v147, v145
	v_pk_add_f32 v[142:143], v[158:159], v[142:143] neg_lo:[0,1] neg_hi:[0,1]
	v_pk_add_f32 v[148:149], v[148:149], v[154:155] neg_lo:[0,1] neg_hi:[0,1]
	v_pk_add_f32 v[144:145], v[146:147], v[166:167] neg_lo:[0,1] neg_hi:[0,1]
	v_pk_add_f32 v[154:155], v[162:163], v[142:143]
	v_pk_add_f32 v[146:147], v[144:145], v[148:149]
	v_mov_b32_e32 v145, v143
	v_pk_add_f32 v[142:143], v[164:165], v[144:145]
	v_mov_b32_e32 v149, v163
	v_pk_add_f32 v[142:143], v[142:143], v[148:149] neg_lo:[0,1] neg_hi:[0,1]
	v_mov_b32_e32 v144, v146
	v_mov_b32_e32 v145, v155
	v_pk_add_f32 v[144:145], v[144:145], v[142:143] neg_lo:[0,1] neg_hi:[0,1]
	v_pk_add_f32 v[142:143], v[150:151], v[142:143] neg_lo:[0,1] neg_hi:[0,1]
	v_pk_add_f32 v[144:145], v[148:149], v[144:145] neg_lo:[0,1] neg_hi:[0,1]
	s_nop 0
	v_pk_add_f32 v[142:143], v[142:143], v[144:145]
	v_pk_add_f32 v[144:145], v[154:155], v[146:147]
	s_nop 0
	v_pk_add_f32 v[146:147], v[152:153], v[144:145]
	s_nop 0
	v_pk_add_f32 v[148:149], v[146:147], v[152:153] neg_lo:[0,1] neg_hi:[0,1]
	s_nop 0
	v_pk_add_f32 v[144:145], v[144:145], v[148:149] neg_lo:[0,1] neg_hi:[0,1]
	s_nop 0
	v_pk_add_f32 v[142:143], v[142:143], v[144:145]
	v_add_f32_e32 v144, v46, v130
	v_mul_f32_e64 v145, |v144|, s20
	v_pk_add_f32 v[142:143], v[146:147], v[142:143]
	v_fma_f32 v146, |v144|, s20, -v145
	v_rndne_f32_e32 v147, v145
	v_fma_f32 v146, |v144|, s51, v146
	v_sub_f32_e32 v145, v145, v147
	v_cndmask_b32_e32 v142, v221, v142, vcc
	v_cmp_neq_f32_e32 vcc, s77, v186
	v_add_f32_e32 v145, v145, v146
	v_exp_f32_e32 v145, v145
	v_cndmask_b32_e32 v143, v221, v143, vcc
	v_cmp_lt_f32_e64 vcc, |v186|, s79
	v_cvt_i32_f32_e32 v146, v147
	s_nop 0
	v_cndmask_b32_e32 v143, v143, v186, vcc
	v_cmp_lt_f32_e64 vcc, |v185|, s79
	s_nop 1
	v_cndmask_b32_e32 v142, v142, v185, vcc
	v_pk_add_f32 v[140:141], v[140:141], v[142:143] neg_lo:[0,1] neg_hi:[0,1]
	global_store_dwordx4 v[136:137], v[138:141], off offset:2048
	v_cmp_ngt_f32_e64 vcc, |v144|, s54
	s_nop 0
	v_ldexp_f32 v139, v145, v146
	v_cndmask_b32_e32 v139, 0, v139, vcc
	v_cmp_nlt_f32_e64 vcc, |v144|, s55
	v_add_f32_e32 v145, v47, v131
	v_min_f32_e32 v138, 0, v144
	v_cndmask_b32_e32 v168, v221, v139, vcc
	v_add_f32_e32 v142, 1.0, v168
	v_add_f32_e32 v139, -1.0, v142
	v_sub_f32_e32 v140, v139, v142
	v_add_f32_e32 v140, 1.0, v140
	v_sub_f32_e32 v139, v168, v139
	v_add_f32_e32 v143, v139, v140
	v_mul_f32_e64 v139, |v145|, s20
	v_fma_f32 v140, |v145|, s20, -v139
	v_rndne_f32_e32 v141, v139
	v_fma_f32 v140, |v145|, s51, v140
	v_sub_f32_e32 v139, v139, v141
	v_add_f32_e32 v139, v139, v140
	v_exp_f32_e32 v146, v139
	v_cvt_i32_f32_e32 v147, v141
	v_cvt_f64_f32_e32 v[140:141], v142
	v_frexp_exp_i32_f64_e32 v148, v[140:141]
	v_cmp_ngt_f32_e64 vcc, |v145|, s54
	v_ldexp_f32 v140, v146, v147
	v_min_f32_e32 v139, 0, v145
	v_cndmask_b32_e32 v140, 0, v140, vcc
	v_cmp_nlt_f32_e64 vcc, |v145|, s55
	v_frexp_mant_f32_e32 v144, v142
	s_nop 0
	v_cndmask_b32_e32 v169, v221, v140, vcc
	v_add_f32_e32 v145, 1.0, v169
	v_add_f32_e32 v140, -1.0, v145
	v_sub_f32_e32 v141, v140, v145
	v_add_f32_e32 v141, 1.0, v141
	v_sub_f32_e32 v140, v169, v140
	v_add_f32_e32 v146, v140, v141
	v_frexp_mant_f32_e32 v147, v145
	v_cvt_f64_f32_e32 v[140:141], v145
	v_frexp_exp_i32_f64_e32 v140, v[140:141]
	v_cmp_gt_f32_e32 vcc, s78, v147
	s_nop 1
	v_subbrev_co_u32_e32 v160, vcc, 0, v140, vcc
	v_cmp_gt_f32_e32 vcc, s78, v144
	s_nop 1
	v_subbrev_co_u32_e32 v161, vcc, 0, v148, vcc
	v_sub_u32_e32 v141, 0, v161
	v_ldexp_f32 v140, v142, v141
	v_ldexp_f32 v142, v143, v141
	v_sub_u32_e32 v143, 0, v160
	v_ldexp_f32 v141, v145, v143
	v_pk_add_f32 v[144:145], v[140:141], 1.0 op_sel_hi:[1,0]
	v_ldexp_f32 v143, v146, v143
	v_pk_add_f32 v[146:147], v[144:145], -1.0 op_sel_hi:[1,0]
	v_pk_add_f32 v[152:153], v[140:141], -1.0 op_sel_hi:[1,0]
	v_pk_add_f32 v[146:147], v[140:141], v[146:147] neg_lo:[0,1] neg_hi:[0,1]
	v_pk_add_f32 v[154:155], v[152:153], 1.0 op_sel_hi:[1,0]
	v_pk_add_f32 v[146:147], v[142:143], v[146:147]
	v_pk_add_f32 v[140:141], v[140:141], v[154:155] neg_lo:[0,1] neg_hi:[0,1]
	v_pk_add_f32 v[148:149], v[144:145], v[146:147]
	v_pk_add_f32 v[140:141], v[142:143], v[140:141]
	v_rcp_f32_e32 v150, v148
	v_rcp_f32_e32 v151, v149
	v_pk_add_f32 v[142:143], v[152:153], v[140:141]
	v_pk_add_f32 v[144:145], v[144:145], v[148:149] neg_lo:[0,1] neg_hi:[0,1]
	v_pk_add_f32 v[152:153], v[152:153], v[142:143] neg_lo:[0,1] neg_hi:[0,1]
	v_pk_add_f32 v[144:145], v[146:147], v[144:145]
	v_pk_mul_f32 v[146:147], v[142:143], v[150:151]
	v_pk_add_f32 v[140:141], v[140:141], v[152:153]
	v_pk_mul_f32 v[152:153], v[148:149], v[146:147]
	v_cmp_neq_f32_e32 vcc, s77, v168
	v_pk_fma_f32 v[154:155], v[146:147], v[148:149], v[152:153] neg_lo:[0,0,1] neg_hi:[0,0,1]
	s_nop 0
	v_pk_fma_f32 v[154:155], v[146:147], v[144:145], v[154:155]
	s_nop 0
	v_pk_add_f32 v[156:157], v[152:153], v[154:155]
; __device__ __forceinline__ void epi_all_run(const void* Pk_, int l, int s, const f32x4 (&acc)[2][2][4][2], const pg8::Unit& u, int wr, int wc, int fr, int fq) {
;     ...
;                         for (int j = 0; j < 4; ++j) ls[j] = fminf(z[j], 0.f) - log1pf(expf(-fabsf(z[j])));
	s_nop 0
	v_pk_add_f32 v[158:159], v[142:143], v[156:157] neg_lo:[0,1] neg_hi:[0,1]
	v_pk_add_f32 v[152:153], v[156:157], v[152:153] neg_lo:[0,1] neg_hi:[0,1]
	v_pk_add_f32 v[142:143], v[142:143], v[158:159] neg_lo:[0,1] neg_hi:[0,1]
	s_nop 0
	v_pk_add_f32 v[142:143], v[142:143], v[156:157] neg_lo:[0,1] neg_hi:[0,1]
	s_nop 0
	v_pk_add_f32 v[140:141], v[140:141], v[142:143]
	v_pk_add_f32 v[142:143], v[152:153], v[154:155] neg_lo:[0,1] neg_hi:[0,1]
	s_nop 0
	v_pk_add_f32 v[140:141], v[142:143], v[140:141]
	s_nop 0
	v_pk_add_f32 v[142:143], v[158:159], v[140:141]
	s_nop 0
	v_pk_mul_f32 v[152:153], v[150:151], v[142:143]
	s_nop 0
	v_pk_mul_f32 v[154:155], v[148:149], v[152:153]
	s_nop 0
	v_pk_fma_f32 v[148:149], v[152:153], v[148:149], v[154:155] neg_lo:[0,0,1] neg_hi:[0,0,1]
	s_nop 0
	v_pk_fma_f32 v[144:145], v[152:153], v[144:145], v[148:149]
	v_pk_add_f32 v[148:149], v[158:159], v[142:143] neg_lo:[0,1] neg_hi:[0,1]
	s_nop 0
	v_pk_add_f32 v[140:141], v[140:141], v[148:149]
	v_pk_add_f32 v[148:149], v[154:155], v[144:145]
	s_nop 0
	v_pk_add_f32 v[156:157], v[142:143], v[148:149] neg_lo:[0,1] neg_hi:[0,1]
	v_pk_add_f32 v[154:155], v[148:149], v[154:155] neg_lo:[0,1] neg_hi:[0,1]
	v_pk_add_f32 v[142:143], v[142:143], v[156:157] neg_lo:[0,1] neg_hi:[0,1]
	s_nop 0
	v_pk_add_f32 v[142:143], v[142:143], v[148:149] neg_lo:[0,1] neg_hi:[0,1]
	s_nop 0
	v_pk_add_f32 v[140:141], v[140:141], v[142:143]
	v_pk_add_f32 v[142:143], v[154:155], v[144:145] neg_lo:[0,1] neg_hi:[0,1]
	s_nop 0
	v_pk_add_f32 v[140:141], v[142:143], v[140:141]
	v_pk_add_f32 v[142:143], v[146:147], v[152:153]
	v_pk_add_f32 v[140:141], v[156:157], v[140:141]
	v_pk_add_f32 v[144:145], v[142:143], v[146:147] neg_lo:[0,1] neg_hi:[0,1]
	v_pk_mul_f32 v[140:141], v[150:151], v[140:141]
	v_pk_add_f32 v[144:145], v[152:153], v[144:145] neg_lo:[0,1] neg_hi:[0,1]
	v_cvt_f32_i32_e32 v147, v160
	v_pk_add_f32 v[140:141], v[144:145], v[140:141]
	v_cvt_f32_i32_e32 v146, v161
	v_pk_add_f32 v[144:145], v[142:143], v[140:141]
	v_pk_mul_f32 v[152:153], v[146:147], s[84:85] op_sel_hi:[1,0]
	v_pk_mul_f32 v[148:149], v[144:145], v[144:145]
	v_pk_add_f32 v[142:143], v[144:145], v[142:143] neg_lo:[0,1] neg_hi:[0,1]
	v_pk_fma_f32 v[150:151], v[148:149], s[80:81], v[134:135] op_sel_hi:[1,0,0]
	v_pk_add_f32 v[140:141], v[140:141], v[142:143] neg_lo:[0,1] neg_hi:[0,1]
	v_ldexp_f32 v142, v144, 1
	v_pk_fma_f32 v[150:151], v[148:149], v[150:151], s[82:83] op_sel_hi:[1,1,0]
	v_ldexp_f32 v143, v145, 1
	v_pk_mul_f32 v[144:145], v[144:145], v[148:149]
	v_pk_fma_f32 v[154:155], v[146:147], s[84:85], v[152:153] op_sel_hi:[1,0,1] neg_lo:[0,0,1] neg_hi:[0,0,1]
	v_pk_mul_f32 v[144:145], v[144:145], v[150:151]
	v_mov_b32_e32 v157, v143
	v_pk_add_f32 v[148:149], v[142:143], v[144:145]
	v_ldexp_f32 v140, v140, 1
	v_pk_add_f32 v[142:143], v[148:149], v[142:143] neg_lo:[0,1] neg_hi:[0,1]
	v_pk_fma_f32 v[146:147], v[146:147], s[86:87], v[154:155] op_sel_hi:[1,0,1]
	v_ldexp_f32 v141, v141, 1
	v_pk_add_f32 v[142:143], v[144:145], v[142:143] neg_lo:[0,1] neg_hi:[0,1]
	v_mov_b32_e32 v150, v152
	v_mov_b32_e32 v151, v145
	v_mov_b32_e32 v156, v146
	v_pk_add_f32 v[144:145], v[140:141], v[142:143]
	v_mov_b32_e32 v142, v152
	v_mov_b32_e32 v140, v146
	v_pk_add_f32 v[150:151], v[150:151], v[156:157]
	v_pk_add_f32 v[156:157], v[142:143], v[140:141]
	v_mov_b32_e32 v140, v148
	v_mov_b32_e32 v142, v144
	v_pk_add_f32 v[154:155], v[152:153], v[146:147]
	v_pk_add_f32 v[140:141], v[140:141], v[142:143]
	v_pk_add_f32 v[142:143], v[148:149], v[144:145]
	v_mov_b32_e32 v158, v154
	v_mov_b32_e32 v159, v153
	v_mov_b32_e32 v160, v142
	v_mov_b32_e32 v161, v147
	v_pk_add_f32 v[140:141], v[150:151], v[140:141]
	v_pk_add_f32 v[150:151], v[154:155], v[142:143]
	v_pk_add_f32 v[162:163], v[158:159], v[160:161]
	v_mov_b32_e32 v164, v142
	v_mov_b32_e32 v165, v151
	v_mov_b32_e32 v166, v148
	v_mov_b32_e32 v167, v155
	v_pk_add_f32 v[158:159], v[162:163], v[158:159] neg_lo:[0,1] neg_hi:[0,1]
	v_pk_add_f32 v[164:165], v[164:165], v[166:167] neg_lo:[0,1] neg_hi:[0,1]
	v_pk_add_f32 v[162:163], v[154:155], v[152:153] neg_lo:[0,1] neg_hi:[0,1]
	v_pk_add_f32 v[160:161], v[160:161], v[158:159] neg_lo:[0,1] neg_hi:[0,1]
	v_mov_b32_e32 v166, v154
	v_mov_b32_e32 v167, v151
	v_mov_b32_e32 v153, v165
	v_mov_b32_e32 v159, v149
	v_pk_add_f32 v[148:149], v[142:143], v[148:149] neg_lo:[0,1] neg_hi:[0,1]
	v_pk_add_f32 v[152:153], v[166:167], v[152:153] neg_lo:[0,1] neg_hi:[0,1]
	v_pk_add_f32 v[162:163], v[146:147], v[162:163] neg_lo:[0,1] neg_hi:[0,1]
	v_pk_add_f32 v[140:141], v[140:141], v[158:159] neg_lo:[0,1] neg_hi:[0,1]
	v_pk_add_f32 v[148:149], v[144:145], v[148:149] neg_lo:[0,1] neg_hi:[0,1]
	v_mov_b32_e32 v147, v155
	v_mov_b32_e32 v145, v143
	v_pk_add_f32 v[140:141], v[156:157], v[140:141] neg_lo:[0,1] neg_hi:[0,1]
	v_pk_add_f32 v[146:147], v[146:147], v[152:153] neg_lo:[0,1] neg_hi:[0,1]
	v_pk_add_f32 v[142:143], v[144:145], v[164:165] neg_lo:[0,1] neg_hi:[0,1]
	v_pk_add_f32 v[152:153], v[160:161], v[140:141]
	v_pk_add_f32 v[144:145], v[142:143], v[146:147]
	v_mov_b32_e32 v143, v141
	v_pk_add_f32 v[140:141], v[162:163], v[142:143]
	v_mov_b32_e32 v147, v161
	v_pk_add_f32 v[140:141], v[140:141], v[146:147] neg_lo:[0,1] neg_hi:[0,1]
	v_mov_b32_e32 v142, v144
	v_mov_b32_e32 v143, v153
	v_pk_add_f32 v[142:143], v[142:143], v[140:141] neg_lo:[0,1] neg_hi:[0,1]
	v_pk_add_f32 v[140:141], v[148:149], v[140:141] neg_lo:[0,1] neg_hi:[0,1]
	v_pk_add_f32 v[142:143], v[146:147], v[142:143] neg_lo:[0,1] neg_hi:[0,1]
	s_nop 0
	v_pk_add_f32 v[140:141], v[140:141], v[142:143]
	v_pk_add_f32 v[142:143], v[152:153], v[144:145]
	s_nop 0
	v_pk_add_f32 v[144:145], v[150:151], v[142:143]
	s_nop 0
; __device__ __forceinline__ void epi_all_run(const void* Pk_, int l, int s, const f32x4 (&acc)[2][2][4][2], const pg8::Unit& u, int wr, int wc, int fr, int fq) {
;     ...
;                         const f32x4 z = acc[ai][0][m][0] + fbv;
;                         f32x4 ls;
; #pragma unroll
;                         for (int j = 0; j < 4; ++j) ls[j] = fminf(z[j], 0.f) - log1pf(expf(-fabsf(z[j])));
;                         *(f32x4*)(logf + (size_t)row * 4) = ls;
	v_pk_add_f32 v[146:147], v[144:145], v[150:151] neg_lo:[0,1] neg_hi:[0,1]
	s_nop 0
	v_pk_add_f32 v[142:143], v[142:143], v[146:147] neg_lo:[0,1] neg_hi:[0,1]
	v_add_f32_e32 v147, v49, v133
	v_pk_add_f32 v[140:141], v[140:141], v[142:143]
	v_add_f32_e32 v142, v48, v132
	v_mul_f32_e64 v143, |v142|, s20
	v_pk_add_f32 v[140:141], v[144:145], v[140:141]
	v_fma_f32 v144, |v142|, s20, -v143
	v_rndne_f32_e32 v145, v143
	v_fma_f32 v144, |v142|, s51, v144
	v_sub_f32_e32 v143, v143, v145
	v_add_f32_e32 v143, v143, v144
	v_cndmask_b32_e32 v140, v221, v140, vcc
	v_cmp_neq_f32_e32 vcc, s77, v169
	v_exp_f32_e32 v143, v143
	v_cvt_i32_f32_e32 v144, v145
	v_cndmask_b32_e32 v141, v221, v141, vcc
	v_cmp_lt_f32_e64 vcc, |v169|, s79
	s_nop 1
	v_cndmask_b32_e32 v141, v141, v169, vcc
	v_cmp_lt_f32_e64 vcc, |v168|, s79
	s_nop 1
	v_cndmask_b32_e32 v140, v140, v168, vcc
	v_pk_add_f32 v[138:139], v[138:139], v[140:141] neg_lo:[0,1] neg_hi:[0,1]
	v_ldexp_f32 v141, v143, v144
	v_cmp_ngt_f32_e64 vcc, |v142|, s54
	v_min_f32_e32 v140, 0, v142
	s_nop 0
	v_cndmask_b32_e32 v141, 0, v141, vcc
	v_cmp_nlt_f32_e64 vcc, |v142|, s55
	s_nop 1
	v_cndmask_b32_e32 v185, v221, v141, vcc
	v_add_f32_e32 v144, 1.0, v185
	v_add_f32_e32 v141, -1.0, v144
	v_sub_f32_e32 v142, v141, v144
	v_add_f32_e32 v142, 1.0, v142
	v_sub_f32_e32 v141, v185, v141
	v_add_f32_e32 v145, v141, v142
	v_mul_f32_e64 v141, |v147|, s20
	v_fma_f32 v142, |v147|, s20, -v141
	v_rndne_f32_e32 v143, v141
	v_fma_f32 v142, |v147|, s51, v142
	v_sub_f32_e32 v141, v141, v143
	v_add_f32_e32 v141, v141, v142
	v_exp_f32_e32 v148, v141
	v_cvt_i32_f32_e32 v149, v143
	v_cvt_f64_f32_e32 v[142:143], v144
	v_frexp_exp_i32_f64_e32 v150, v[142:143]
	v_cmp_ngt_f32_e64 vcc, |v147|, s54
	v_ldexp_f32 v142, v148, v149
	v_min_f32_e32 v141, 0, v147
	v_cndmask_b32_e32 v142, 0, v142, vcc
	v_cmp_nlt_f32_e64 vcc, |v147|, s55
	v_frexp_mant_f32_e32 v146, v144
	s_nop 0
	v_cndmask_b32_e32 v186, v221, v142, vcc
	v_add_f32_e32 v147, 1.0, v186
	v_add_f32_e32 v142, -1.0, v147
	v_sub_f32_e32 v143, v142, v147
	v_add_f32_e32 v143, 1.0, v143
	v_sub_f32_e32 v142, v186, v142
	v_add_f32_e32 v148, v142, v143
	v_frexp_mant_f32_e32 v149, v147
	v_cvt_f64_f32_e32 v[142:143], v147
	v_frexp_exp_i32_f64_e32 v142, v[142:143]
	v_cmp_gt_f32_e32 vcc, s78, v149
	s_nop 1
	v_subbrev_co_u32_e32 v162, vcc, 0, v142, vcc
	v_cmp_gt_f32_e32 vcc, s78, v146
	s_nop 1
	v_subbrev_co_u32_e32 v163, vcc, 0, v150, vcc
	v_sub_u32_e32 v143, 0, v163
	v_ldexp_f32 v142, v144, v143
	v_ldexp_f32 v144, v145, v143
	v_sub_u32_e32 v145, 0, v162
	v_ldexp_f32 v143, v147, v145
	v_pk_add_f32 v[146:147], v[142:143], 1.0 op_sel_hi:[1,0]
	v_ldexp_f32 v145, v148, v145
	v_pk_add_f32 v[148:149], v[146:147], -1.0 op_sel_hi:[1,0]
	v_pk_add_f32 v[154:155], v[142:143], -1.0 op_sel_hi:[1,0]
	v_pk_add_f32 v[148:149], v[142:143], v[148:149] neg_lo:[0,1] neg_hi:[0,1]
	v_pk_add_f32 v[156:157], v[154:155], 1.0 op_sel_hi:[1,0]
	v_pk_add_f32 v[148:149], v[144:145], v[148:149]
	v_pk_add_f32 v[142:143], v[142:143], v[156:157] neg_lo:[0,1] neg_hi:[0,1]
	v_pk_add_f32 v[150:151], v[146:147], v[148:149]
	v_pk_add_f32 v[142:143], v[144:145], v[142:143]
	v_rcp_f32_e32 v152, v150
	v_rcp_f32_e32 v153, v151
	v_pk_add_f32 v[144:145], v[154:155], v[142:143]
	v_pk_add_f32 v[146:147], v[146:147], v[150:151] neg_lo:[0,1] neg_hi:[0,1]
	v_pk_add_f32 v[154:155], v[154:155], v[144:145] neg_lo:[0,1] neg_hi:[0,1]
	v_pk_add_f32 v[146:147], v[148:149], v[146:147]
	v_pk_mul_f32 v[148:149], v[144:145], v[152:153]
	v_pk_add_f32 v[142:143], v[142:143], v[154:155]
	v_pk_mul_f32 v[154:155], v[150:151], v[148:149]
	v_cmp_neq_f32_e32 vcc, s77, v185
	v_pk_fma_f32 v[156:157], v[148:149], v[150:151], v[154:155] neg_lo:[0,0,1] neg_hi:[0,0,1]
	s_nop 0
	v_pk_fma_f32 v[156:157], v[148:149], v[146:147], v[156:157]
	s_nop 0
	v_pk_add_f32 v[158:159], v[154:155], v[156:157]
	s_nop 0
	v_pk_add_f32 v[160:161], v[144:145], v[158:159] neg_lo:[0,1] neg_hi:[0,1]
	v_pk_add_f32 v[154:155], v[158:159], v[154:155] neg_lo:[0,1] neg_hi:[0,1]
	v_pk_add_f32 v[144:145], v[144:145], v[160:161] neg_lo:[0,1] neg_hi:[0,1]
	s_nop 0
	v_pk_add_f32 v[144:145], v[144:145], v[158:159] neg_lo:[0,1] neg_hi:[0,1]
	s_nop 0
	v_pk_add_f32 v[142:143], v[142:143], v[144:145]
	v_pk_add_f32 v[144:145], v[154:155], v[156:157] neg_lo:[0,1] neg_hi:[0,1]
	s_nop 0
	v_pk_add_f32 v[142:143], v[144:145], v[142:143]
	s_nop 0
	v_pk_add_f32 v[144:145], v[160:161], v[142:143]
	s_nop 0
	v_pk_mul_f32 v[154:155], v[152:153], v[144:145]
	s_nop 0
	v_pk_mul_f32 v[156:157], v[150:151], v[154:155]
	s_nop 0
	v_pk_fma_f32 v[150:151], v[154:155], v[150:151], v[156:157] neg_lo:[0,0,1] neg_hi:[0,0,1]
	s_nop 0
	v_pk_fma_f32 v[146:147], v[154:155], v[146:147], v[150:151]
	v_pk_add_f32 v[150:151], v[160:161], v[144:145] neg_lo:[0,1] neg_hi:[0,1]
	s_nop 0
	v_pk_add_f32 v[142:143], v[142:143], v[150:151]
	v_pk_add_f32 v[150:151], v[156:157], v[146:147]
	s_nop 0
	v_pk_add_f32 v[158:159], v[144:145], v[150:151] neg_lo:[0,1] neg_hi:[0,1]
	v_pk_add_f32 v[156:157], v[150:151], v[156:157] neg_lo:[0,1] neg_hi:[0,1]
	v_pk_add_f32 v[144:145], v[144:145], v[158:159] neg_lo:[0,1] neg_hi:[0,1]
	s_nop 0
	v_pk_add_f32 v[144:145], v[144:145], v[150:151] neg_lo:[0,1] neg_hi:[0,1]
	s_nop 0
	v_pk_add_f32 v[142:143], v[142:143], v[144:145]
	v_pk_add_f32 v[144:145], v[156:157], v[146:147] neg_lo:[0,1] neg_hi:[0,1]
	s_nop 0
	v_pk_add_f32 v[142:143], v[144:145], v[142:143]
	v_pk_add_f32 v[144:145], v[148:149], v[154:155]
	v_pk_add_f32 v[142:143], v[158:159], v[142:143]
	v_pk_add_f32 v[146:147], v[144:145], v[148:149] neg_lo:[0,1] neg_hi:[0,1]
	v_pk_mul_f32 v[142:143], v[152:153], v[142:143]
	v_pk_add_f32 v[146:147], v[154:155], v[146:147] neg_lo:[0,1] neg_hi:[0,1]
; __device__ __forceinline__ void epi_all_run(const void* Pk_, int l, int s, const f32x4 (&acc)[2][2][4][2], const pg8::Unit& u, int wr, int wc, int fr, int fq) {
;     ...
;                         const f32x4 z = acc[ai][0][m][0] + fbv;
;                         f32x4 ls;
; #pragma unroll
;                         for (int j = 0; j < 4; ++j) ls[j] = fminf(z[j], 0.f) - log1pf(expf(-fabsf(z[j])));
;                         *(f32x4*)(logf + (size_t)row * 4) = ls;
	v_cvt_f32_i32_e32 v149, v162
	v_pk_add_f32 v[142:143], v[146:147], v[142:143]
	v_cvt_f32_i32_e32 v148, v163
	v_pk_add_f32 v[146:147], v[144:145], v[142:143]
	v_pk_mul_f32 v[154:155], v[148:149], s[84:85] op_sel_hi:[1,0]
	v_pk_mul_f32 v[150:151], v[146:147], v[146:147]
	v_pk_add_f32 v[144:145], v[146:147], v[144:145] neg_lo:[0,1] neg_hi:[0,1]
	v_pk_fma_f32 v[152:153], v[150:151], s[80:81], v[134:135] op_sel_hi:[1,0,0]
	v_pk_add_f32 v[142:143], v[142:143], v[144:145] neg_lo:[0,1] neg_hi:[0,1]
	v_ldexp_f32 v144, v146, 1
	v_pk_fma_f32 v[152:153], v[150:151], v[152:153], s[82:83] op_sel_hi:[1,1,0]
	v_ldexp_f32 v145, v147, 1
	v_pk_mul_f32 v[146:147], v[146:147], v[150:151]
	v_pk_fma_f32 v[156:157], v[148:149], s[84:85], v[154:155] op_sel_hi:[1,0,1] neg_lo:[0,0,1] neg_hi:[0,0,1]
	v_pk_mul_f32 v[146:147], v[146:147], v[152:153]
	v_mov_b32_e32 v159, v145
	v_pk_add_f32 v[150:151], v[144:145], v[146:147]
	v_ldexp_f32 v142, v142, 1
	v_pk_add_f32 v[144:145], v[150:151], v[144:145] neg_lo:[0,1] neg_hi:[0,1]
	v_pk_fma_f32 v[148:149], v[148:149], s[86:87], v[156:157] op_sel_hi:[1,0,1]
	v_ldexp_f32 v143, v143, 1
	v_pk_add_f32 v[144:145], v[146:147], v[144:145] neg_lo:[0,1] neg_hi:[0,1]
	v_mov_b32_e32 v152, v154
	v_mov_b32_e32 v153, v147
	v_mov_b32_e32 v158, v148
	v_pk_add_f32 v[146:147], v[142:143], v[144:145]
	v_mov_b32_e32 v144, v154
	v_mov_b32_e32 v142, v148
	v_pk_add_f32 v[152:153], v[152:153], v[158:159]
	v_pk_add_f32 v[158:159], v[144:145], v[142:143]
	v_mov_b32_e32 v142, v150
	v_mov_b32_e32 v144, v146
	v_pk_add_f32 v[156:157], v[154:155], v[148:149]
	v_pk_add_f32 v[142:143], v[142:143], v[144:145]
	v_pk_add_f32 v[144:145], v[150:151], v[146:147]
	v_mov_b32_e32 v160, v156
	v_mov_b32_e32 v161, v155
	v_mov_b32_e32 v162, v144
	v_mov_b32_e32 v163, v149
	v_pk_add_f32 v[142:143], v[152:153], v[142:143]
	v_pk_add_f32 v[152:153], v[156:157], v[144:145]
	v_pk_add_f32 v[164:165], v[160:161], v[162:163]
	v_mov_b32_e32 v166, v144
	v_mov_b32_e32 v167, v153
	v_mov_b32_e32 v168, v150
	v_mov_b32_e32 v169, v157
	v_pk_add_f32 v[160:161], v[164:165], v[160:161] neg_lo:[0,1] neg_hi:[0,1]
	v_pk_add_f32 v[166:167], v[166:167], v[168:169] neg_lo:[0,1] neg_hi:[0,1]
	v_pk_add_f32 v[164:165], v[156:157], v[154:155] neg_lo:[0,1] neg_hi:[0,1]
	v_pk_add_f32 v[162:163], v[162:163], v[160:161] neg_lo:[0,1] neg_hi:[0,1]
	v_mov_b32_e32 v168, v156
	v_mov_b32_e32 v169, v153
	v_mov_b32_e32 v155, v167
	v_mov_b32_e32 v161, v151
	v_pk_add_f32 v[150:151], v[144:145], v[150:151] neg_lo:[0,1] neg_hi:[0,1]
	v_pk_add_f32 v[154:155], v[168:169], v[154:155] neg_lo:[0,1] neg_hi:[0,1]
	v_pk_add_f32 v[164:165], v[148:149], v[164:165] neg_lo:[0,1] neg_hi:[0,1]
	v_pk_add_f32 v[142:143], v[142:143], v[160:161] neg_lo:[0,1] neg_hi:[0,1]
	v_pk_add_f32 v[150:151], v[146:147], v[150:151] neg_lo:[0,1] neg_hi:[0,1]
	v_mov_b32_e32 v149, v157
	v_mov_b32_e32 v147, v145
	v_pk_add_f32 v[142:143], v[158:159], v[142:143] neg_lo:[0,1] neg_hi:[0,1]
	v_pk_add_f32 v[148:149], v[148:149], v[154:155] neg_lo:[0,1] neg_hi:[0,1]
	v_pk_add_f32 v[144:145], v[146:147], v[166:167] neg_lo:[0,1] neg_hi:[0,1]
	v_pk_add_f32 v[154:155], v[162:163], v[142:143]
	v_pk_add_f32 v[146:147], v[144:145], v[148:149]
	v_mov_b32_e32 v145, v143
	v_pk_add_f32 v[142:143], v[164:165], v[144:145]
	v_mov_b32_e32 v149, v163
	v_pk_add_f32 v[142:143], v[142:143], v[148:149] neg_lo:[0,1] neg_hi:[0,1]
	v_mov_b32_e32 v144, v146
	v_mov_b32_e32 v145, v155
	v_pk_add_f32 v[144:145], v[144:145], v[142:143] neg_lo:[0,1] neg_hi:[0,1]
	v_pk_add_f32 v[142:143], v[150:151], v[142:143] neg_lo:[0,1] neg_hi:[0,1]
	v_pk_add_f32 v[144:145], v[148:149], v[144:145] neg_lo:[0,1] neg_hi:[0,1]
	s_nop 0
	v_pk_add_f32 v[142:143], v[142:143], v[144:145]
	v_pk_add_f32 v[144:145], v[154:155], v[146:147]
	s_nop 0
	v_pk_add_f32 v[146:147], v[152:153], v[144:145]
	s_nop 0
	v_pk_add_f32 v[148:149], v[146:147], v[152:153] neg_lo:[0,1] neg_hi:[0,1]
	s_nop 0
	v_pk_add_f32 v[144:145], v[144:145], v[148:149] neg_lo:[0,1] neg_hi:[0,1]
	s_nop 0
	v_pk_add_f32 v[142:143], v[142:143], v[144:145]
	v_add_f32_e32 v144, v30, v130
	v_mul_f32_e64 v145, |v144|, s20
	v_pk_add_f32 v[142:143], v[146:147], v[142:143]
	v_fma_f32 v146, |v144|, s20, -v145
	v_rndne_f32_e32 v147, v145
	v_fma_f32 v146, |v144|, s51, v146
	v_sub_f32_e32 v145, v145, v147
	v_cndmask_b32_e32 v142, v221, v142, vcc
	v_cmp_neq_f32_e32 vcc, s77, v186
	v_add_f32_e32 v145, v145, v146
	v_exp_f32_e32 v145, v145
	v_cndmask_b32_e32 v143, v221, v143, vcc
	v_cmp_lt_f32_e64 vcc, |v186|, s79
	v_cvt_i32_f32_e32 v146, v147
	s_nop 0
	v_cndmask_b32_e32 v143, v143, v186, vcc
	v_cmp_lt_f32_e64 vcc, |v185|, s79
	s_nop 1
	v_cndmask_b32_e32 v142, v142, v185, vcc
	v_pk_add_f32 v[140:141], v[140:141], v[142:143] neg_lo:[0,1] neg_hi:[0,1]
	global_store_dwordx4 v[136:137], v[138:141], off offset:2304
	v_cmp_ngt_f32_e64 vcc, |v144|, s54
	s_nop 0
	v_ldexp_f32 v139, v145, v146
	v_cndmask_b32_e32 v139, 0, v139, vcc
	v_cmp_nlt_f32_e64 vcc, |v144|, s55
	v_add_f32_e32 v145, v31, v131
	v_min_f32_e32 v138, 0, v144
	v_cndmask_b32_e32 v168, v221, v139, vcc
	v_add_f32_e32 v142, 1.0, v168
	v_add_f32_e32 v139, -1.0, v142
	v_sub_f32_e32 v140, v139, v142
	v_add_f32_e32 v140, 1.0, v140
	v_sub_f32_e32 v139, v168, v139
	v_add_f32_e32 v143, v139, v140
	v_mul_f32_e64 v139, |v145|, s20
	v_fma_f32 v140, |v145|, s20, -v139
	v_rndne_f32_e32 v141, v139
	v_fma_f32 v140, |v145|, s51, v140
	v_sub_f32_e32 v139, v139, v141
	v_add_f32_e32 v139, v139, v140
	v_exp_f32_e32 v146, v139
	v_cvt_i32_f32_e32 v147, v141
	v_cvt_f64_f32_e32 v[140:141], v142
	v_frexp_exp_i32_f64_e32 v148, v[140:141]
	v_cmp_ngt_f32_e64 vcc, |v145|, s54
	v_ldexp_f32 v140, v146, v147
	v_min_f32_e32 v139, 0, v145
; __device__ __forceinline__ void epi_all_run(const void* Pk_, int l, int s, const f32x4 (&acc)[2][2][4][2], const pg8::Unit& u, int wr, int wc, int fr, int fq) {
;     ...
;                         for (int j = 0; j < 4; ++j) ls[j] = fminf(z[j], 0.f) - log1pf(expf(-fabsf(z[j])));
	v_cndmask_b32_e32 v140, 0, v140, vcc
	v_cmp_nlt_f32_e64 vcc, |v145|, s55
	v_frexp_mant_f32_e32 v144, v142
	s_nop 0
	v_cndmask_b32_e32 v169, v221, v140, vcc
	v_add_f32_e32 v145, 1.0, v169
	v_add_f32_e32 v140, -1.0, v145
	v_sub_f32_e32 v141, v140, v145
	v_add_f32_e32 v141, 1.0, v141
	v_sub_f32_e32 v140, v169, v140
	v_add_f32_e32 v146, v140, v141
	v_frexp_mant_f32_e32 v147, v145
	v_cvt_f64_f32_e32 v[140:141], v145
	v_frexp_exp_i32_f64_e32 v140, v[140:141]
	v_cmp_gt_f32_e32 vcc, s78, v147
	s_nop 1
	v_subbrev_co_u32_e32 v160, vcc, 0, v140, vcc
	v_cmp_gt_f32_e32 vcc, s78, v144
	s_nop 1
	v_subbrev_co_u32_e32 v161, vcc, 0, v148, vcc
	v_sub_u32_e32 v141, 0, v161
	v_ldexp_f32 v140, v142, v141
	v_ldexp_f32 v142, v143, v141
	v_sub_u32_e32 v143, 0, v160
	v_ldexp_f32 v141, v145, v143
	v_pk_add_f32 v[144:145], v[140:141], 1.0 op_sel_hi:[1,0]
	v_ldexp_f32 v143, v146, v143
	v_pk_add_f32 v[146:147], v[144:145], -1.0 op_sel_hi:[1,0]
	v_pk_add_f32 v[152:153], v[140:141], -1.0 op_sel_hi:[1,0]
	v_pk_add_f32 v[146:147], v[140:141], v[146:147] neg_lo:[0,1] neg_hi:[0,1]
	v_pk_add_f32 v[154:155], v[152:153], 1.0 op_sel_hi:[1,0]
	v_pk_add_f32 v[146:147], v[142:143], v[146:147]
	v_pk_add_f32 v[140:141], v[140:141], v[154:155] neg_lo:[0,1] neg_hi:[0,1]
	v_pk_add_f32 v[148:149], v[144:145], v[146:147]
	v_pk_add_f32 v[140:141], v[142:143], v[140:141]
	v_rcp_f32_e32 v150, v148
	v_rcp_f32_e32 v151, v149
	v_pk_add_f32 v[142:143], v[152:153], v[140:141]
	v_pk_add_f32 v[144:145], v[144:145], v[148:149] neg_lo:[0,1] neg_hi:[0,1]
	v_pk_add_f32 v[152:153], v[152:153], v[142:143] neg_lo:[0,1] neg_hi:[0,1]
	v_pk_add_f32 v[144:145], v[146:147], v[144:145]
	v_pk_mul_f32 v[146:147], v[142:143], v[150:151]
	v_pk_add_f32 v[140:141], v[140:141], v[152:153]
	v_pk_mul_f32 v[152:153], v[148:149], v[146:147]
	v_cmp_neq_f32_e32 vcc, s77, v168
	v_pk_fma_f32 v[154:155], v[146:147], v[148:149], v[152:153] neg_lo:[0,0,1] neg_hi:[0,0,1]
	s_nop 0
	v_pk_fma_f32 v[154:155], v[146:147], v[144:145], v[154:155]
	s_nop 0
	v_pk_add_f32 v[156:157], v[152:153], v[154:155]
	s_nop 0
	v_pk_add_f32 v[158:159], v[142:143], v[156:157] neg_lo:[0,1] neg_hi:[0,1]
	v_pk_add_f32 v[152:153], v[156:157], v[152:153] neg_lo:[0,1] neg_hi:[0,1]
	v_pk_add_f32 v[142:143], v[142:143], v[158:159] neg_lo:[0,1] neg_hi:[0,1]
	s_nop 0
	v_pk_add_f32 v[142:143], v[142:143], v[156:157] neg_lo:[0,1] neg_hi:[0,1]
	s_nop 0
	v_pk_add_f32 v[140:141], v[140:141], v[142:143]
	v_pk_add_f32 v[142:143], v[152:153], v[154:155] neg_lo:[0,1] neg_hi:[0,1]
	s_nop 0
	v_pk_add_f32 v[140:141], v[142:143], v[140:141]
	s_nop 0
	v_pk_add_f32 v[142:143], v[158:159], v[140:141]
	s_nop 0
	v_pk_mul_f32 v[152:153], v[150:151], v[142:143]
	s_nop 0
	v_pk_mul_f32 v[154:155], v[148:149], v[152:153]
	s_nop 0
	v_pk_fma_f32 v[148:149], v[152:153], v[148:149], v[154:155] neg_lo:[0,0,1] neg_hi:[0,0,1]
	s_nop 0
	v_pk_fma_f32 v[144:145], v[152:153], v[144:145], v[148:149]
	v_pk_add_f32 v[148:149], v[158:159], v[142:143] neg_lo:[0,1] neg_hi:[0,1]
	s_nop 0
	v_pk_add_f32 v[140:141], v[140:141], v[148:149]
	v_pk_add_f32 v[148:149], v[154:155], v[144:145]
	s_nop 0
	v_pk_add_f32 v[156:157], v[142:143], v[148:149] neg_lo:[0,1] neg_hi:[0,1]
	v_pk_add_f32 v[154:155], v[148:149], v[154:155] neg_lo:[0,1] neg_hi:[0,1]
	v_pk_add_f32 v[142:143], v[142:143], v[156:157] neg_lo:[0,1] neg_hi:[0,1]
	s_nop 0
	v_pk_add_f32 v[142:143], v[142:143], v[148:149] neg_lo:[0,1] neg_hi:[0,1]
	s_nop 0
	v_pk_add_f32 v[140:141], v[140:141], v[142:143]
	v_pk_add_f32 v[142:143], v[154:155], v[144:145] neg_lo:[0,1] neg_hi:[0,1]
	s_nop 0
	v_pk_add_f32 v[140:141], v[142:143], v[140:141]
	v_pk_add_f32 v[142:143], v[146:147], v[152:153]
	v_pk_add_f32 v[140:141], v[156:157], v[140:141]
	v_pk_add_f32 v[144:145], v[142:143], v[146:147] neg_lo:[0,1] neg_hi:[0,1]
	v_pk_mul_f32 v[140:141], v[150:151], v[140:141]
	v_pk_add_f32 v[144:145], v[152:153], v[144:145] neg_lo:[0,1] neg_hi:[0,1]
	v_cvt_f32_i32_e32 v147, v160
	v_pk_add_f32 v[140:141], v[144:145], v[140:141]
	v_cvt_f32_i32_e32 v146, v161
	v_pk_add_f32 v[144:145], v[142:143], v[140:141]
	v_pk_mul_f32 v[152:153], v[146:147], s[84:85] op_sel_hi:[1,0]
	v_pk_mul_f32 v[148:149], v[144:145], v[144:145]
	v_pk_add_f32 v[142:143], v[144:145], v[142:143] neg_lo:[0,1] neg_hi:[0,1]
	v_pk_fma_f32 v[150:151], v[148:149], s[80:81], v[134:135] op_sel_hi:[1,0,0]
	v_pk_add_f32 v[140:141], v[140:141], v[142:143] neg_lo:[0,1] neg_hi:[0,1]
	v_ldexp_f32 v142, v144, 1
	v_pk_fma_f32 v[150:151], v[148:149], v[150:151], s[82:83] op_sel_hi:[1,1,0]
	v_ldexp_f32 v143, v145, 1
	v_pk_mul_f32 v[144:145], v[144:145], v[148:149]
	v_pk_fma_f32 v[154:155], v[146:147], s[84:85], v[152:153] op_sel_hi:[1,0,1] neg_lo:[0,0,1] neg_hi:[0,0,1]
	v_pk_mul_f32 v[144:145], v[144:145], v[150:151]
	v_mov_b32_e32 v157, v143
	v_pk_add_f32 v[148:149], v[142:143], v[144:145]
	v_ldexp_f32 v140, v140, 1
	v_pk_add_f32 v[142:143], v[148:149], v[142:143] neg_lo:[0,1] neg_hi:[0,1]
	v_pk_fma_f32 v[146:147], v[146:147], s[86:87], v[154:155] op_sel_hi:[1,0,1]
	v_ldexp_f32 v141, v141, 1
	v_pk_add_f32 v[142:143], v[144:145], v[142:143] neg_lo:[0,1] neg_hi:[0,1]
	v_mov_b32_e32 v150, v152
	v_mov_b32_e32 v151, v145
	v_mov_b32_e32 v156, v146
	v_pk_add_f32 v[144:145], v[140:141], v[142:143]
	v_mov_b32_e32 v142, v152
	v_mov_b32_e32 v140, v146
	v_pk_add_f32 v[150:151], v[150:151], v[156:157]
	v_pk_add_f32 v[156:157], v[142:143], v[140:141]
	v_mov_b32_e32 v140, v148
	v_mov_b32_e32 v142, v144
	v_pk_add_f32 v[154:155], v[152:153], v[146:147]
	v_pk_add_f32 v[140:141], v[140:141], v[142:143]
	v_pk_add_f32 v[142:143], v[148:149], v[144:145]
	v_mov_b32_e32 v158, v154
	v_mov_b32_e32 v159, v153
	v_mov_b32_e32 v160, v142
; __device__ __forceinline__ void epi_all_run(const void* Pk_, int l, int s, const f32x4 (&acc)[2][2][4][2], const pg8::Unit& u, int wr, int wc, int fr, int fq) {
;     ...
;                         const f32x4 z = acc[ai][0][m][0] + fbv;
;                         f32x4 ls;
; #pragma unroll
;                         for (int j = 0; j < 4; ++j) ls[j] = fminf(z[j], 0.f) - log1pf(expf(-fabsf(z[j])));
;                         *(f32x4*)(logf + (size_t)row * 4) = ls;
	v_mov_b32_e32 v161, v147
	v_pk_add_f32 v[140:141], v[150:151], v[140:141]
	v_pk_add_f32 v[150:151], v[154:155], v[142:143]
	v_pk_add_f32 v[162:163], v[158:159], v[160:161]
	v_mov_b32_e32 v164, v142
	v_mov_b32_e32 v165, v151
	v_mov_b32_e32 v166, v148
	v_mov_b32_e32 v167, v155
	v_pk_add_f32 v[158:159], v[162:163], v[158:159] neg_lo:[0,1] neg_hi:[0,1]
	v_pk_add_f32 v[164:165], v[164:165], v[166:167] neg_lo:[0,1] neg_hi:[0,1]
	v_pk_add_f32 v[162:163], v[154:155], v[152:153] neg_lo:[0,1] neg_hi:[0,1]
	v_pk_add_f32 v[160:161], v[160:161], v[158:159] neg_lo:[0,1] neg_hi:[0,1]
	v_mov_b32_e32 v166, v154
	v_mov_b32_e32 v167, v151
	v_mov_b32_e32 v153, v165
	v_mov_b32_e32 v159, v149
	v_pk_add_f32 v[148:149], v[142:143], v[148:149] neg_lo:[0,1] neg_hi:[0,1]
	v_pk_add_f32 v[152:153], v[166:167], v[152:153] neg_lo:[0,1] neg_hi:[0,1]
	v_pk_add_f32 v[162:163], v[146:147], v[162:163] neg_lo:[0,1] neg_hi:[0,1]
	v_pk_add_f32 v[140:141], v[140:141], v[158:159] neg_lo:[0,1] neg_hi:[0,1]
	v_pk_add_f32 v[148:149], v[144:145], v[148:149] neg_lo:[0,1] neg_hi:[0,1]
	v_mov_b32_e32 v147, v155
	v_mov_b32_e32 v145, v143
	v_pk_add_f32 v[140:141], v[156:157], v[140:141] neg_lo:[0,1] neg_hi:[0,1]
	v_pk_add_f32 v[146:147], v[146:147], v[152:153] neg_lo:[0,1] neg_hi:[0,1]
	v_pk_add_f32 v[142:143], v[144:145], v[164:165] neg_lo:[0,1] neg_hi:[0,1]
	v_pk_add_f32 v[152:153], v[160:161], v[140:141]
	v_pk_add_f32 v[144:145], v[142:143], v[146:147]
	v_mov_b32_e32 v143, v141
	v_pk_add_f32 v[140:141], v[162:163], v[142:143]
	v_mov_b32_e32 v147, v161
	v_pk_add_f32 v[140:141], v[140:141], v[146:147] neg_lo:[0,1] neg_hi:[0,1]
	v_mov_b32_e32 v142, v144
	v_mov_b32_e32 v143, v153
	v_pk_add_f32 v[142:143], v[142:143], v[140:141] neg_lo:[0,1] neg_hi:[0,1]
	v_pk_add_f32 v[140:141], v[148:149], v[140:141] neg_lo:[0,1] neg_hi:[0,1]
	v_pk_add_f32 v[142:143], v[146:147], v[142:143] neg_lo:[0,1] neg_hi:[0,1]
	s_nop 0
	v_pk_add_f32 v[140:141], v[140:141], v[142:143]
	v_pk_add_f32 v[142:143], v[152:153], v[144:145]
	s_nop 0
	v_pk_add_f32 v[144:145], v[150:151], v[142:143]
	s_nop 0
	v_pk_add_f32 v[146:147], v[144:145], v[150:151] neg_lo:[0,1] neg_hi:[0,1]
	s_nop 0
	v_pk_add_f32 v[142:143], v[142:143], v[146:147] neg_lo:[0,1] neg_hi:[0,1]
	v_add_f32_e32 v147, v33, v133
	v_pk_add_f32 v[140:141], v[140:141], v[142:143]
	v_add_f32_e32 v142, v32, v132
	v_mul_f32_e64 v143, |v142|, s20
	v_pk_add_f32 v[140:141], v[144:145], v[140:141]
	v_fma_f32 v144, |v142|, s20, -v143
	v_rndne_f32_e32 v145, v143
	v_fma_f32 v144, |v142|, s51, v144
	v_sub_f32_e32 v143, v143, v145
	v_add_f32_e32 v143, v143, v144
	v_cndmask_b32_e32 v140, v221, v140, vcc
	v_cmp_neq_f32_e32 vcc, s77, v169
	v_exp_f32_e32 v143, v143
	v_cvt_i32_f32_e32 v144, v145
	v_cndmask_b32_e32 v141, v221, v141, vcc
	v_cmp_lt_f32_e64 vcc, |v169|, s79
	s_nop 1
	v_cndmask_b32_e32 v141, v141, v169, vcc
	v_cmp_lt_f32_e64 vcc, |v168|, s79
	s_nop 1
	v_cndmask_b32_e32 v140, v140, v168, vcc
	v_pk_add_f32 v[138:139], v[138:139], v[140:141] neg_lo:[0,1] neg_hi:[0,1]
	v_ldexp_f32 v141, v143, v144
	v_cmp_ngt_f32_e64 vcc, |v142|, s54
	v_min_f32_e32 v140, 0, v142
	s_nop 0
	v_cndmask_b32_e32 v141, 0, v141, vcc
	v_cmp_nlt_f32_e64 vcc, |v142|, s55
	s_nop 1
	v_cndmask_b32_e32 v185, v221, v141, vcc
	v_add_f32_e32 v144, 1.0, v185
	v_add_f32_e32 v141, -1.0, v144
	v_sub_f32_e32 v142, v141, v144
	v_add_f32_e32 v142, 1.0, v142
	v_sub_f32_e32 v141, v185, v141
	v_add_f32_e32 v145, v141, v142
	v_mul_f32_e64 v141, |v147|, s20
	v_fma_f32 v142, |v147|, s20, -v141
	v_rndne_f32_e32 v143, v141
	v_fma_f32 v142, |v147|, s51, v142
	v_sub_f32_e32 v141, v141, v143
	v_add_f32_e32 v141, v141, v142
	v_exp_f32_e32 v148, v141
	v_cvt_i32_f32_e32 v149, v143
	v_cvt_f64_f32_e32 v[142:143], v144
	v_frexp_exp_i32_f64_e32 v150, v[142:143]
	v_cmp_ngt_f32_e64 vcc, |v147|, s54
	v_ldexp_f32 v142, v148, v149
	v_min_f32_e32 v141, 0, v147
	v_cndmask_b32_e32 v142, 0, v142, vcc
	v_cmp_nlt_f32_e64 vcc, |v147|, s55
	v_frexp_mant_f32_e32 v146, v144
	s_nop 0
	v_cndmask_b32_e32 v186, v221, v142, vcc
	v_add_f32_e32 v147, 1.0, v186
	v_add_f32_e32 v142, -1.0, v147
	v_sub_f32_e32 v143, v142, v147
	v_add_f32_e32 v143, 1.0, v143
	v_sub_f32_e32 v142, v186, v142
	v_add_f32_e32 v148, v142, v143
	v_frexp_mant_f32_e32 v149, v147
	v_cvt_f64_f32_e32 v[142:143], v147
	v_frexp_exp_i32_f64_e32 v142, v[142:143]
	v_cmp_gt_f32_e32 vcc, s78, v149
	s_nop 1
	v_subbrev_co_u32_e32 v162, vcc, 0, v142, vcc
	v_cmp_gt_f32_e32 vcc, s78, v146
	s_nop 1
	v_subbrev_co_u32_e32 v163, vcc, 0, v150, vcc
	v_sub_u32_e32 v143, 0, v163
	v_ldexp_f32 v142, v144, v143
	v_ldexp_f32 v144, v145, v143
	v_sub_u32_e32 v145, 0, v162
	v_ldexp_f32 v143, v147, v145
	v_pk_add_f32 v[146:147], v[142:143], 1.0 op_sel_hi:[1,0]
	v_ldexp_f32 v145, v148, v145
	v_pk_add_f32 v[148:149], v[146:147], -1.0 op_sel_hi:[1,0]
	v_pk_add_f32 v[154:155], v[142:143], -1.0 op_sel_hi:[1,0]
	v_pk_add_f32 v[148:149], v[142:143], v[148:149] neg_lo:[0,1] neg_hi:[0,1]
	v_pk_add_f32 v[156:157], v[154:155], 1.0 op_sel_hi:[1,0]
	v_pk_add_f32 v[148:149], v[144:145], v[148:149]
	v_pk_add_f32 v[142:143], v[142:143], v[156:157] neg_lo:[0,1] neg_hi:[0,1]
	v_pk_add_f32 v[150:151], v[146:147], v[148:149]
	v_pk_add_f32 v[142:143], v[144:145], v[142:143]
	v_rcp_f32_e32 v152, v150
	v_rcp_f32_e32 v153, v151
	v_pk_add_f32 v[144:145], v[154:155], v[142:143]
	v_pk_add_f32 v[146:147], v[146:147], v[150:151] neg_lo:[0,1] neg_hi:[0,1]
	v_pk_add_f32 v[154:155], v[154:155], v[144:145] neg_lo:[0,1] neg_hi:[0,1]
	v_pk_add_f32 v[146:147], v[148:149], v[146:147]
	v_pk_mul_f32 v[148:149], v[144:145], v[152:153]
	v_pk_add_f32 v[142:143], v[142:143], v[154:155]
	v_pk_mul_f32 v[154:155], v[150:151], v[148:149]
; __device__ __forceinline__ void epi_all_run(const void* Pk_, int l, int s, const f32x4 (&acc)[2][2][4][2], const pg8::Unit& u, int wr, int wc, int fr, int fq) {
;     ...
;                         for (int j = 0; j < 4; ++j) ls[j] = fminf(z[j], 0.f) - log1pf(expf(-fabsf(z[j])));
	v_cmp_neq_f32_e32 vcc, s77, v185
	v_pk_fma_f32 v[156:157], v[148:149], v[150:151], v[154:155] neg_lo:[0,0,1] neg_hi:[0,0,1]
	s_nop 0
	v_pk_fma_f32 v[156:157], v[148:149], v[146:147], v[156:157]
	s_nop 0
	v_pk_add_f32 v[158:159], v[154:155], v[156:157]
	s_nop 0
	v_pk_add_f32 v[160:161], v[144:145], v[158:159] neg_lo:[0,1] neg_hi:[0,1]
	v_pk_add_f32 v[154:155], v[158:159], v[154:155] neg_lo:[0,1] neg_hi:[0,1]
	v_pk_add_f32 v[144:145], v[144:145], v[160:161] neg_lo:[0,1] neg_hi:[0,1]
	s_nop 0
	v_pk_add_f32 v[144:145], v[144:145], v[158:159] neg_lo:[0,1] neg_hi:[0,1]
	s_nop 0
	v_pk_add_f32 v[142:143], v[142:143], v[144:145]
	v_pk_add_f32 v[144:145], v[154:155], v[156:157] neg_lo:[0,1] neg_hi:[0,1]
	s_nop 0
	v_pk_add_f32 v[142:143], v[144:145], v[142:143]
	s_nop 0
	v_pk_add_f32 v[144:145], v[160:161], v[142:143]
	s_nop 0
	v_pk_mul_f32 v[154:155], v[152:153], v[144:145]
	s_nop 0
	v_pk_mul_f32 v[156:157], v[150:151], v[154:155]
	s_nop 0
	v_pk_fma_f32 v[150:151], v[154:155], v[150:151], v[156:157] neg_lo:[0,0,1] neg_hi:[0,0,1]
	s_nop 0
	v_pk_fma_f32 v[146:147], v[154:155], v[146:147], v[150:151]
	v_pk_add_f32 v[150:151], v[160:161], v[144:145] neg_lo:[0,1] neg_hi:[0,1]
	s_nop 0
	v_pk_add_f32 v[142:143], v[142:143], v[150:151]
	v_pk_add_f32 v[150:151], v[156:157], v[146:147]
	s_nop 0
	v_pk_add_f32 v[158:159], v[144:145], v[150:151] neg_lo:[0,1] neg_hi:[0,1]
	v_pk_add_f32 v[156:157], v[150:151], v[156:157] neg_lo:[0,1] neg_hi:[0,1]
	v_pk_add_f32 v[144:145], v[144:145], v[158:159] neg_lo:[0,1] neg_hi:[0,1]
	s_nop 0
	v_pk_add_f32 v[144:145], v[144:145], v[150:151] neg_lo:[0,1] neg_hi:[0,1]
	s_nop 0
	v_pk_add_f32 v[142:143], v[142:143], v[144:145]
	v_pk_add_f32 v[144:145], v[156:157], v[146:147] neg_lo:[0,1] neg_hi:[0,1]
	s_nop 0
	v_pk_add_f32 v[142:143], v[144:145], v[142:143]
	v_pk_add_f32 v[144:145], v[148:149], v[154:155]
	v_pk_add_f32 v[142:143], v[158:159], v[142:143]
	v_pk_add_f32 v[146:147], v[144:145], v[148:149] neg_lo:[0,1] neg_hi:[0,1]
	v_pk_mul_f32 v[142:143], v[152:153], v[142:143]
	v_pk_add_f32 v[146:147], v[154:155], v[146:147] neg_lo:[0,1] neg_hi:[0,1]
	v_cvt_f32_i32_e32 v149, v162
	v_pk_add_f32 v[142:143], v[146:147], v[142:143]
	v_cvt_f32_i32_e32 v148, v163
	v_pk_add_f32 v[146:147], v[144:145], v[142:143]
	v_pk_mul_f32 v[154:155], v[148:149], s[84:85] op_sel_hi:[1,0]
	v_pk_mul_f32 v[150:151], v[146:147], v[146:147]
	v_pk_add_f32 v[144:145], v[146:147], v[144:145] neg_lo:[0,1] neg_hi:[0,1]
	v_pk_fma_f32 v[152:153], v[150:151], s[80:81], v[134:135] op_sel_hi:[1,0,0]
	v_pk_add_f32 v[142:143], v[142:143], v[144:145] neg_lo:[0,1] neg_hi:[0,1]
	v_ldexp_f32 v144, v146, 1
	v_pk_fma_f32 v[152:153], v[150:151], v[152:153], s[82:83] op_sel_hi:[1,1,0]
	v_ldexp_f32 v145, v147, 1
	v_pk_mul_f32 v[146:147], v[146:147], v[150:151]
	v_pk_fma_f32 v[156:157], v[148:149], s[84:85], v[154:155] op_sel_hi:[1,0,1] neg_lo:[0,0,1] neg_hi:[0,0,1]
	v_pk_mul_f32 v[146:147], v[146:147], v[152:153]
	v_mov_b32_e32 v159, v145
	v_pk_add_f32 v[150:151], v[144:145], v[146:147]
	v_ldexp_f32 v142, v142, 1
	v_pk_add_f32 v[144:145], v[150:151], v[144:145] neg_lo:[0,1] neg_hi:[0,1]
	v_pk_fma_f32 v[148:149], v[148:149], s[86:87], v[156:157] op_sel_hi:[1,0,1]
	v_ldexp_f32 v143, v143, 1
	v_pk_add_f32 v[144:145], v[146:147], v[144:145] neg_lo:[0,1] neg_hi:[0,1]
	v_mov_b32_e32 v152, v154
	v_mov_b32_e32 v153, v147
	v_mov_b32_e32 v158, v148
	v_pk_add_f32 v[146:147], v[142:143], v[144:145]
	v_mov_b32_e32 v144, v154
	v_mov_b32_e32 v142, v148
	v_pk_add_f32 v[152:153], v[152:153], v[158:159]
	v_pk_add_f32 v[158:159], v[144:145], v[142:143]
	v_mov_b32_e32 v142, v150
	v_mov_b32_e32 v144, v146
	v_pk_add_f32 v[156:157], v[154:155], v[148:149]
	v_pk_add_f32 v[142:143], v[142:143], v[144:145]
	v_pk_add_f32 v[144:145], v[150:151], v[146:147]
	v_mov_b32_e32 v160, v156
	v_mov_b32_e32 v161, v155
	v_mov_b32_e32 v162, v144
	v_mov_b32_e32 v163, v149
	v_pk_add_f32 v[142:143], v[152:153], v[142:143]
	v_pk_add_f32 v[152:153], v[156:157], v[144:145]
	v_pk_add_f32 v[164:165], v[160:161], v[162:163]
	v_mov_b32_e32 v166, v144
	v_mov_b32_e32 v167, v153
	v_mov_b32_e32 v168, v150
	v_mov_b32_e32 v169, v157
	v_pk_add_f32 v[160:161], v[164:165], v[160:161] neg_lo:[0,1] neg_hi:[0,1]
	v_pk_add_f32 v[166:167], v[166:167], v[168:169] neg_lo:[0,1] neg_hi:[0,1]
	v_pk_add_f32 v[164:165], v[156:157], v[154:155] neg_lo:[0,1] neg_hi:[0,1]
	v_pk_add_f32 v[162:163], v[162:163], v[160:161] neg_lo:[0,1] neg_hi:[0,1]
	v_mov_b32_e32 v168, v156
	v_mov_b32_e32 v169, v153
	v_mov_b32_e32 v155, v167
	v_mov_b32_e32 v161, v151
	v_pk_add_f32 v[150:151], v[144:145], v[150:151] neg_lo:[0,1] neg_hi:[0,1]
	v_pk_add_f32 v[154:155], v[168:169], v[154:155] neg_lo:[0,1] neg_hi:[0,1]
	v_pk_add_f32 v[164:165], v[148:149], v[164:165] neg_lo:[0,1] neg_hi:[0,1]
	v_pk_add_f32 v[142:143], v[142:143], v[160:161] neg_lo:[0,1] neg_hi:[0,1]
	v_pk_add_f32 v[150:151], v[146:147], v[150:151] neg_lo:[0,1] neg_hi:[0,1]
	v_mov_b32_e32 v149, v157
	v_mov_b32_e32 v147, v145
	v_pk_add_f32 v[142:143], v[158:159], v[142:143] neg_lo:[0,1] neg_hi:[0,1]
	v_pk_add_f32 v[148:149], v[148:149], v[154:155] neg_lo:[0,1] neg_hi:[0,1]
	v_pk_add_f32 v[144:145], v[146:147], v[166:167] neg_lo:[0,1] neg_hi:[0,1]
	v_pk_add_f32 v[154:155], v[162:163], v[142:143]
	v_pk_add_f32 v[146:147], v[144:145], v[148:149]
	v_mov_b32_e32 v145, v143
	v_pk_add_f32 v[142:143], v[164:165], v[144:145]
	v_mov_b32_e32 v149, v163
	v_pk_add_f32 v[142:143], v[142:143], v[148:149] neg_lo:[0,1] neg_hi:[0,1]
	v_mov_b32_e32 v144, v146
	v_mov_b32_e32 v145, v155
	v_pk_add_f32 v[144:145], v[144:145], v[142:143] neg_lo:[0,1] neg_hi:[0,1]
	v_pk_add_f32 v[142:143], v[150:151], v[142:143] neg_lo:[0,1] neg_hi:[0,1]
; __device__ __forceinline__ void epi_all_run(const void* Pk_, int l, int s, const f32x4 (&acc)[2][2][4][2], const pg8::Unit& u, int wr, int wc, int fr, int fq) {
;     ...
;                         const f32x4 z = acc[ai][0][m][0] + fbv;
;                         f32x4 ls;
; #pragma unroll
;                         for (int j = 0; j < 4; ++j) ls[j] = fminf(z[j], 0.f) - log1pf(expf(-fabsf(z[j])));
;                         *(f32x4*)(logf + (size_t)row * 4) = ls;
	v_pk_add_f32 v[144:145], v[148:149], v[144:145] neg_lo:[0,1] neg_hi:[0,1]
	s_nop 0
	v_pk_add_f32 v[142:143], v[142:143], v[144:145]
	v_pk_add_f32 v[144:145], v[154:155], v[146:147]
	s_nop 0
	v_pk_add_f32 v[146:147], v[152:153], v[144:145]
	s_nop 0
	v_pk_add_f32 v[148:149], v[146:147], v[152:153] neg_lo:[0,1] neg_hi:[0,1]
	s_nop 0
	v_pk_add_f32 v[144:145], v[144:145], v[148:149] neg_lo:[0,1] neg_hi:[0,1]
	s_nop 0
	v_pk_add_f32 v[142:143], v[142:143], v[144:145]
	v_add_f32_e32 v144, v14, v130
	v_mul_f32_e64 v130, |v144|, s20
	v_pk_add_f32 v[142:143], v[146:147], v[142:143]
	v_fma_f32 v145, |v144|, s20, -v130
	v_rndne_f32_e32 v146, v130
	v_fma_f32 v145, |v144|, s51, v145
	v_sub_f32_e32 v130, v130, v146
	v_cndmask_b32_e32 v142, v221, v142, vcc
	v_cmp_neq_f32_e32 vcc, s77, v186
	v_add_f32_e32 v130, v130, v145
	v_exp_f32_e32 v145, v130
	v_cndmask_b32_e32 v143, v221, v143, vcc
	v_cmp_lt_f32_e64 vcc, |v186|, s79
	v_cvt_i32_f32_e32 v146, v146
	v_min_f32_e32 v130, 0, v144
	v_cndmask_b32_e32 v143, v143, v186, vcc
	v_cmp_lt_f32_e64 vcc, |v185|, s79
	s_nop 1
	v_cndmask_b32_e32 v142, v142, v185, vcc
	v_pk_add_f32 v[140:141], v[140:141], v[142:143] neg_lo:[0,1] neg_hi:[0,1]
	global_store_dwordx4 v[136:137], v[138:141], off offset:2560
	v_cmp_ngt_f32_e64 vcc, |v144|, s54
	v_add_f32_e32 v143, v15, v131
	v_ldexp_f32 v138, v145, v146
	v_cndmask_b32_e32 v138, 0, v138, vcc
	v_cmp_nlt_f32_e64 vcc, |v144|, s55
	v_mul_f32_e64 v131, |v143|, s20
	s_nop 0
	v_cndmask_b32_e32 v166, v221, v138, vcc
	v_add_f32_e32 v140, 1.0, v166
	v_add_f32_e32 v138, -1.0, v140
	v_sub_f32_e32 v139, v138, v140
	v_add_f32_e32 v139, 1.0, v139
	v_sub_f32_e32 v138, v166, v138
	v_add_f32_e32 v141, v138, v139
	v_fma_f32 v138, |v143|, s20, -v131
	v_rndne_f32_e32 v139, v131
	v_fma_f32 v138, |v143|, s51, v138
	v_sub_f32_e32 v131, v131, v139
	v_add_f32_e32 v131, v131, v138
	v_exp_f32_e32 v144, v131
	v_cvt_i32_f32_e32 v145, v139
	v_cvt_f64_f32_e32 v[138:139], v140
	v_frexp_exp_i32_f64_e32 v146, v[138:139]
	v_cmp_ngt_f32_e64 vcc, |v143|, s54
	v_ldexp_f32 v138, v144, v145
	v_min_f32_e32 v131, 0, v143
	v_cndmask_b32_e32 v138, 0, v138, vcc
	v_cmp_nlt_f32_e64 vcc, |v143|, s55
	v_frexp_mant_f32_e32 v142, v140
	s_nop 0
	v_cndmask_b32_e32 v167, v221, v138, vcc
	v_add_f32_e32 v143, 1.0, v167
	v_add_f32_e32 v138, -1.0, v143
	v_sub_f32_e32 v139, v138, v143
	v_add_f32_e32 v139, 1.0, v139
	v_sub_f32_e32 v138, v167, v138
	v_add_f32_e32 v144, v138, v139
	v_frexp_mant_f32_e32 v145, v143
	v_cvt_f64_f32_e32 v[138:139], v143
	v_frexp_exp_i32_f64_e32 v138, v[138:139]
	v_cmp_gt_f32_e32 vcc, s78, v145
	s_nop 1
	v_subbrev_co_u32_e32 v158, vcc, 0, v138, vcc
	v_cmp_gt_f32_e32 vcc, s78, v142
	s_nop 1
	v_subbrev_co_u32_e32 v159, vcc, 0, v146, vcc
	v_sub_u32_e32 v139, 0, v159
	v_ldexp_f32 v138, v140, v139
	v_ldexp_f32 v140, v141, v139
	v_sub_u32_e32 v141, 0, v158
	v_ldexp_f32 v139, v143, v141
	v_pk_add_f32 v[142:143], v[138:139], 1.0 op_sel_hi:[1,0]
	v_ldexp_f32 v141, v144, v141
	v_pk_add_f32 v[144:145], v[142:143], -1.0 op_sel_hi:[1,0]
	v_pk_add_f32 v[150:151], v[138:139], -1.0 op_sel_hi:[1,0]
	v_pk_add_f32 v[144:145], v[138:139], v[144:145] neg_lo:[0,1] neg_hi:[0,1]
	v_pk_add_f32 v[152:153], v[150:151], 1.0 op_sel_hi:[1,0]
	v_pk_add_f32 v[144:145], v[140:141], v[144:145]
	v_pk_add_f32 v[138:139], v[138:139], v[152:153] neg_lo:[0,1] neg_hi:[0,1]
	v_pk_add_f32 v[146:147], v[142:143], v[144:145]
	v_pk_add_f32 v[138:139], v[140:141], v[138:139]
	v_rcp_f32_e32 v148, v146
	v_rcp_f32_e32 v149, v147
	v_pk_add_f32 v[140:141], v[150:151], v[138:139]
	v_pk_add_f32 v[142:143], v[142:143], v[146:147] neg_lo:[0,1] neg_hi:[0,1]
	v_pk_add_f32 v[150:151], v[150:151], v[140:141] neg_lo:[0,1] neg_hi:[0,1]
	v_pk_add_f32 v[142:143], v[144:145], v[142:143]
	v_pk_mul_f32 v[144:145], v[140:141], v[148:149]
	v_pk_add_f32 v[138:139], v[138:139], v[150:151]
	v_pk_mul_f32 v[150:151], v[146:147], v[144:145]
	v_cmp_neq_f32_e32 vcc, s77, v166
	v_pk_fma_f32 v[152:153], v[144:145], v[146:147], v[150:151] neg_lo:[0,0,1] neg_hi:[0,0,1]
	s_nop 0
	v_pk_fma_f32 v[152:153], v[144:145], v[142:143], v[152:153]
	s_nop 0
	v_pk_add_f32 v[154:155], v[150:151], v[152:153]
	s_nop 0
	v_pk_add_f32 v[156:157], v[140:141], v[154:155] neg_lo:[0,1] neg_hi:[0,1]
	v_pk_add_f32 v[150:151], v[154:155], v[150:151] neg_lo:[0,1] neg_hi:[0,1]
	v_pk_add_f32 v[140:141], v[140:141], v[156:157] neg_lo:[0,1] neg_hi:[0,1]
	s_nop 0
	v_pk_add_f32 v[140:141], v[140:141], v[154:155] neg_lo:[0,1] neg_hi:[0,1]
	s_nop 0
	v_pk_add_f32 v[138:139], v[138:139], v[140:141]
	v_pk_add_f32 v[140:141], v[150:151], v[152:153] neg_lo:[0,1] neg_hi:[0,1]
	s_nop 0
	v_pk_add_f32 v[138:139], v[140:141], v[138:139]
	s_nop 0
	v_pk_add_f32 v[140:141], v[156:157], v[138:139]
	s_nop 0
	v_pk_mul_f32 v[150:151], v[148:149], v[140:141]
	s_nop 0
	v_pk_mul_f32 v[152:153], v[146:147], v[150:151]
	s_nop 0
	v_pk_fma_f32 v[146:147], v[150:151], v[146:147], v[152:153] neg_lo:[0,0,1] neg_hi:[0,0,1]
	s_nop 0
	v_pk_fma_f32 v[142:143], v[150:151], v[142:143], v[146:147]
	v_pk_add_f32 v[146:147], v[156:157], v[140:141] neg_lo:[0,1] neg_hi:[0,1]
	s_nop 0
	v_pk_add_f32 v[138:139], v[138:139], v[146:147]
	v_pk_add_f32 v[146:147], v[152:153], v[142:143]
	s_nop 0
	v_pk_add_f32 v[154:155], v[140:141], v[146:147] neg_lo:[0,1] neg_hi:[0,1]
	v_pk_add_f32 v[152:153], v[146:147], v[152:153] neg_lo:[0,1] neg_hi:[0,1]
	v_pk_add_f32 v[140:141], v[140:141], v[154:155] neg_lo:[0,1] neg_hi:[0,1]
	s_nop 0
	v_pk_add_f32 v[140:141], v[140:141], v[146:147] neg_lo:[0,1] neg_hi:[0,1]
	s_nop 0
	v_pk_add_f32 v[138:139], v[138:139], v[140:141]
	v_pk_add_f32 v[140:141], v[152:153], v[142:143] neg_lo:[0,1] neg_hi:[0,1]
	s_nop 0
	v_pk_add_f32 v[138:139], v[140:141], v[138:139]
; __device__ __forceinline__ void epi_all_run(const void* Pk_, int l, int s, const f32x4 (&acc)[2][2][4][2], const pg8::Unit& u, int wr, int wc, int fr, int fq) {
;     ...
;                         const f32x4 z = acc[ai][0][m][0] + fbv;
;                         f32x4 ls;
; #pragma unroll
;                         for (int j = 0; j < 4; ++j) ls[j] = fminf(z[j], 0.f) - log1pf(expf(-fabsf(z[j])));
;                         *(f32x4*)(logf + (size_t)row * 4) = ls;
	v_pk_add_f32 v[140:141], v[144:145], v[150:151]
	v_pk_add_f32 v[138:139], v[154:155], v[138:139]
	v_pk_add_f32 v[142:143], v[140:141], v[144:145] neg_lo:[0,1] neg_hi:[0,1]
	v_pk_mul_f32 v[138:139], v[148:149], v[138:139]
	v_pk_add_f32 v[142:143], v[150:151], v[142:143] neg_lo:[0,1] neg_hi:[0,1]
	v_cvt_f32_i32_e32 v145, v158
	v_pk_add_f32 v[138:139], v[142:143], v[138:139]
	v_cvt_f32_i32_e32 v144, v159
	v_pk_add_f32 v[142:143], v[140:141], v[138:139]
	v_pk_mul_f32 v[150:151], v[144:145], s[84:85] op_sel_hi:[1,0]
	v_pk_mul_f32 v[146:147], v[142:143], v[142:143]
	v_pk_add_f32 v[140:141], v[142:143], v[140:141] neg_lo:[0,1] neg_hi:[0,1]
	v_pk_fma_f32 v[148:149], v[146:147], s[80:81], v[134:135] op_sel_hi:[1,0,0]
	v_pk_add_f32 v[138:139], v[138:139], v[140:141] neg_lo:[0,1] neg_hi:[0,1]
	v_ldexp_f32 v140, v142, 1
	v_pk_fma_f32 v[148:149], v[146:147], v[148:149], s[82:83] op_sel_hi:[1,1,0]
	v_ldexp_f32 v141, v143, 1
	v_pk_mul_f32 v[142:143], v[142:143], v[146:147]
	v_pk_fma_f32 v[152:153], v[144:145], s[84:85], v[150:151] op_sel_hi:[1,0,1] neg_lo:[0,0,1] neg_hi:[0,0,1]
	v_pk_mul_f32 v[142:143], v[142:143], v[148:149]
	v_mov_b32_e32 v155, v141
	v_pk_add_f32 v[146:147], v[140:141], v[142:143]
	v_ldexp_f32 v138, v138, 1
	v_pk_add_f32 v[140:141], v[146:147], v[140:141] neg_lo:[0,1] neg_hi:[0,1]
	v_pk_fma_f32 v[144:145], v[144:145], s[86:87], v[152:153] op_sel_hi:[1,0,1]
	v_ldexp_f32 v139, v139, 1
	v_pk_add_f32 v[140:141], v[142:143], v[140:141] neg_lo:[0,1] neg_hi:[0,1]
	v_mov_b32_e32 v148, v150
	v_mov_b32_e32 v149, v143
	v_mov_b32_e32 v154, v144
	v_pk_add_f32 v[142:143], v[138:139], v[140:141]
	v_mov_b32_e32 v140, v150
	v_mov_b32_e32 v138, v144
	v_pk_add_f32 v[148:149], v[148:149], v[154:155]
	v_pk_add_f32 v[154:155], v[140:141], v[138:139]
	v_mov_b32_e32 v138, v146
	v_mov_b32_e32 v140, v142
	v_pk_add_f32 v[152:153], v[150:151], v[144:145]
	v_pk_add_f32 v[138:139], v[138:139], v[140:141]
	v_pk_add_f32 v[140:141], v[146:147], v[142:143]
	v_mov_b32_e32 v156, v152
	v_mov_b32_e32 v157, v151
	v_mov_b32_e32 v158, v140
	v_mov_b32_e32 v159, v145
	v_pk_add_f32 v[138:139], v[148:149], v[138:139]
	v_pk_add_f32 v[148:149], v[152:153], v[140:141]
	v_pk_add_f32 v[160:161], v[156:157], v[158:159]
	v_mov_b32_e32 v162, v140
	v_mov_b32_e32 v163, v149
	v_mov_b32_e32 v164, v146
	v_mov_b32_e32 v165, v153
	v_pk_add_f32 v[156:157], v[160:161], v[156:157] neg_lo:[0,1] neg_hi:[0,1]
	v_pk_add_f32 v[162:163], v[162:163], v[164:165] neg_lo:[0,1] neg_hi:[0,1]
	v_pk_add_f32 v[160:161], v[152:153], v[150:151] neg_lo:[0,1] neg_hi:[0,1]
	v_pk_add_f32 v[158:159], v[158:159], v[156:157] neg_lo:[0,1] neg_hi:[0,1]
	v_mov_b32_e32 v164, v152
	v_mov_b32_e32 v165, v149
	v_mov_b32_e32 v151, v163
	v_mov_b32_e32 v157, v147
	v_pk_add_f32 v[146:147], v[140:141], v[146:147] neg_lo:[0,1] neg_hi:[0,1]
	v_pk_add_f32 v[150:151], v[164:165], v[150:151] neg_lo:[0,1] neg_hi:[0,1]
	v_pk_add_f32 v[160:161], v[144:145], v[160:161] neg_lo:[0,1] neg_hi:[0,1]
	v_pk_add_f32 v[138:139], v[138:139], v[156:157] neg_lo:[0,1] neg_hi:[0,1]
	v_pk_add_f32 v[146:147], v[142:143], v[146:147] neg_lo:[0,1] neg_hi:[0,1]
	v_mov_b32_e32 v145, v153
	v_mov_b32_e32 v143, v141
	v_pk_add_f32 v[138:139], v[154:155], v[138:139] neg_lo:[0,1] neg_hi:[0,1]
	v_pk_add_f32 v[144:145], v[144:145], v[150:151] neg_lo:[0,1] neg_hi:[0,1]
	v_pk_add_f32 v[140:141], v[142:143], v[162:163] neg_lo:[0,1] neg_hi:[0,1]
	v_pk_add_f32 v[150:151], v[158:159], v[138:139]
	v_pk_add_f32 v[142:143], v[140:141], v[144:145]
	v_mov_b32_e32 v141, v139
	v_pk_add_f32 v[138:139], v[160:161], v[140:141]
	v_mov_b32_e32 v145, v159
	v_pk_add_f32 v[138:139], v[138:139], v[144:145] neg_lo:[0,1] neg_hi:[0,1]
	v_mov_b32_e32 v140, v142
	v_mov_b32_e32 v141, v151
	v_pk_add_f32 v[140:141], v[140:141], v[138:139] neg_lo:[0,1] neg_hi:[0,1]
	v_pk_add_f32 v[138:139], v[146:147], v[138:139] neg_lo:[0,1] neg_hi:[0,1]
	v_pk_add_f32 v[140:141], v[144:145], v[140:141] neg_lo:[0,1] neg_hi:[0,1]
	s_nop 0
	v_pk_add_f32 v[138:139], v[138:139], v[140:141]
	v_pk_add_f32 v[140:141], v[150:151], v[142:143]
	s_nop 0
	v_pk_add_f32 v[142:143], v[148:149], v[140:141]
	s_nop 0
	v_pk_add_f32 v[144:145], v[142:143], v[148:149] neg_lo:[0,1] neg_hi:[0,1]
	s_nop 0
	v_pk_add_f32 v[140:141], v[140:141], v[144:145] neg_lo:[0,1] neg_hi:[0,1]
	s_nop 0
	v_pk_add_f32 v[138:139], v[138:139], v[140:141]
	v_add_f32_e32 v140, v16, v132
	v_mul_f32_e64 v132, |v140|, s20
	v_pk_add_f32 v[138:139], v[142:143], v[138:139]
	v_fma_f32 v141, |v140|, s20, -v132
	v_rndne_f32_e32 v142, v132
	v_fma_f32 v141, |v140|, s51, v141
	v_sub_f32_e32 v132, v132, v142
	v_add_f32_e32 v132, v132, v141
	v_cndmask_b32_e32 v138, v221, v138, vcc
	v_cmp_neq_f32_e32 vcc, s77, v167
	v_exp_f32_e32 v141, v132
	v_cvt_i32_f32_e32 v142, v142
	v_cndmask_b32_e32 v139, v221, v139, vcc
	v_cmp_lt_f32_e64 vcc, |v167|, s79
	v_min_f32_e32 v132, 0, v140
	v_add_f32_e32 v143, v17, v133
	v_cndmask_b32_e32 v139, v139, v167, vcc
	v_cmp_lt_f32_e64 vcc, |v166|, s79
	v_mul_f32_e64 v133, |v143|, s20
	s_nop 0
	v_cndmask_b32_e32 v138, v138, v166, vcc
	v_pk_add_f32 v[130:131], v[130:131], v[138:139] neg_lo:[0,1] neg_hi:[0,1]
	v_ldexp_f32 v138, v141, v142
	v_cmp_ngt_f32_e64 vcc, |v140|, s54
	s_nop 1
	v_cndmask_b32_e32 v138, 0, v138, vcc
	v_cmp_nlt_f32_e64 vcc, |v140|, s55
	s_nop 1
	v_cndmask_b32_e32 v164, v221, v138, vcc
	v_add_f32_e32 v140, 1.0, v164
	v_add_f32_e32 v138, -1.0, v140
	v_sub_f32_e32 v139, v138, v140
	v_add_f32_e32 v139, 1.0, v139
	v_sub_f32_e32 v138, v164, v138
	v_add_f32_e32 v141, v138, v139
	v_fma_f32 v138, |v143|, s20, -v133
	v_rndne_f32_e32 v139, v133
	v_fma_f32 v138, |v143|, s51, v138
	v_sub_f32_e32 v133, v133, v139
	v_add_f32_e32 v133, v133, v138
; __device__ __forceinline__ void epi_all_run(const void* Pk_, int l, int s, const f32x4 (&acc)[2][2][4][2], const pg8::Unit& u, int wr, int wc, int fr, int fq) {
;     ...
;                         for (int j = 0; j < 4; ++j) ls[j] = fminf(z[j], 0.f) - log1pf(expf(-fabsf(z[j])));
	v_exp_f32_e32 v144, v133
	v_cvt_i32_f32_e32 v145, v139
	v_cvt_f64_f32_e32 v[138:139], v140
	v_frexp_exp_i32_f64_e32 v146, v[138:139]
	v_cmp_ngt_f32_e64 vcc, |v143|, s54
	v_ldexp_f32 v138, v144, v145
	v_min_f32_e32 v133, 0, v143
	v_cndmask_b32_e32 v138, 0, v138, vcc
	v_cmp_nlt_f32_e64 vcc, |v143|, s55
	v_frexp_mant_f32_e32 v142, v140
	s_nop 0
	v_cndmask_b32_e32 v165, v221, v138, vcc
	v_add_f32_e32 v143, 1.0, v165
	v_add_f32_e32 v138, -1.0, v143
	v_sub_f32_e32 v139, v138, v143
	v_add_f32_e32 v139, 1.0, v139
	v_sub_f32_e32 v138, v165, v138
	v_add_f32_e32 v144, v138, v139
	v_frexp_mant_f32_e32 v145, v143
	v_cvt_f64_f32_e32 v[138:139], v143
	v_frexp_exp_i32_f64_e32 v138, v[138:139]
	v_cmp_gt_f32_e32 vcc, s78, v145
	s_nop 1
	v_subbrev_co_u32_e32 v158, vcc, 0, v138, vcc
	v_cmp_gt_f32_e32 vcc, s78, v142
	s_nop 1
	v_subbrev_co_u32_e32 v159, vcc, 0, v146, vcc
	v_sub_u32_e32 v139, 0, v159
	v_ldexp_f32 v138, v140, v139
	v_ldexp_f32 v140, v141, v139
	v_sub_u32_e32 v141, 0, v158
	v_ldexp_f32 v139, v143, v141
	v_pk_add_f32 v[142:143], v[138:139], 1.0 op_sel_hi:[1,0]
	v_ldexp_f32 v141, v144, v141
	v_pk_add_f32 v[144:145], v[142:143], -1.0 op_sel_hi:[1,0]
	v_pk_add_f32 v[150:151], v[138:139], -1.0 op_sel_hi:[1,0]
	v_pk_add_f32 v[144:145], v[138:139], v[144:145] neg_lo:[0,1] neg_hi:[0,1]
	v_pk_add_f32 v[152:153], v[150:151], 1.0 op_sel_hi:[1,0]
	v_pk_add_f32 v[144:145], v[140:141], v[144:145]
	v_pk_add_f32 v[138:139], v[138:139], v[152:153] neg_lo:[0,1] neg_hi:[0,1]
	v_pk_add_f32 v[146:147], v[142:143], v[144:145]
	v_pk_add_f32 v[138:139], v[140:141], v[138:139]
	v_rcp_f32_e32 v148, v146
	v_rcp_f32_e32 v149, v147
	v_pk_add_f32 v[140:141], v[150:151], v[138:139]
	v_pk_add_f32 v[142:143], v[142:143], v[146:147] neg_lo:[0,1] neg_hi:[0,1]
	v_pk_add_f32 v[150:151], v[150:151], v[140:141] neg_lo:[0,1] neg_hi:[0,1]
	v_pk_add_f32 v[142:143], v[144:145], v[142:143]
	v_pk_mul_f32 v[144:145], v[140:141], v[148:149]
	v_pk_add_f32 v[138:139], v[138:139], v[150:151]
	v_pk_mul_f32 v[150:151], v[146:147], v[144:145]
	v_cmp_neq_f32_e32 vcc, s77, v164
	v_pk_fma_f32 v[152:153], v[144:145], v[146:147], v[150:151] neg_lo:[0,0,1] neg_hi:[0,0,1]
	s_nop 0
	v_pk_fma_f32 v[152:153], v[144:145], v[142:143], v[152:153]
	s_nop 0
	v_pk_add_f32 v[154:155], v[150:151], v[152:153]
	s_nop 0
	v_pk_add_f32 v[156:157], v[140:141], v[154:155] neg_lo:[0,1] neg_hi:[0,1]
	v_pk_add_f32 v[150:151], v[154:155], v[150:151] neg_lo:[0,1] neg_hi:[0,1]
	v_pk_add_f32 v[140:141], v[140:141], v[156:157] neg_lo:[0,1] neg_hi:[0,1]
	s_nop 0
	v_pk_add_f32 v[140:141], v[140:141], v[154:155] neg_lo:[0,1] neg_hi:[0,1]
	s_nop 0
	v_pk_add_f32 v[138:139], v[138:139], v[140:141]
	v_pk_add_f32 v[140:141], v[150:151], v[152:153] neg_lo:[0,1] neg_hi:[0,1]
	s_nop 0
	v_pk_add_f32 v[138:139], v[140:141], v[138:139]
	s_nop 0
	v_pk_add_f32 v[140:141], v[156:157], v[138:139]
	s_nop 0
	v_pk_mul_f32 v[150:151], v[148:149], v[140:141]
	s_nop 0
	v_pk_mul_f32 v[152:153], v[146:147], v[150:151]
	s_nop 0
	v_pk_fma_f32 v[146:147], v[150:151], v[146:147], v[152:153] neg_lo:[0,0,1] neg_hi:[0,0,1]
	s_nop 0
	v_pk_fma_f32 v[142:143], v[150:151], v[142:143], v[146:147]
	v_pk_add_f32 v[146:147], v[156:157], v[140:141] neg_lo:[0,1] neg_hi:[0,1]
	s_nop 0
	v_pk_add_f32 v[138:139], v[138:139], v[146:147]
	v_pk_add_f32 v[146:147], v[152:153], v[142:143]
	s_nop 0
	v_pk_add_f32 v[154:155], v[140:141], v[146:147] neg_lo:[0,1] neg_hi:[0,1]
	v_pk_add_f32 v[152:153], v[146:147], v[152:153] neg_lo:[0,1] neg_hi:[0,1]
	v_pk_add_f32 v[140:141], v[140:141], v[154:155] neg_lo:[0,1] neg_hi:[0,1]
	s_nop 0
	v_pk_add_f32 v[140:141], v[140:141], v[146:147] neg_lo:[0,1] neg_hi:[0,1]
	s_nop 0
	v_pk_add_f32 v[138:139], v[138:139], v[140:141]
	v_pk_add_f32 v[140:141], v[152:153], v[142:143] neg_lo:[0,1] neg_hi:[0,1]
	s_nop 0
	v_pk_add_f32 v[138:139], v[140:141], v[138:139]
	v_pk_add_f32 v[140:141], v[144:145], v[150:151]
	v_pk_add_f32 v[138:139], v[154:155], v[138:139]
	v_pk_add_f32 v[142:143], v[140:141], v[144:145] neg_lo:[0,1] neg_hi:[0,1]
	v_pk_mul_f32 v[138:139], v[148:149], v[138:139]
	v_pk_add_f32 v[142:143], v[150:151], v[142:143] neg_lo:[0,1] neg_hi:[0,1]
	v_cvt_f32_i32_e32 v145, v158
	v_pk_add_f32 v[138:139], v[142:143], v[138:139]
	v_cvt_f32_i32_e32 v144, v159
	v_pk_add_f32 v[142:143], v[140:141], v[138:139]
	v_pk_mul_f32 v[148:149], v[144:145], s[84:85] op_sel_hi:[1,0]
; __device__ __forceinline__ void epi_all_run(const void* Pk_, int l, int s, const f32x4 (&acc)[2][2][4][2], const pg8::Unit& u, int wr, int wc, int fr, int fq) {
;     ...
;                         const f32x4 z = acc[ai][0][m][0] + fbv;
;                         f32x4 ls;
; #pragma unroll
;                         for (int j = 0; j < 4; ++j) ls[j] = fminf(z[j], 0.f) - log1pf(expf(-fabsf(z[j])));
;                         *(f32x4*)(logf + (size_t)row * 4) = ls;
	v_pk_mul_f32 v[146:147], v[142:143], v[142:143]
	v_pk_add_f32 v[140:141], v[142:143], v[140:141] neg_lo:[0,1] neg_hi:[0,1]
	v_pk_fma_f32 v[134:135], v[146:147], s[80:81], v[134:135] op_sel_hi:[1,0,0]
	v_pk_add_f32 v[138:139], v[138:139], v[140:141] neg_lo:[0,1] neg_hi:[0,1]
	v_ldexp_f32 v140, v142, 1
	v_pk_fma_f32 v[134:135], v[146:147], v[134:135], s[82:83] op_sel_hi:[1,1,0]
	v_ldexp_f32 v141, v143, 1
	v_pk_mul_f32 v[142:143], v[142:143], v[146:147]
	v_pk_fma_f32 v[150:151], v[144:145], s[84:85], v[148:149] op_sel_hi:[1,0,1] neg_lo:[0,0,1] neg_hi:[0,0,1]
	v_pk_mul_f32 v[134:135], v[142:143], v[134:135]
	v_mov_b32_e32 v153, v141
	v_pk_add_f32 v[142:143], v[140:141], v[134:135]
	v_ldexp_f32 v138, v138, 1
	v_pk_add_f32 v[140:141], v[142:143], v[140:141] neg_lo:[0,1] neg_hi:[0,1]
	v_pk_fma_f32 v[144:145], v[144:145], s[86:87], v[150:151] op_sel_hi:[1,0,1]
	v_ldexp_f32 v139, v139, 1
	v_mov_b32_e32 v147, v135
	v_pk_add_f32 v[134:135], v[134:135], v[140:141] neg_lo:[0,1] neg_hi:[0,1]
	v_mov_b32_e32 v146, v148
	v_mov_b32_e32 v152, v144
	v_pk_add_f32 v[140:141], v[138:139], v[134:135]
	v_mov_b32_e32 v134, v148
	v_mov_b32_e32 v138, v144
	v_pk_add_f32 v[146:147], v[146:147], v[152:153]
	v_pk_add_f32 v[152:153], v[134:135], v[138:139]
	v_mov_b32_e32 v138, v142
	v_mov_b32_e32 v134, v140
	v_pk_add_f32 v[150:151], v[148:149], v[144:145]
	v_pk_add_f32 v[134:135], v[138:139], v[134:135]
	v_pk_add_f32 v[138:139], v[142:143], v[140:141]
	v_mov_b32_e32 v154, v150
	v_mov_b32_e32 v155, v149
	v_mov_b32_e32 v156, v138
	v_mov_b32_e32 v157, v145
	v_pk_add_f32 v[134:135], v[146:147], v[134:135]
	v_pk_add_f32 v[146:147], v[150:151], v[138:139]
	v_pk_add_f32 v[158:159], v[154:155], v[156:157]
	v_mov_b32_e32 v160, v138
	v_mov_b32_e32 v161, v147
	v_mov_b32_e32 v162, v142
	v_mov_b32_e32 v163, v151
	v_pk_add_f32 v[154:155], v[158:159], v[154:155] neg_lo:[0,1] neg_hi:[0,1]
	v_pk_add_f32 v[160:161], v[160:161], v[162:163] neg_lo:[0,1] neg_hi:[0,1]
	v_pk_add_f32 v[158:159], v[150:151], v[148:149] neg_lo:[0,1] neg_hi:[0,1]
	v_pk_add_f32 v[156:157], v[156:157], v[154:155] neg_lo:[0,1] neg_hi:[0,1]
	v_mov_b32_e32 v162, v150
	v_mov_b32_e32 v163, v147
	v_mov_b32_e32 v149, v161
	v_mov_b32_e32 v155, v143
	v_pk_add_f32 v[142:143], v[138:139], v[142:143] neg_lo:[0,1] neg_hi:[0,1]
	v_pk_add_f32 v[148:149], v[162:163], v[148:149] neg_lo:[0,1] neg_hi:[0,1]
	v_pk_add_f32 v[158:159], v[144:145], v[158:159] neg_lo:[0,1] neg_hi:[0,1]
	v_pk_add_f32 v[134:135], v[134:135], v[154:155] neg_lo:[0,1] neg_hi:[0,1]
	v_pk_add_f32 v[142:143], v[140:141], v[142:143] neg_lo:[0,1] neg_hi:[0,1]
	v_mov_b32_e32 v145, v151
	v_mov_b32_e32 v141, v139
	v_pk_add_f32 v[134:135], v[152:153], v[134:135] neg_lo:[0,1] neg_hi:[0,1]
	v_pk_add_f32 v[144:145], v[144:145], v[148:149] neg_lo:[0,1] neg_hi:[0,1]
	v_pk_add_f32 v[138:139], v[140:141], v[160:161] neg_lo:[0,1] neg_hi:[0,1]
	v_pk_add_f32 v[148:149], v[156:157], v[134:135]
	v_pk_add_f32 v[140:141], v[138:139], v[144:145]
	v_mov_b32_e32 v139, v135
	v_pk_add_f32 v[134:135], v[158:159], v[138:139]
	v_mov_b32_e32 v145, v157
	v_pk_add_f32 v[134:135], v[134:135], v[144:145] neg_lo:[0,1] neg_hi:[0,1]
	v_mov_b32_e32 v138, v140
	v_mov_b32_e32 v139, v149
	v_pk_add_f32 v[138:139], v[138:139], v[134:135] neg_lo:[0,1] neg_hi:[0,1]
	v_pk_add_f32 v[134:135], v[142:143], v[134:135] neg_lo:[0,1] neg_hi:[0,1]
	v_pk_add_f32 v[138:139], v[144:145], v[138:139] neg_lo:[0,1] neg_hi:[0,1]
	s_nop 0
	v_pk_add_f32 v[134:135], v[134:135], v[138:139]
	v_pk_add_f32 v[138:139], v[148:149], v[140:141]
	s_nop 0
	v_pk_add_f32 v[140:141], v[146:147], v[138:139]
	s_nop 0
	v_pk_add_f32 v[142:143], v[140:141], v[146:147] neg_lo:[0,1] neg_hi:[0,1]
	s_nop 0
	v_pk_add_f32 v[138:139], v[138:139], v[142:143] neg_lo:[0,1] neg_hi:[0,1]
	s_nop 0
	v_pk_add_f32 v[134:135], v[134:135], v[138:139]
	s_nop 0
	v_pk_add_f32 v[134:135], v[140:141], v[134:135]
	s_nop 0
	v_cndmask_b32_e32 v134, v221, v134, vcc
	v_cmp_neq_f32_e32 vcc, s77, v165
	s_nop 1
	v_cndmask_b32_e32 v135, v221, v135, vcc
	v_cmp_lt_f32_e64 vcc, |v165|, s79
	s_nop 1
	v_cndmask_b32_e32 v135, v135, v165, vcc
	v_cmp_lt_f32_e64 vcc, |v164|, s79
	s_nop 1
	v_cndmask_b32_e32 v134, v134, v164, vcc
	v_pk_add_f32 v[132:133], v[132:133], v[134:135] neg_lo:[0,1] neg_hi:[0,1]
	global_store_dwordx4 v[136:137], v[130:133], off offset:2816
